# kdma with per=3: three ds_reads between LDS-DMA loads in the load segments
# baseline (speedup 1.0000x reference)
; #define PG8_STAGE(bufoff, gbase, voff) do { _Pragma("unroll") for (int _i = 0; _i < 2; ++_i) \
;         __builtin_amdgcn_global_load_lds((const unsigned*)((const char*)(gbase) + (voff)[_i]), (LAS unsigned*)(lds + (bufoff) + ldsw + _i * 8192), 16, 0, 0); } while (0)
; #define PG8_LDA(dst, b, h) do { _Pragma("unroll") for (int m = 0; m < 4; ++m) _Pragma("unroll") for (int k = 0; k < 2; ++k) dst[m][k] = *(const LAS bf16x8*)(lds + PG8_SA(b, h) + aoff + m * 2048 + k * 1024); } while (0)
; #define PG8_LDB(dst, b, h) do { _Pragma("unroll") for (int n = 0; n < 2; ++n) _Pragma("unroll") for (int k = 0; k < 2; ++k) dst[n][k] = *(const LAS bf16x8*)(lds + PG8_SB(b, h) + boff + n * 2048 + k * 1024); } while (0)
; #define PG8_WAIT_V(n) asm volatile("s_waitcnt vmcnt(" #n ")" ::: "memory")
; #define PG8_WAIT_L(n) asm volatile("s_waitcnt lgkmcnt(" #n ")" ::: "memory")
; #define PG8_BAR __builtin_amdgcn_s_barrier()
; #define PG8_SCHED __builtin_amdgcn_sched_barrier(0)
; template <class Epi>
; __device__ __forceinline__ void gemm_phase(LAS unsigned char* lds, const Gemm g, const StaticOrder& S, const Epi& E, const int tid) {
;     ...
;             const bool last = (t == ntt - 2);
;             const bool s1 = Epi::TWO && (t >= nt), s2 = Epi::TWO && (t + 2 >= nt);
;             const char* a1 = (s1 ? cA2 + (size_t)(t - nt + 1) * kstep : cA + (size_t)(t + 1) * kstep);
;             const char* a2 = last ? nA : (s2 ? cA2 + (size_t)(t + 2 - nt) * kstep : cA + (size_t)(t + 2) * kstep);
;             const char* b2 = last ? nB : (s2 ? cB2 + (size_t)(t + 2 - nt) * kstep : cB + (size_t)(t + 2) * kstep);
;             const char* a3 = a2 + kstep; const char* b3 = b2 + kstep;
;             if constexpr (Epi::TWO) { if (t == nt) E.mid(acc, cur, wr, wc, fr, fq); }
;             if constexpr (SP2) {
;             PG8_LDB(B0, 0, 0); PG8_LDB(B1, 0, 1); PG8_SCHED; PG8_LDA(At, 0, 0); PG8_STAGE(PG8_SA(1, 1), a1 + hstep, voffA);
;             PG8_WAIT_V(8); PG8_WAIT_L(0); PG8_BAR; PG8_MMA(0, 0, At, B0); PG8_MMA(0, 1, At, B1); PG8_BAR; PG8_SCHED;
;             PG8_LDA(At, 0, 1); PG8_STAGE(PG8_SB(0, 0), b2, voffB); PG8_STAGE(PG8_SB(0, 1), b2 + bhs, voffB); PG8_STAGE(PG8_SA(0, 0), a2, voffA);
;             PG8_WAIT_V(8); PG8_WAIT_L(0); PG8_BAR; PG8_MMA(1, 0, At, B0); PG8_MMA(1, 1, At, B1); PG8_BAR; PG8_SCHED;
.LBB0_126:
	s_add_u32 s30, s28, 0xffe00080
	s_addc_u32 s31, s29, -1
	s_add_i32 s52, 0, 0x10000
	s_cmpk_eq_i32 s51, 0x7c
	s_cselect_b32 s35, s17, s31
	s_cselect_b32 s34, s27, s30
	s_cselect_b32 s31, s15, s50
	s_cselect_b32 s30, s33, s49
	s_add_i32 s54, 0, 0x14000
	v_add_u32_e32 v30, s52, v193
	v_add_u32_e32 v54, s54, v193
	ds_read_b128 v[18:21], v30
	ds_read_b128 v[22:25], v30 offset:1024
	ds_read_b128 v[26:29], v30 offset:2048
	ds_read_b128 v[30:33], v30 offset:3072
	ds_read_b128 v[42:45], v54
	ds_read_b128 v[46:49], v54 offset:1024
	ds_read_b128 v[50:53], v54 offset:2048
	ds_read_b128 v[54:57], v54 offset:3072
	v_lshl_add_u64 v[172:173], s[28:29], 0, v[180:181]
	s_add_i32 m0, s37, 0xc000
	ds_read_b128 v[182:185], v199
	global_load_lds_dwordx4 v[172:173], off
	ds_read_b128 v[186:189], v199 offset:1024
	ds_read_b128 v[212:215], v199 offset:2048
	ds_read_b128 v[216:219], v199 offset:3072
	v_lshl_add_u64 v[172:173], s[28:29], 0, v[178:179]
	s_add_i32 m0, s37, 0xe000
	s_nop 0
	global_load_lds_dwordx4 v[172:173], off
	ds_read_b128 v[220:223], v199 offset:4096
	ds_read_b128 v[224:227], v199 offset:5120
	ds_read_b128 v[228:231], v199 offset:6144
	ds_read_b128 v[232:235], v199 offset:7168
	s_waitcnt vmcnt(8)
	s_waitcnt lgkmcnt(0)
	s_barrier
	s_setprio 1
	s_waitcnt lgkmcnt(0)
	v_mfma_f32_16x16x32_bf16 v[158:161], v[18:21], v[182:185], v[158:161]
	v_mfma_f32_16x16x32_bf16 v[154:157], v[26:29], v[182:185], v[154:157]
	v_mfma_f32_16x16x32_bf16 v[142:145], v[18:21], v[212:215], v[142:145]
	v_mfma_f32_16x16x32_bf16 v[138:141], v[26:29], v[212:215], v[138:141]
	v_mfma_f32_16x16x32_bf16 v[126:129], v[18:21], v[220:223], v[126:129]
	v_mfma_f32_16x16x32_bf16 v[122:125], v[26:29], v[220:223], v[122:125]
	v_mfma_f32_16x16x32_bf16 v[110:113], v[18:21], v[228:231], v[110:113]
	v_mfma_f32_16x16x32_bf16 v[106:109], v[26:29], v[228:231], v[106:109]
	v_mfma_f32_16x16x32_bf16 v[158:161], v[22:25], v[186:189], v[158:161]
	v_mfma_f32_16x16x32_bf16 v[154:157], v[30:33], v[186:189], v[154:157]
	v_mfma_f32_16x16x32_bf16 v[142:145], v[22:25], v[216:219], v[142:145]
	v_mfma_f32_16x16x32_bf16 v[138:141], v[30:33], v[216:219], v[138:141]
	v_mfma_f32_16x16x32_bf16 v[126:129], v[22:25], v[224:227], v[126:129]
	v_mfma_f32_16x16x32_bf16 v[122:125], v[30:33], v[224:227], v[122:125]
	v_mfma_f32_16x16x32_bf16 v[110:113], v[22:25], v[232:235], v[110:113]
	v_mfma_f32_16x16x32_bf16 v[106:109], v[30:33], v[232:235], v[106:109]
	s_setprio 0
	s_setprio 1
	v_mfma_f32_16x16x32_bf16 v[150:153], v[42:45], v[182:185], v[150:153]
	v_mfma_f32_16x16x32_bf16 v[146:149], v[50:53], v[182:185], v[146:149]
	v_mfma_f32_16x16x32_bf16 v[134:137], v[42:45], v[212:215], v[134:137]
	v_mfma_f32_16x16x32_bf16 v[130:133], v[50:53], v[212:215], v[130:133]
	v_mfma_f32_16x16x32_bf16 v[118:121], v[42:45], v[220:223], v[118:121]
	v_mfma_f32_16x16x32_bf16 v[114:117], v[50:53], v[220:223], v[114:117]
	v_mfma_f32_16x16x32_bf16 v[102:105], v[42:45], v[228:231], v[102:105]
	v_mfma_f32_16x16x32_bf16 v[98:101], v[50:53], v[228:231], v[98:101]
	v_mfma_f32_16x16x32_bf16 v[150:153], v[46:49], v[186:189], v[150:153]
	v_mfma_f32_16x16x32_bf16 v[146:149], v[54:57], v[186:189], v[146:149]
	v_mfma_f32_16x16x32_bf16 v[134:137], v[46:49], v[216:219], v[134:137]
	v_mfma_f32_16x16x32_bf16 v[130:133], v[54:57], v[216:219], v[130:133]
	v_mfma_f32_16x16x32_bf16 v[118:121], v[46:49], v[224:227], v[118:121]
	v_mfma_f32_16x16x32_bf16 v[114:117], v[54:57], v[224:227], v[114:117]
	v_mfma_f32_16x16x32_bf16 v[102:105], v[46:49], v[232:235], v[102:105]
	v_mfma_f32_16x16x32_bf16 v[98:101], v[54:57], v[232:235], v[98:101]
	s_setprio 0
	s_barrier
	s_add_i32 s52, s52, s36
	v_lshl_add_u64 v[172:173], s[30:31], 0, v[0:1]
	s_mov_b32 m0, s52
	ds_read_b128 v[182:185], v199 offset:16384
	global_load_lds_dwordx4 v[172:173], off
	ds_read_b128 v[186:189], v199 offset:17408
	ds_read_b128 v[212:215], v199 offset:18432
	ds_read_b128 v[216:219], v199 offset:19456
	s_add_i32 m0, s52, 0x2000
	s_add_u32 s52, s30, 0x20000
	v_lshl_add_u64 v[174:175], s[30:31], 0, v[166:167]
	s_addc_u32 s53, s31, 0
	s_add_i32 s54, s54, s36
	global_load_lds_dwordx4 v[174:175], off
	ds_read_b128 v[220:223], v199 offset:20480
	ds_read_b128 v[224:227], v199 offset:21504
	ds_read_b128 v[228:231], v199 offset:22528
	v_lshl_add_u64 v[176:177], s[52:53], 0, v[0:1]
	s_mov_b32 m0, s54
	v_lshl_add_u64 v[200:201], s[34:35], 0, v[164:165]
	global_load_lds_dwordx4 v[176:177], off
	ds_read_b128 v[232:235], v199 offset:23552
	v_lshl_add_u64 v[176:177], s[52:53], 0, v[166:167]
	s_add_i32 m0, s54, 0x2000
	s_nop 0
	global_load_lds_dwordx4 v[176:177], off
	v_lshl_add_u64 v[176:177], s[34:35], 0, v[162:163]
	s_mov_b32 m0, s37
	s_nop 0
	global_load_lds_dwordx4 v[176:177], off
	s_mov_b32 m0, s38
	s_nop 0
	global_load_lds_dwordx4 v[200:201], off
	s_waitcnt vmcnt(8)
	s_waitcnt lgkmcnt(0)
	s_barrier
; #define PG8_STAGE(bufoff, gbase, voff) do { _Pragma("unroll") for (int _i = 0; _i < 2; ++_i) \
;         __builtin_amdgcn_global_load_lds((const unsigned*)((const char*)(gbase) + (voff)[_i]), (LAS unsigned*)(lds + (bufoff) + ldsw + _i * 8192), 16, 0, 0); } while (0)
; #define PG8_LDA(dst, b, h) do { _Pragma("unroll") for (int m = 0; m < 4; ++m) _Pragma("unroll") for (int k = 0; k < 2; ++k) dst[m][k] = *(const LAS bf16x8*)(lds + PG8_SA(b, h) + aoff + m * 2048 + k * 1024); } while (0)
; #define PG8_LDB(dst, b, h) do { _Pragma("unroll") for (int n = 0; n < 2; ++n) _Pragma("unroll") for (int k = 0; k < 2; ++k) dst[n][k] = *(const LAS bf16x8*)(lds + PG8_SB(b, h) + boff + n * 2048 + k * 1024); } while (0)
; #define PG8_MMA(ai, bj, At, Bt) do { __builtin_amdgcn_s_setprio(1); _Pragma("unroll") for (int m = 0; m < 4; ++m) _Pragma("unroll") for (int n = 0; n < 2; ++n) _Pragma("unroll") for (int k = 0; k < 2; ++k) \
;         acc[ai][bj][m][n] = __builtin_amdgcn_mfma_f32_16x16x32_bf16(Bt[n][k], At[m][k], acc[ai][bj][m][n], 0, 0, 0); __builtin_amdgcn_s_setprio(0); } while (0)
; #define PG8_WAIT_V(n) asm volatile("s_waitcnt vmcnt(" #n ")" ::: "memory")
; #define PG8_WAIT_L(n) asm volatile("s_waitcnt lgkmcnt(" #n ")" ::: "memory")
; #define PG8_BAR __builtin_amdgcn_s_barrier()
; #define PG8_SCHED __builtin_amdgcn_sched_barrier(0)
; template <class Epi>
; __device__ __forceinline__ void gemm_phase(LAS unsigned char* lds, const Gemm g, const StaticOrder& S, const Epi& E, const int tid) {
;     ...
;             PG8_WAIT_V(8); PG8_WAIT_L(0); PG8_BAR; PG8_MMA(1, 0, At, B0); PG8_MMA(1, 1, At, B1); PG8_BAR; PG8_SCHED;
;             PG8_LDB(B0, 1, 0); PG8_LDB(B1, 1, 1); PG8_SCHED; PG8_LDA(At, 1, 0); PG8_STAGE(PG8_SA(0, 1), a2 + hstep, voffA);
;             PG8_WAIT_V(8); PG8_WAIT_L(0); PG8_BAR; PG8_MMA(0, 0, At, B0); PG8_MMA(0, 1, At, B1); PG8_BAR; PG8_SCHED;
	s_setprio 1
	s_waitcnt lgkmcnt(0)
	v_mfma_f32_16x16x32_bf16 v[94:97], v[18:21], v[182:185], v[94:97]
	v_mfma_f32_16x16x32_bf16 v[90:93], v[26:29], v[182:185], v[90:93]
	v_mfma_f32_16x16x32_bf16 v[78:81], v[18:21], v[212:215], v[78:81]
	v_mfma_f32_16x16x32_bf16 v[74:77], v[26:29], v[212:215], v[74:77]
	v_mfma_f32_16x16x32_bf16 v[62:65], v[18:21], v[220:223], v[62:65]
	v_mfma_f32_16x16x32_bf16 v[58:61], v[26:29], v[220:223], v[58:61]
	v_mfma_f32_16x16x32_bf16 v[14:17], v[18:21], v[228:231], v[14:17]
	v_mfma_f32_16x16x32_bf16 v[10:13], v[26:29], v[228:231], v[10:13]
	v_mfma_f32_16x16x32_bf16 v[94:97], v[22:25], v[186:189], v[94:97]
	v_mfma_f32_16x16x32_bf16 v[90:93], v[30:33], v[186:189], v[90:93]
	v_mfma_f32_16x16x32_bf16 v[78:81], v[22:25], v[216:219], v[78:81]
	v_mfma_f32_16x16x32_bf16 v[74:77], v[30:33], v[216:219], v[74:77]
	v_mfma_f32_16x16x32_bf16 v[62:65], v[22:25], v[224:227], v[62:65]
	v_mfma_f32_16x16x32_bf16 v[58:61], v[30:33], v[224:227], v[58:61]
	v_mfma_f32_16x16x32_bf16 v[14:17], v[22:25], v[232:235], v[14:17]
	v_mfma_f32_16x16x32_bf16 v[10:13], v[30:33], v[232:235], v[10:13]
	s_setprio 0
	s_setprio 1
	v_mfma_f32_16x16x32_bf16 v[38:41], v[42:45], v[220:223], v[38:41]
	v_mfma_f32_16x16x32_bf16 v[34:37], v[50:53], v[220:223], v[34:37]
	v_mfma_f32_16x16x32_bf16 v[6:9], v[42:45], v[228:231], v[6:9]
	v_mfma_f32_16x16x32_bf16 v[2:5], v[50:53], v[228:231], v[2:5]
	v_mfma_f32_16x16x32_bf16 v[18:21], v[42:45], v[182:185], v[86:89]
	v_mfma_f32_16x16x32_bf16 v[22:25], v[50:53], v[182:185], v[82:85]
	v_mfma_f32_16x16x32_bf16 v[26:29], v[42:45], v[212:215], v[70:73]
	v_mfma_f32_16x16x32_bf16 v[30:33], v[50:53], v[212:215], v[66:69]
	v_mfma_f32_16x16x32_bf16 v[38:41], v[46:49], v[224:227], v[38:41]
	v_mfma_f32_16x16x32_bf16 v[34:37], v[54:57], v[224:227], v[34:37]
	v_mfma_f32_16x16x32_bf16 v[6:9], v[46:49], v[232:235], v[6:9]
	v_mfma_f32_16x16x32_bf16 v[2:5], v[54:57], v[232:235], v[2:5]
	v_mfma_f32_16x16x32_bf16 v[18:21], v[46:49], v[186:189], v[18:21]
	v_mfma_f32_16x16x32_bf16 v[22:25], v[54:57], v[186:189], v[22:25]
	v_mfma_f32_16x16x32_bf16 v[26:29], v[46:49], v[216:219], v[26:29]
	v_mfma_f32_16x16x32_bf16 v[30:33], v[54:57], v[216:219], v[30:33]
	s_setprio 0
	s_barrier
	s_add_i32 s52, 0, 0x18000
	s_add_i32 s53, 0, 0x1c000
	v_add_u32_e32 v54, s52, v193
	v_add_u32_e32 v66, s53, v193
	ds_read_b128 v[42:45], v54
	ds_read_b128 v[46:49], v54 offset:1024
	ds_read_b128 v[50:53], v54 offset:2048
	ds_read_b128 v[54:57], v54 offset:3072
	ds_read_b128 v[182:185], v66
	ds_read_b128 v[186:189], v66 offset:1024
	ds_read_b128 v[212:215], v66 offset:2048
	ds_read_b128 v[216:219], v66 offset:3072
	s_add_u32 s34, s34, 0x200000
	s_addc_u32 s35, s35, 0
	s_mov_b32 m0, s39
	v_lshl_add_u64 v[236:237], s[34:35], 0, v[162:163]
	ds_read_b128 v[66:69], v199 offset:32768
	global_load_lds_dwordx4 v[236:237], off
	ds_read_b128 v[70:73], v199 offset:33792
	ds_read_b128 v[82:85], v199 offset:34816
	ds_read_b128 v[86:89], v199 offset:35840
	v_lshl_add_u64 v[236:237], s[34:35], 0, v[164:165]
	s_mov_b32 m0, s44
	s_nop 0
	global_load_lds_dwordx4 v[236:237], off
	ds_read_b128 v[220:223], v199 offset:36864
	ds_read_b128 v[224:227], v199 offset:37888
	ds_read_b128 v[228:231], v199 offset:38912
	ds_read_b128 v[232:235], v199 offset:39936
	s_waitcnt vmcnt(8)
	s_waitcnt lgkmcnt(0)
	s_barrier
	s_setprio 1
	s_waitcnt lgkmcnt(0)
	v_mfma_f32_16x16x32_bf16 v[158:161], v[42:45], v[66:69], v[158:161]
	v_mfma_f32_16x16x32_bf16 v[154:157], v[50:53], v[66:69], v[154:157]
	v_mfma_f32_16x16x32_bf16 v[142:145], v[42:45], v[82:85], v[142:145]
	v_mfma_f32_16x16x32_bf16 v[138:141], v[50:53], v[82:85], v[138:141]
	v_mfma_f32_16x16x32_bf16 v[126:129], v[42:45], v[220:223], v[126:129]
	v_mfma_f32_16x16x32_bf16 v[122:125], v[50:53], v[220:223], v[122:125]
	v_mfma_f32_16x16x32_bf16 v[110:113], v[42:45], v[228:231], v[110:113]
	v_mfma_f32_16x16x32_bf16 v[106:109], v[50:53], v[228:231], v[106:109]
	v_mfma_f32_16x16x32_bf16 v[158:161], v[46:49], v[70:73], v[158:161]
	v_mfma_f32_16x16x32_bf16 v[154:157], v[54:57], v[70:73], v[154:157]
	v_mfma_f32_16x16x32_bf16 v[142:145], v[46:49], v[86:89], v[142:145]
	v_mfma_f32_16x16x32_bf16 v[138:141], v[54:57], v[86:89], v[138:141]
	v_mfma_f32_16x16x32_bf16 v[126:129], v[46:49], v[224:227], v[126:129]
	v_mfma_f32_16x16x32_bf16 v[122:125], v[54:57], v[224:227], v[122:125]
	v_mfma_f32_16x16x32_bf16 v[110:113], v[46:49], v[232:235], v[110:113]
	v_mfma_f32_16x16x32_bf16 v[106:109], v[54:57], v[232:235], v[106:109]
	s_setprio 0
	s_setprio 1
	v_mfma_f32_16x16x32_bf16 v[150:153], v[182:185], v[66:69], v[150:153]
	v_mfma_f32_16x16x32_bf16 v[66:69], v[212:215], v[66:69], v[146:149]
	v_mfma_f32_16x16x32_bf16 v[146:149], v[216:219], v[70:73], v[66:69]
	v_mfma_f32_16x16x32_bf16 v[66:69], v[182:185], v[82:85], v[134:137]
	v_mfma_f32_16x16x32_bf16 v[134:137], v[186:189], v[86:89], v[66:69]
	v_mfma_f32_16x16x32_bf16 v[66:69], v[212:215], v[82:85], v[130:133]
	v_mfma_f32_16x16x32_bf16 v[130:133], v[216:219], v[86:89], v[66:69]
	v_mfma_f32_16x16x32_bf16 v[66:69], v[182:185], v[220:223], v[118:121]
	v_mfma_f32_16x16x32_bf16 v[118:121], v[186:189], v[224:227], v[66:69]
	v_mfma_f32_16x16x32_bf16 v[66:69], v[212:215], v[220:223], v[114:117]
	v_mfma_f32_16x16x32_bf16 v[114:117], v[216:219], v[224:227], v[66:69]
	v_mfma_f32_16x16x32_bf16 v[66:69], v[182:185], v[228:231], v[102:105]
	v_mfma_f32_16x16x32_bf16 v[102:105], v[186:189], v[232:235], v[66:69]
	v_mfma_f32_16x16x32_bf16 v[66:69], v[212:215], v[228:231], v[98:101]
	v_mfma_f32_16x16x32_bf16 v[150:153], v[186:189], v[70:73], v[150:153]
	v_mfma_f32_16x16x32_bf16 v[98:101], v[216:219], v[232:235], v[66:69]
	s_setprio 0
	s_barrier
; #define PG8_STAGE(bufoff, gbase, voff) do { _Pragma("unroll") for (int _i = 0; _i < 2; ++_i) \
;         __builtin_amdgcn_global_load_lds((const unsigned*)((const char*)(gbase) + (voff)[_i]), (LAS unsigned*)(lds + (bufoff) + ldsw + _i * 8192), 16, 0, 0); } while (0)
; #define PG8_LDA(dst, b, h) do { _Pragma("unroll") for (int m = 0; m < 4; ++m) _Pragma("unroll") for (int k = 0; k < 2; ++k) dst[m][k] = *(const LAS bf16x8*)(lds + PG8_SA(b, h) + aoff + m * 2048 + k * 1024); } while (0)
; #define PG8_MMA(ai, bj, At, Bt) do { __builtin_amdgcn_s_setprio(1); _Pragma("unroll") for (int m = 0; m < 4; ++m) _Pragma("unroll") for (int n = 0; n < 2; ++n) _Pragma("unroll") for (int k = 0; k < 2; ++k) \
;         acc[ai][bj][m][n] = __builtin_amdgcn_mfma_f32_16x16x32_bf16(Bt[n][k], At[m][k], acc[ai][bj][m][n], 0, 0, 0); __builtin_amdgcn_s_setprio(0); } while (0)
; #define PG8_WAIT_V(n) asm volatile("s_waitcnt vmcnt(" #n ")" ::: "memory")
; #define PG8_WAIT_L(n) asm volatile("s_waitcnt lgkmcnt(" #n ")" ::: "memory")
; #define PG8_BAR __builtin_amdgcn_s_barrier()
; #define PG8_SCHED __builtin_amdgcn_sched_barrier(0)
; template <class Epi>
; __device__ __forceinline__ void gemm_phase(LAS unsigned char* lds, const Gemm g, const StaticOrder& S, const Epi& E, const int tid) {
;     ...
;             PG8_LDA(At, 1, 1); PG8_STAGE(PG8_SB(1, 0), b3, voffB); PG8_STAGE(PG8_SB(1, 1), b3 + bhs, voffB); PG8_STAGE(PG8_SA(1, 0), a3, voffA);
;             PG8_WAIT_V(8); PG8_WAIT_L(0); PG8_BAR; PG8_MMA(1, 0, At, B0); PG8_MMA(1, 1, At, B1); PG8_BAR; PG8_SCHED;
;     ...
;         if (ALIGN_EPI) { if (wr == 0) PG8_BAR; }
	s_add_i32 s34, s52, s36
	v_lshl_add_u64 v[82:83], v[172:173], 0, s[70:71]
	s_mov_b32 m0, s34
	s_nop 0
	ds_read_b128 v[66:69], v199 offset:49152
	global_load_lds_dwordx4 v[82:83], off
	ds_read_b128 v[70:73], v199 offset:50176
	ds_read_b128 v[220:223], v199 offset:51200
	ds_read_b128 v[224:227], v199 offset:52224
	s_add_i32 m0, s34, 0x2000
	s_add_u32 s30, s30, 0x20080
	v_lshl_add_u64 v[82:83], v[174:175], 0, s[70:71]
	s_addc_u32 s31, s31, 0
	s_add_i32 s34, s53, s36
	global_load_lds_dwordx4 v[82:83], off
	ds_read_b128 v[228:231], v199 offset:53248
	ds_read_b128 v[232:235], v199 offset:54272
	ds_read_b128 v[236:239], v199 offset:55296
	v_lshl_add_u64 v[82:83], s[30:31], 0, v[0:1]
	s_mov_b32 m0, s34
	s_nop 0
	global_load_lds_dwordx4 v[82:83], off
	ds_read_b128 v[240:243], v199 offset:56320
	v_lshl_add_u64 v[82:83], s[30:31], 0, v[166:167]
	s_add_i32 m0, s34, 0x2000
	s_nop 0
	global_load_lds_dwordx4 v[82:83], off
	v_lshl_add_u64 v[82:83], v[176:177], 0, s[70:71]
	s_mov_b32 m0, s45
	s_nop 0
	global_load_lds_dwordx4 v[82:83], off
	v_lshl_add_u64 v[82:83], v[200:201], 0, s[70:71]
	s_mov_b32 m0, s46
	s_nop 0
	global_load_lds_dwordx4 v[82:83], off
	s_waitcnt vmcnt(8)
	s_waitcnt lgkmcnt(0)
	s_barrier
	s_setprio 1
	s_waitcnt lgkmcnt(0)
	v_mfma_f32_16x16x32_bf16 v[82:85], v[42:45], v[66:69], v[94:97]
	v_mfma_f32_16x16x32_bf16 v[94:97], v[46:49], v[70:73], v[82:85]
	v_mfma_f32_16x16x32_bf16 v[82:85], v[50:53], v[66:69], v[90:93]
	v_mfma_f32_16x16x32_bf16 v[78:81], v[42:45], v[220:223], v[78:81]
	v_mfma_f32_16x16x32_bf16 v[74:77], v[50:53], v[220:223], v[74:77]
	v_mfma_f32_16x16x32_bf16 v[62:65], v[42:45], v[228:231], v[62:65]
	v_mfma_f32_16x16x32_bf16 v[58:61], v[50:53], v[228:231], v[58:61]
	v_mfma_f32_16x16x32_bf16 v[14:17], v[42:45], v[236:239], v[14:17]
	v_mfma_f32_16x16x32_bf16 v[10:13], v[50:53], v[236:239], v[10:13]
	v_mfma_f32_16x16x32_bf16 v[90:93], v[54:57], v[70:73], v[82:85]
	v_mfma_f32_16x16x32_bf16 v[78:81], v[46:49], v[224:227], v[78:81]
	v_mfma_f32_16x16x32_bf16 v[74:77], v[54:57], v[224:227], v[74:77]
	v_mfma_f32_16x16x32_bf16 v[62:65], v[46:49], v[232:235], v[62:65]
	v_mfma_f32_16x16x32_bf16 v[58:61], v[54:57], v[232:235], v[58:61]
	v_mfma_f32_16x16x32_bf16 v[14:17], v[46:49], v[240:243], v[14:17]
	v_mfma_f32_16x16x32_bf16 v[10:13], v[54:57], v[240:243], v[10:13]
	s_setprio 0
	s_setprio 1
	v_mfma_f32_16x16x32_bf16 v[18:21], v[182:185], v[66:69], v[18:21]
	v_mfma_f32_16x16x32_bf16 v[86:89], v[186:189], v[70:73], v[18:21]
	v_mfma_f32_16x16x32_bf16 v[18:21], v[212:215], v[66:69], v[22:25]
	v_mfma_f32_16x16x32_bf16 v[82:85], v[216:219], v[70:73], v[18:21]
	v_mfma_f32_16x16x32_bf16 v[18:21], v[182:185], v[220:223], v[26:29]
	v_mfma_f32_16x16x32_bf16 v[70:73], v[186:189], v[224:227], v[18:21]
	v_mfma_f32_16x16x32_bf16 v[18:21], v[212:215], v[220:223], v[30:33]
	v_mfma_f32_16x16x32_bf16 v[66:69], v[216:219], v[224:227], v[18:21]
	v_mfma_f32_16x16x32_bf16 v[18:21], v[182:185], v[228:231], v[38:41]
	v_mfma_f32_16x16x32_bf16 v[38:41], v[186:189], v[232:235], v[18:21]
	v_mfma_f32_16x16x32_bf16 v[18:21], v[212:215], v[228:231], v[34:37]
	v_mfma_f32_16x16x32_bf16 v[6:9], v[182:185], v[236:239], v[6:9]
	v_mfma_f32_16x16x32_bf16 v[2:5], v[212:215], v[236:239], v[2:5]
	v_mfma_f32_16x16x32_bf16 v[34:37], v[216:219], v[232:235], v[18:21]
	v_mfma_f32_16x16x32_bf16 v[6:9], v[186:189], v[240:243], v[6:9]
	v_mfma_f32_16x16x32_bf16 v[2:5], v[216:219], v[240:243], v[2:5]
	s_setprio 0
	s_barrier
	s_add_i32 s51, s51, 2
	s_add_u32 s49, s49, 0x100
	s_addc_u32 s50, s50, 0
	s_add_u32 s28, s28, 0x100
	s_addc_u32 s29, s29, 0
	s_cmpk_gt_u32 s51, 0x7d
	s_cbranch_scc0 .LBB0_126
	s_and_b64 vcc, exec, s[12:13]
	s_cbranch_vccz .LBB0_129
	s_barrier

; #define PG8_STAGE(bufoff, gbase, voff) do { _Pragma("unroll") for (int _i = 0; _i < 2; ++_i) \
;         __builtin_amdgcn_global_load_lds((const unsigned*)((const char*)(gbase) + (voff)[_i]), (LAS unsigned*)(lds + (bufoff) + ldsw + _i * 8192), 16, 0, 0); } while (0)
; #define PG8_LDA(dst, b, h) do { _Pragma("unroll") for (int m = 0; m < 4; ++m) _Pragma("unroll") for (int k = 0; k < 2; ++k) dst[m][k] = *(const LAS bf16x8*)(lds + PG8_SA(b, h) + aoff + m * 2048 + k * 1024); } while (0)
; #define PG8_LDB(dst, b, h) do { _Pragma("unroll") for (int n = 0; n < 2; ++n) _Pragma("unroll") for (int k = 0; k < 2; ++k) dst[n][k] = *(const LAS bf16x8*)(lds + PG8_SB(b, h) + boff + n * 2048 + k * 1024); } while (0)
; #define PG8_WAIT_V(n) asm volatile("s_waitcnt vmcnt(" #n ")" ::: "memory")
; #define PG8_WAIT_L(n) asm volatile("s_waitcnt lgkmcnt(" #n ")" ::: "memory")
; #define PG8_BAR __builtin_amdgcn_s_barrier()
; #define PG8_SCHED __builtin_amdgcn_sched_barrier(0)
; template <class Epi>
; __device__ __forceinline__ void gemm_phase(LAS unsigned char* lds, const Gemm g, const StaticOrder& S, const Epi& E, const int tid) {
;     ...
;             const bool last = (t == ntt - 2);
;             const bool s1 = Epi::TWO && (t >= nt), s2 = Epi::TWO && (t + 2 >= nt);
;             const char* a1 = (s1 ? cA2 + (size_t)(t - nt + 1) * kstep : cA + (size_t)(t + 1) * kstep);
;             const char* a2 = last ? nA : (s2 ? cA2 + (size_t)(t + 2 - nt) * kstep : cA + (size_t)(t + 2) * kstep);
;             const char* b2 = last ? nB : (s2 ? cB2 + (size_t)(t + 2 - nt) * kstep : cB + (size_t)(t + 2) * kstep);
;             const char* a3 = a2 + kstep; const char* b3 = b2 + kstep;
;             if constexpr (Epi::TWO) { if (t == nt) E.mid(acc, cur, wr, wc, fr, fq); }
;             if constexpr (SP2) {
;             PG8_LDB(B0, 0, 0); PG8_LDB(B1, 0, 1); PG8_SCHED; PG8_LDA(At, 0, 0); PG8_STAGE(PG8_SA(1, 1), a1 + hstep, voffA);
;             PG8_WAIT_V(8); PG8_WAIT_L(0); PG8_BAR; PG8_MMA(0, 0, At, B0); PG8_MMA(0, 1, At, B1); PG8_BAR; PG8_SCHED;
;             PG8_LDA(At, 0, 1); PG8_STAGE(PG8_SB(0, 0), b2, voffB); PG8_STAGE(PG8_SB(0, 1), b2 + bhs, voffB); PG8_STAGE(PG8_SA(0, 0), a2, voffA);
;             PG8_WAIT_V(8); PG8_WAIT_L(0); PG8_BAR; PG8_MMA(1, 0, At, B0); PG8_MMA(1, 1, At, B1); PG8_BAR; PG8_SCHED;
.LBB0_173:
	s_add_u32 s28, s26, 0xfff80080
	s_addc_u32 s29, s27, -1
	s_add_i32 s47, 0, 0x10000
	s_cmp_eq_u32 s46, 28
	s_cselect_b32 s31, s17, s29
	s_cselect_b32 s30, s42, s28
	v_add_u32_e32 v142, s47, v149
	s_cselect_b32 s29, s15, s45
	s_cselect_b32 s28, s43, s44
	s_add_i32 s50, 0, 0x14000
	ds_read_b128 v[156:159], v142
	ds_read_b128 v[160:163], v142 offset:1024
	ds_read_b128 v[164:167], v142 offset:2048
	ds_read_b128 v[178:181], v142 offset:3072
	v_add_u32_e32 v142, s50, v149
	ds_read_b128 v[182:185], v142
	ds_read_b128 v[186:189], v142 offset:1024
	ds_read_b128 v[190:193], v142 offset:2048
	ds_read_b128 v[194:197], v142 offset:3072
	v_lshl_add_u64 v[142:143], s[26:27], 0, v[140:141]
	s_add_i32 m0, s2, 0xc000
	ds_read_b128 v[198:201], v154
	global_load_lds_dwordx4 v[142:143], off
	ds_read_b128 v[212:215], v154 offset:1024
	ds_read_b128 v[216:219], v154 offset:2048
	ds_read_b128 v[220:223], v154 offset:3072
	v_lshl_add_u64 v[142:143], s[26:27], 0, v[138:139]
	s_add_i32 m0, s2, 0xe000
	s_nop 0
	global_load_lds_dwordx4 v[142:143], off
	ds_read_b128 v[224:227], v154 offset:4096
	ds_read_b128 v[228:231], v154 offset:5120
	ds_read_b128 v[232:235], v154 offset:6144
	ds_read_b128 v[236:239], v154 offset:7168
	s_waitcnt vmcnt(8)
	s_waitcnt lgkmcnt(0)
	s_barrier
	s_setprio 1
	s_waitcnt lgkmcnt(0)
	v_mfma_f32_16x16x32_bf16 v[126:129], v[156:159], v[198:201], v[126:129]
	v_mfma_f32_16x16x32_bf16 v[122:125], v[164:167], v[198:201], v[122:125]
	v_mfma_f32_16x16x32_bf16 v[110:113], v[156:159], v[216:219], v[110:113]
	v_mfma_f32_16x16x32_bf16 v[106:109], v[164:167], v[216:219], v[106:109]
	v_mfma_f32_16x16x32_bf16 v[94:97], v[156:159], v[224:227], v[94:97]
	v_mfma_f32_16x16x32_bf16 v[90:93], v[164:167], v[224:227], v[90:93]
	v_mfma_f32_16x16x32_bf16 v[78:81], v[156:159], v[232:235], v[78:81]
	v_mfma_f32_16x16x32_bf16 v[74:77], v[164:167], v[232:235], v[74:77]
	v_mfma_f32_16x16x32_bf16 v[126:129], v[160:163], v[212:215], v[126:129]
	v_mfma_f32_16x16x32_bf16 v[122:125], v[178:181], v[212:215], v[122:125]
	v_mfma_f32_16x16x32_bf16 v[110:113], v[160:163], v[220:223], v[110:113]
	v_mfma_f32_16x16x32_bf16 v[106:109], v[178:181], v[220:223], v[106:109]
	v_mfma_f32_16x16x32_bf16 v[94:97], v[160:163], v[228:231], v[94:97]
	v_mfma_f32_16x16x32_bf16 v[90:93], v[178:181], v[228:231], v[90:93]
	v_mfma_f32_16x16x32_bf16 v[78:81], v[160:163], v[236:239], v[78:81]
	v_mfma_f32_16x16x32_bf16 v[74:77], v[178:181], v[236:239], v[74:77]
	s_setprio 0
	s_setprio 1
	v_mfma_f32_16x16x32_bf16 v[118:121], v[182:185], v[198:201], v[118:121]
	v_mfma_f32_16x16x32_bf16 v[114:117], v[190:193], v[198:201], v[114:117]
	v_mfma_f32_16x16x32_bf16 v[102:105], v[182:185], v[216:219], v[102:105]
	v_mfma_f32_16x16x32_bf16 v[98:101], v[190:193], v[216:219], v[98:101]
	v_mfma_f32_16x16x32_bf16 v[86:89], v[182:185], v[224:227], v[86:89]
	v_mfma_f32_16x16x32_bf16 v[82:85], v[190:193], v[224:227], v[82:85]
	v_mfma_f32_16x16x32_bf16 v[70:73], v[182:185], v[232:235], v[70:73]
	v_mfma_f32_16x16x32_bf16 v[66:69], v[190:193], v[232:235], v[66:69]
	v_mfma_f32_16x16x32_bf16 v[118:121], v[186:189], v[212:215], v[118:121]
	v_mfma_f32_16x16x32_bf16 v[114:117], v[194:197], v[212:215], v[114:117]
	v_mfma_f32_16x16x32_bf16 v[102:105], v[186:189], v[220:223], v[102:105]
	v_mfma_f32_16x16x32_bf16 v[98:101], v[194:197], v[220:223], v[98:101]
	v_mfma_f32_16x16x32_bf16 v[86:89], v[186:189], v[228:231], v[86:89]
	v_mfma_f32_16x16x32_bf16 v[82:85], v[194:197], v[228:231], v[82:85]
	v_mfma_f32_16x16x32_bf16 v[70:73], v[186:189], v[236:239], v[70:73]
	v_mfma_f32_16x16x32_bf16 v[66:69], v[194:197], v[236:239], v[66:69]
	s_setprio 0
	s_barrier
	s_add_i32 s47, s47, s34
	v_lshl_add_u64 v[142:143], s[28:29], 0, v[0:1]
	s_mov_b32 m0, s47
	ds_read_b128 v[198:201], v154 offset:16384
	global_load_lds_dwordx4 v[142:143], off
	ds_read_b128 v[212:215], v154 offset:17408
	ds_read_b128 v[216:219], v154 offset:18432
	ds_read_b128 v[220:223], v154 offset:19456
	s_add_i32 m0, s47, 0x2000
	s_add_u32 s48, s28, 0x8000
	v_lshl_add_u64 v[168:169], s[28:29], 0, v[134:135]
	s_addc_u32 s49, s29, 0
	s_add_i32 s47, s50, s34
	global_load_lds_dwordx4 v[168:169], off
	ds_read_b128 v[224:227], v154 offset:20480
	ds_read_b128 v[228:231], v154 offset:21504
	ds_read_b128 v[232:235], v154 offset:22528
	v_lshl_add_u64 v[172:173], s[48:49], 0, v[0:1]
	s_mov_b32 m0, s47
	v_lshl_add_u64 v[174:175], s[30:31], 0, v[132:133]
	global_load_lds_dwordx4 v[172:173], off
	ds_read_b128 v[236:239], v154 offset:23552
	v_lshl_add_u64 v[172:173], s[48:49], 0, v[134:135]
	s_add_i32 m0, s47, 0x2000
	s_nop 0
	global_load_lds_dwordx4 v[172:173], off
	v_lshl_add_u64 v[172:173], s[30:31], 0, v[130:131]
	s_mov_b32 m0, s2
	s_nop 0
	global_load_lds_dwordx4 v[172:173], off
	s_mov_b32 m0, s25
	s_nop 0
	global_load_lds_dwordx4 v[174:175], off
	s_waitcnt vmcnt(8)
	s_waitcnt lgkmcnt(0)
	s_barrier
; #define PG8_STAGE(bufoff, gbase, voff) do { _Pragma("unroll") for (int _i = 0; _i < 2; ++_i) \
;         __builtin_amdgcn_global_load_lds((const unsigned*)((const char*)(gbase) + (voff)[_i]), (LAS unsigned*)(lds + (bufoff) + ldsw + _i * 8192), 16, 0, 0); } while (0)
; #define PG8_LDA(dst, b, h) do { _Pragma("unroll") for (int m = 0; m < 4; ++m) _Pragma("unroll") for (int k = 0; k < 2; ++k) dst[m][k] = *(const LAS bf16x8*)(lds + PG8_SA(b, h) + aoff + m * 2048 + k * 1024); } while (0)
; #define PG8_LDB(dst, b, h) do { _Pragma("unroll") for (int n = 0; n < 2; ++n) _Pragma("unroll") for (int k = 0; k < 2; ++k) dst[n][k] = *(const LAS bf16x8*)(lds + PG8_SB(b, h) + boff + n * 2048 + k * 1024); } while (0)
; #define PG8_MMA(ai, bj, At, Bt) do { __builtin_amdgcn_s_setprio(1); _Pragma("unroll") for (int m = 0; m < 4; ++m) _Pragma("unroll") for (int n = 0; n < 2; ++n) _Pragma("unroll") for (int k = 0; k < 2; ++k) \
;         acc[ai][bj][m][n] = __builtin_amdgcn_mfma_f32_16x16x32_bf16(Bt[n][k], At[m][k], acc[ai][bj][m][n], 0, 0, 0); __builtin_amdgcn_s_setprio(0); } while (0)
; #define PG8_WAIT_V(n) asm volatile("s_waitcnt vmcnt(" #n ")" ::: "memory")
; #define PG8_WAIT_L(n) asm volatile("s_waitcnt lgkmcnt(" #n ")" ::: "memory")
; #define PG8_BAR __builtin_amdgcn_s_barrier()
; #define PG8_SCHED __builtin_amdgcn_sched_barrier(0)
; template <class Epi>
; __device__ __forceinline__ void gemm_phase(LAS unsigned char* lds, const Gemm g, const StaticOrder& S, const Epi& E, const int tid) {
;     ...
;             PG8_WAIT_V(8); PG8_WAIT_L(0); PG8_BAR; PG8_MMA(1, 0, At, B0); PG8_MMA(1, 1, At, B1); PG8_BAR; PG8_SCHED;
;             PG8_LDB(B0, 1, 0); PG8_LDB(B1, 1, 1); PG8_SCHED; PG8_LDA(At, 1, 0); PG8_STAGE(PG8_SA(0, 1), a2 + hstep, voffA);
;             PG8_WAIT_V(8); PG8_WAIT_L(0); PG8_BAR; PG8_MMA(0, 0, At, B0); PG8_MMA(0, 1, At, B1); PG8_BAR; PG8_SCHED;
	s_setprio 1
	s_waitcnt lgkmcnt(0)
	v_mfma_f32_16x16x32_bf16 v[62:65], v[156:159], v[198:201], v[62:65]
	v_mfma_f32_16x16x32_bf16 v[58:61], v[164:167], v[198:201], v[58:61]
	v_mfma_f32_16x16x32_bf16 v[46:49], v[156:159], v[216:219], v[46:49]
	v_mfma_f32_16x16x32_bf16 v[42:45], v[164:167], v[216:219], v[42:45]
	v_mfma_f32_16x16x32_bf16 v[30:33], v[156:159], v[224:227], v[30:33]
	v_mfma_f32_16x16x32_bf16 v[26:29], v[164:167], v[224:227], v[26:29]
	v_mfma_f32_16x16x32_bf16 v[14:17], v[156:159], v[232:235], v[14:17]
	v_mfma_f32_16x16x32_bf16 v[10:13], v[164:167], v[232:235], v[10:13]
	v_mfma_f32_16x16x32_bf16 v[62:65], v[160:163], v[212:215], v[62:65]
	v_mfma_f32_16x16x32_bf16 v[58:61], v[178:181], v[212:215], v[58:61]
	v_mfma_f32_16x16x32_bf16 v[46:49], v[160:163], v[220:223], v[46:49]
	v_mfma_f32_16x16x32_bf16 v[42:45], v[178:181], v[220:223], v[42:45]
	v_mfma_f32_16x16x32_bf16 v[30:33], v[160:163], v[228:231], v[30:33]
	v_mfma_f32_16x16x32_bf16 v[26:29], v[178:181], v[228:231], v[26:29]
	v_mfma_f32_16x16x32_bf16 v[14:17], v[160:163], v[236:239], v[14:17]
	v_mfma_f32_16x16x32_bf16 v[10:13], v[178:181], v[236:239], v[10:13]
	s_setprio 0
	s_setprio 1
	v_mfma_f32_16x16x32_bf16 v[54:57], v[182:185], v[198:201], v[54:57]
	v_mfma_f32_16x16x32_bf16 v[50:53], v[190:193], v[198:201], v[50:53]
	v_mfma_f32_16x16x32_bf16 v[38:41], v[182:185], v[216:219], v[38:41]
	v_mfma_f32_16x16x32_bf16 v[34:37], v[190:193], v[216:219], v[34:37]
	v_mfma_f32_16x16x32_bf16 v[22:25], v[182:185], v[224:227], v[22:25]
	v_mfma_f32_16x16x32_bf16 v[18:21], v[190:193], v[224:227], v[18:21]
	v_mfma_f32_16x16x32_bf16 v[6:9], v[182:185], v[232:235], v[6:9]
	v_mfma_f32_16x16x32_bf16 v[2:5], v[190:193], v[232:235], v[2:5]
	v_mfma_f32_16x16x32_bf16 v[54:57], v[186:189], v[212:215], v[54:57]
	v_mfma_f32_16x16x32_bf16 v[50:53], v[194:197], v[212:215], v[50:53]
	v_mfma_f32_16x16x32_bf16 v[38:41], v[186:189], v[220:223], v[38:41]
	v_mfma_f32_16x16x32_bf16 v[34:37], v[194:197], v[220:223], v[34:37]
	v_mfma_f32_16x16x32_bf16 v[22:25], v[186:189], v[228:231], v[22:25]
	v_mfma_f32_16x16x32_bf16 v[18:21], v[194:197], v[228:231], v[18:21]
	v_mfma_f32_16x16x32_bf16 v[6:9], v[186:189], v[236:239], v[6:9]
	v_mfma_f32_16x16x32_bf16 v[2:5], v[194:197], v[236:239], v[2:5]
	s_setprio 0
	s_barrier
	s_add_i32 s47, 0, 0x18000
	v_add_u32_e32 v155, s47, v149
	s_add_i32 s48, 0, 0x1c000
	ds_read_b128 v[156:159], v155
	ds_read_b128 v[160:163], v155 offset:1024
	ds_read_b128 v[164:167], v155 offset:2048
	ds_read_b128 v[178:181], v155 offset:3072
	v_add_u32_e32 v155, s48, v149
	ds_read_b128 v[182:185], v155
	ds_read_b128 v[186:189], v155 offset:1024
	ds_read_b128 v[190:193], v155 offset:2048
	ds_read_b128 v[194:197], v155 offset:3072
	s_add_u32 s30, s30, 0x80000
	s_addc_u32 s31, s31, 0
	s_mov_b32 m0, s35
	v_lshl_add_u64 v[176:177], s[30:31], 0, v[130:131]
	ds_read_b128 v[198:201], v154 offset:32768
	global_load_lds_dwordx4 v[176:177], off
	ds_read_b128 v[212:215], v154 offset:33792
	ds_read_b128 v[216:219], v154 offset:34816
	ds_read_b128 v[220:223], v154 offset:35840
	v_lshl_add_u64 v[176:177], s[30:31], 0, v[132:133]
	s_mov_b32 m0, s36
	s_nop 0
	global_load_lds_dwordx4 v[176:177], off
	ds_read_b128 v[224:227], v154 offset:36864
	ds_read_b128 v[228:231], v154 offset:37888
	ds_read_b128 v[232:235], v154 offset:38912
	ds_read_b128 v[236:239], v154 offset:39936
	s_waitcnt vmcnt(8)
	s_waitcnt lgkmcnt(0)
	s_barrier
	s_setprio 1
	s_waitcnt lgkmcnt(0)
	v_mfma_f32_16x16x32_bf16 v[126:129], v[156:159], v[198:201], v[126:129]
	v_mfma_f32_16x16x32_bf16 v[122:125], v[164:167], v[198:201], v[122:125]
	v_mfma_f32_16x16x32_bf16 v[110:113], v[156:159], v[216:219], v[110:113]
	v_mfma_f32_16x16x32_bf16 v[106:109], v[164:167], v[216:219], v[106:109]
	v_mfma_f32_16x16x32_bf16 v[94:97], v[156:159], v[224:227], v[94:97]
	v_mfma_f32_16x16x32_bf16 v[90:93], v[164:167], v[224:227], v[90:93]
	v_mfma_f32_16x16x32_bf16 v[78:81], v[156:159], v[232:235], v[78:81]
	v_mfma_f32_16x16x32_bf16 v[74:77], v[164:167], v[232:235], v[74:77]
	v_mfma_f32_16x16x32_bf16 v[126:129], v[160:163], v[212:215], v[126:129]
	v_mfma_f32_16x16x32_bf16 v[122:125], v[178:181], v[212:215], v[122:125]
	v_mfma_f32_16x16x32_bf16 v[110:113], v[160:163], v[220:223], v[110:113]
	v_mfma_f32_16x16x32_bf16 v[106:109], v[178:181], v[220:223], v[106:109]
	v_mfma_f32_16x16x32_bf16 v[94:97], v[160:163], v[228:231], v[94:97]
	v_mfma_f32_16x16x32_bf16 v[90:93], v[178:181], v[228:231], v[90:93]
	v_mfma_f32_16x16x32_bf16 v[78:81], v[160:163], v[236:239], v[78:81]
	v_mfma_f32_16x16x32_bf16 v[74:77], v[178:181], v[236:239], v[74:77]
	s_setprio 0
	s_setprio 1
	v_mfma_f32_16x16x32_bf16 v[118:121], v[182:185], v[198:201], v[118:121]
	v_mfma_f32_16x16x32_bf16 v[114:117], v[190:193], v[198:201], v[114:117]
	v_mfma_f32_16x16x32_bf16 v[102:105], v[182:185], v[216:219], v[102:105]
	v_mfma_f32_16x16x32_bf16 v[98:101], v[190:193], v[216:219], v[98:101]
	v_mfma_f32_16x16x32_bf16 v[86:89], v[182:185], v[224:227], v[86:89]
	v_mfma_f32_16x16x32_bf16 v[82:85], v[190:193], v[224:227], v[82:85]
	v_mfma_f32_16x16x32_bf16 v[70:73], v[182:185], v[232:235], v[70:73]
	v_mfma_f32_16x16x32_bf16 v[66:69], v[190:193], v[232:235], v[66:69]
	v_mfma_f32_16x16x32_bf16 v[118:121], v[186:189], v[212:215], v[118:121]
	v_mfma_f32_16x16x32_bf16 v[114:117], v[194:197], v[212:215], v[114:117]
	v_mfma_f32_16x16x32_bf16 v[102:105], v[186:189], v[220:223], v[102:105]
	v_mfma_f32_16x16x32_bf16 v[98:101], v[194:197], v[220:223], v[98:101]
	v_mfma_f32_16x16x32_bf16 v[86:89], v[186:189], v[228:231], v[86:89]
	v_mfma_f32_16x16x32_bf16 v[82:85], v[194:197], v[228:231], v[82:85]
	v_mfma_f32_16x16x32_bf16 v[70:73], v[186:189], v[236:239], v[70:73]
	v_mfma_f32_16x16x32_bf16 v[66:69], v[194:197], v[236:239], v[66:69]
	s_setprio 0
	s_barrier
; #define PG8_STAGE(bufoff, gbase, voff) do { _Pragma("unroll") for (int _i = 0; _i < 2; ++_i) \
;         __builtin_amdgcn_global_load_lds((const unsigned*)((const char*)(gbase) + (voff)[_i]), (LAS unsigned*)(lds + (bufoff) + ldsw + _i * 8192), 16, 0, 0); } while (0)
; #define PG8_LDA(dst, b, h) do { _Pragma("unroll") for (int m = 0; m < 4; ++m) _Pragma("unroll") for (int k = 0; k < 2; ++k) dst[m][k] = *(const LAS bf16x8*)(lds + PG8_SA(b, h) + aoff + m * 2048 + k * 1024); } while (0)
; #define PG8_MMA(ai, bj, At, Bt) do { __builtin_amdgcn_s_setprio(1); _Pragma("unroll") for (int m = 0; m < 4; ++m) _Pragma("unroll") for (int n = 0; n < 2; ++n) _Pragma("unroll") for (int k = 0; k < 2; ++k) \
;         acc[ai][bj][m][n] = __builtin_amdgcn_mfma_f32_16x16x32_bf16(Bt[n][k], At[m][k], acc[ai][bj][m][n], 0, 0, 0); __builtin_amdgcn_s_setprio(0); } while (0)
; #define PG8_WAIT_V(n) asm volatile("s_waitcnt vmcnt(" #n ")" ::: "memory")
; #define PG8_WAIT_L(n) asm volatile("s_waitcnt lgkmcnt(" #n ")" ::: "memory")
; #define PG8_BAR __builtin_amdgcn_s_barrier()
; #define PG8_SCHED __builtin_amdgcn_sched_barrier(0)
; template <class Epi>
; __device__ __forceinline__ void gemm_phase(LAS unsigned char* lds, const Gemm g, const StaticOrder& S, const Epi& E, const int tid) {
;     ...
;             PG8_LDA(At, 1, 1); PG8_STAGE(PG8_SB(1, 0), b3, voffB); PG8_STAGE(PG8_SB(1, 1), b3 + bhs, voffB); PG8_STAGE(PG8_SA(1, 0), a3, voffA);
;             PG8_WAIT_V(8); PG8_WAIT_L(0); PG8_BAR; PG8_MMA(1, 0, At, B0); PG8_MMA(1, 1, At, B1); PG8_BAR; PG8_SCHED;
;     ...
;         if (ALIGN_EPI) { if (wr == 0) PG8_BAR; }
	s_add_i32 s30, s47, s34
	v_lshl_add_u64 v[142:143], v[142:143], 0, s[70:71]
	s_mov_b32 m0, s30
	ds_read_b128 v[198:201], v154 offset:49152
	global_load_lds_dwordx4 v[142:143], off
	ds_read_b128 v[212:215], v154 offset:50176
	ds_read_b128 v[216:219], v154 offset:51200
	ds_read_b128 v[220:223], v154 offset:52224
	s_add_i32 m0, s30, 0x2000
	s_add_u32 s28, s28, 0x8080
	v_lshl_add_u64 v[142:143], v[168:169], 0, s[70:71]
	s_addc_u32 s29, s29, 0
	s_add_i32 s30, s48, s34
	global_load_lds_dwordx4 v[142:143], off
	ds_read_b128 v[224:227], v154 offset:53248
	ds_read_b128 v[228:231], v154 offset:54272
	ds_read_b128 v[232:235], v154 offset:55296
	v_lshl_add_u64 v[142:143], s[28:29], 0, v[0:1]
	s_mov_b32 m0, s30
	s_nop 0
	global_load_lds_dwordx4 v[142:143], off
	ds_read_b128 v[236:239], v154 offset:56320
	v_lshl_add_u64 v[142:143], s[28:29], 0, v[134:135]
	s_add_i32 m0, s30, 0x2000
	s_nop 0
	global_load_lds_dwordx4 v[142:143], off
	v_lshl_add_u64 v[142:143], v[172:173], 0, s[70:71]
	s_mov_b32 m0, s37
	s_nop 0
	global_load_lds_dwordx4 v[142:143], off
	v_lshl_add_u64 v[142:143], v[174:175], 0, s[70:71]
	s_mov_b32 m0, s38
	s_nop 0
	global_load_lds_dwordx4 v[142:143], off
	s_waitcnt vmcnt(8)
	s_waitcnt lgkmcnt(0)
	s_barrier
	s_setprio 1
	s_waitcnt lgkmcnt(0)
	v_mfma_f32_16x16x32_bf16 v[62:65], v[156:159], v[198:201], v[62:65]
	v_mfma_f32_16x16x32_bf16 v[58:61], v[164:167], v[198:201], v[58:61]
	v_mfma_f32_16x16x32_bf16 v[46:49], v[156:159], v[216:219], v[46:49]
	v_mfma_f32_16x16x32_bf16 v[42:45], v[164:167], v[216:219], v[42:45]
	v_mfma_f32_16x16x32_bf16 v[30:33], v[156:159], v[224:227], v[30:33]
	v_mfma_f32_16x16x32_bf16 v[26:29], v[164:167], v[224:227], v[26:29]
	v_mfma_f32_16x16x32_bf16 v[14:17], v[156:159], v[232:235], v[14:17]
	v_mfma_f32_16x16x32_bf16 v[10:13], v[164:167], v[232:235], v[10:13]
	v_mfma_f32_16x16x32_bf16 v[62:65], v[160:163], v[212:215], v[62:65]
	v_mfma_f32_16x16x32_bf16 v[58:61], v[178:181], v[212:215], v[58:61]
	v_mfma_f32_16x16x32_bf16 v[46:49], v[160:163], v[220:223], v[46:49]
	v_mfma_f32_16x16x32_bf16 v[42:45], v[178:181], v[220:223], v[42:45]
	v_mfma_f32_16x16x32_bf16 v[30:33], v[160:163], v[228:231], v[30:33]
	v_mfma_f32_16x16x32_bf16 v[26:29], v[178:181], v[228:231], v[26:29]
	v_mfma_f32_16x16x32_bf16 v[14:17], v[160:163], v[236:239], v[14:17]
	v_mfma_f32_16x16x32_bf16 v[10:13], v[178:181], v[236:239], v[10:13]
	s_setprio 0
	s_setprio 1
	v_mfma_f32_16x16x32_bf16 v[54:57], v[182:185], v[198:201], v[54:57]
	v_mfma_f32_16x16x32_bf16 v[50:53], v[190:193], v[198:201], v[50:53]
	v_mfma_f32_16x16x32_bf16 v[38:41], v[182:185], v[216:219], v[38:41]
	v_mfma_f32_16x16x32_bf16 v[34:37], v[190:193], v[216:219], v[34:37]
	v_mfma_f32_16x16x32_bf16 v[22:25], v[182:185], v[224:227], v[22:25]
	v_mfma_f32_16x16x32_bf16 v[18:21], v[190:193], v[224:227], v[18:21]
	v_mfma_f32_16x16x32_bf16 v[6:9], v[182:185], v[232:235], v[6:9]
	v_mfma_f32_16x16x32_bf16 v[2:5], v[190:193], v[232:235], v[2:5]
	v_mfma_f32_16x16x32_bf16 v[54:57], v[186:189], v[212:215], v[54:57]
	v_mfma_f32_16x16x32_bf16 v[50:53], v[194:197], v[212:215], v[50:53]
	v_mfma_f32_16x16x32_bf16 v[38:41], v[186:189], v[220:223], v[38:41]
	v_mfma_f32_16x16x32_bf16 v[34:37], v[194:197], v[220:223], v[34:37]
	v_mfma_f32_16x16x32_bf16 v[22:25], v[186:189], v[228:231], v[22:25]
	v_mfma_f32_16x16x32_bf16 v[18:21], v[194:197], v[228:231], v[18:21]
	v_mfma_f32_16x16x32_bf16 v[6:9], v[186:189], v[236:239], v[6:9]
	v_mfma_f32_16x16x32_bf16 v[2:5], v[194:197], v[236:239], v[2:5]
	s_setprio 0
	s_barrier
	s_add_i32 s46, s46, 2
	s_add_u32 s44, s44, 0x100
	s_addc_u32 s45, s45, 0
	s_add_u32 s26, s26, 0x100
	s_addc_u32 s27, s27, 0
	s_cmp_gt_u32 s46, 29
	s_cbranch_scc0 .LBB0_173
	v_readlane_b32 s42, v251, 53
	s_and_b64 vcc, exec, s[12:13]
	v_readlane_b32 s43, v251, 54
	s_cbranch_vccz .LBB0_176
	s_barrier

; #define PG8_STAGE(bufoff, gbase, voff) do { _Pragma("unroll") for (int _i = 0; _i < 2; ++_i) \
;         __builtin_amdgcn_global_load_lds((const unsigned*)((const char*)(gbase) + (voff)[_i]), (LAS unsigned*)(lds + (bufoff) + ldsw + _i * 8192), 16, 0, 0); } while (0)
; #define PG8_LDA(dst, b, h) do { _Pragma("unroll") for (int m = 0; m < 4; ++m) _Pragma("unroll") for (int k = 0; k < 2; ++k) dst[m][k] = *(const LAS bf16x8*)(lds + PG8_SA(b, h) + aoff + m * 2048 + k * 1024); } while (0)
; #define PG8_LDB(dst, b, h) do { _Pragma("unroll") for (int n = 0; n < 2; ++n) _Pragma("unroll") for (int k = 0; k < 2; ++k) dst[n][k] = *(const LAS bf16x8*)(lds + PG8_SB(b, h) + boff + n * 2048 + k * 1024); } while (0)
; #define PG8_WAIT_V(n) asm volatile("s_waitcnt vmcnt(" #n ")" ::: "memory")
; #define PG8_WAIT_L(n) asm volatile("s_waitcnt lgkmcnt(" #n ")" ::: "memory")
; #define PG8_BAR __builtin_amdgcn_s_barrier()
; #define PG8_SCHED __builtin_amdgcn_sched_barrier(0)
; template <class Epi>
; __device__ __forceinline__ void gemm_phase(LAS unsigned char* lds, const Gemm g, const StaticOrder& S, const Epi& E, const int tid) {
;     ...
;             const bool last = (t == ntt - 2);
;             const bool s1 = Epi::TWO && (t >= nt), s2 = Epi::TWO && (t + 2 >= nt);
;             const char* a1 = (s1 ? cA2 + (size_t)(t - nt + 1) * kstep : cA + (size_t)(t + 1) * kstep);
;             const char* a2 = last ? nA : (s2 ? cA2 + (size_t)(t + 2 - nt) * kstep : cA + (size_t)(t + 2) * kstep);
;             const char* b2 = last ? nB : (s2 ? cB2 + (size_t)(t + 2 - nt) * kstep : cB + (size_t)(t + 2) * kstep);
;             const char* a3 = a2 + kstep; const char* b3 = b2 + kstep;
;             if constexpr (Epi::TWO) { if (t == nt) E.mid(acc, cur, wr, wc, fr, fq); }
;             if constexpr (SP2) {
;             PG8_LDB(B0, 0, 0); PG8_LDB(B1, 0, 1); PG8_SCHED; PG8_LDA(At, 0, 0); PG8_STAGE(PG8_SA(1, 1), a1 + hstep, voffA);
;             PG8_WAIT_V(8); PG8_WAIT_L(0); PG8_BAR; PG8_MMA(0, 0, At, B0); PG8_MMA(0, 1, At, B1); PG8_BAR; PG8_SCHED;
;             PG8_LDA(At, 0, 1); PG8_STAGE(PG8_SB(0, 0), b2, voffB); PG8_STAGE(PG8_SB(0, 1), b2 + bhs, voffB); PG8_STAGE(PG8_SA(0, 0), a2, voffA);
;             PG8_WAIT_V(8); PG8_WAIT_L(0); PG8_BAR; PG8_MMA(1, 0, At, B0); PG8_MMA(1, 1, At, B1); PG8_BAR; PG8_SCHED;
.LBB0_206:
	s_add_u32 s30, s28, 0xfffe0080
	s_addc_u32 s31, s29, -1
	s_add_i32 s52, 0, 0x10000
	s_cmp_eq_u32 s51, 4
	s_cselect_b32 s35, s17, s31
	s_cselect_b32 s34, s27, s30
	s_cselect_b32 s31, s15, s50
	s_cselect_b32 s30, s33, s49
	s_add_i32 s54, 0, 0x14000
	v_add_u32_e32 v30, s52, v193
	v_add_u32_e32 v54, s54, v193
	ds_read_b128 v[18:21], v30
	ds_read_b128 v[22:25], v30 offset:1024
	ds_read_b128 v[26:29], v30 offset:2048
	ds_read_b128 v[30:33], v30 offset:3072
	ds_read_b128 v[42:45], v54
	ds_read_b128 v[46:49], v54 offset:1024
	ds_read_b128 v[50:53], v54 offset:2048
	ds_read_b128 v[54:57], v54 offset:3072
	v_lshl_add_u64 v[172:173], s[28:29], 0, v[180:181]
	s_add_i32 m0, s37, 0xc000
	ds_read_b128 v[182:185], v199
	global_load_lds_dwordx4 v[172:173], off
	ds_read_b128 v[186:189], v199 offset:1024
	ds_read_b128 v[212:215], v199 offset:2048
	ds_read_b128 v[216:219], v199 offset:3072
	v_lshl_add_u64 v[172:173], s[28:29], 0, v[178:179]
	s_add_i32 m0, s37, 0xe000
	s_nop 0
	global_load_lds_dwordx4 v[172:173], off
	ds_read_b128 v[220:223], v199 offset:4096
	ds_read_b128 v[224:227], v199 offset:5120
	ds_read_b128 v[228:231], v199 offset:6144
	ds_read_b128 v[232:235], v199 offset:7168
	s_waitcnt vmcnt(8)
	s_waitcnt lgkmcnt(0)
	s_barrier
	s_setprio 1
	s_waitcnt lgkmcnt(0)
	v_mfma_f32_16x16x32_bf16 v[158:161], v[18:21], v[182:185], v[158:161]
	v_mfma_f32_16x16x32_bf16 v[154:157], v[26:29], v[182:185], v[154:157]
	v_mfma_f32_16x16x32_bf16 v[142:145], v[18:21], v[212:215], v[142:145]
	v_mfma_f32_16x16x32_bf16 v[138:141], v[26:29], v[212:215], v[138:141]
	v_mfma_f32_16x16x32_bf16 v[126:129], v[18:21], v[220:223], v[126:129]
	v_mfma_f32_16x16x32_bf16 v[122:125], v[26:29], v[220:223], v[122:125]
	v_mfma_f32_16x16x32_bf16 v[110:113], v[18:21], v[228:231], v[110:113]
	v_mfma_f32_16x16x32_bf16 v[106:109], v[26:29], v[228:231], v[106:109]
	v_mfma_f32_16x16x32_bf16 v[158:161], v[22:25], v[186:189], v[158:161]
	v_mfma_f32_16x16x32_bf16 v[154:157], v[30:33], v[186:189], v[154:157]
	v_mfma_f32_16x16x32_bf16 v[142:145], v[22:25], v[216:219], v[142:145]
	v_mfma_f32_16x16x32_bf16 v[138:141], v[30:33], v[216:219], v[138:141]
	v_mfma_f32_16x16x32_bf16 v[126:129], v[22:25], v[224:227], v[126:129]
	v_mfma_f32_16x16x32_bf16 v[122:125], v[30:33], v[224:227], v[122:125]
	v_mfma_f32_16x16x32_bf16 v[110:113], v[22:25], v[232:235], v[110:113]
	v_mfma_f32_16x16x32_bf16 v[106:109], v[30:33], v[232:235], v[106:109]
	s_setprio 0
	s_setprio 1
	v_mfma_f32_16x16x32_bf16 v[150:153], v[42:45], v[182:185], v[150:153]
	v_mfma_f32_16x16x32_bf16 v[146:149], v[50:53], v[182:185], v[146:149]
	v_mfma_f32_16x16x32_bf16 v[134:137], v[42:45], v[212:215], v[134:137]
	v_mfma_f32_16x16x32_bf16 v[130:133], v[50:53], v[212:215], v[130:133]
	v_mfma_f32_16x16x32_bf16 v[118:121], v[42:45], v[220:223], v[118:121]
	v_mfma_f32_16x16x32_bf16 v[114:117], v[50:53], v[220:223], v[114:117]
	v_mfma_f32_16x16x32_bf16 v[102:105], v[42:45], v[228:231], v[102:105]
	v_mfma_f32_16x16x32_bf16 v[98:101], v[50:53], v[228:231], v[98:101]
	v_mfma_f32_16x16x32_bf16 v[150:153], v[46:49], v[186:189], v[150:153]
	v_mfma_f32_16x16x32_bf16 v[146:149], v[54:57], v[186:189], v[146:149]
	v_mfma_f32_16x16x32_bf16 v[134:137], v[46:49], v[216:219], v[134:137]
	v_mfma_f32_16x16x32_bf16 v[130:133], v[54:57], v[216:219], v[130:133]
	v_mfma_f32_16x16x32_bf16 v[118:121], v[46:49], v[224:227], v[118:121]
	v_mfma_f32_16x16x32_bf16 v[114:117], v[54:57], v[224:227], v[114:117]
	v_mfma_f32_16x16x32_bf16 v[102:105], v[46:49], v[232:235], v[102:105]
	v_mfma_f32_16x16x32_bf16 v[98:101], v[54:57], v[232:235], v[98:101]
	s_setprio 0
	s_barrier
	s_add_i32 s52, s52, s36
	v_lshl_add_u64 v[172:173], s[30:31], 0, v[0:1]
	s_mov_b32 m0, s52
	ds_read_b128 v[182:185], v199 offset:16384
	global_load_lds_dwordx4 v[172:173], off
	ds_read_b128 v[186:189], v199 offset:17408
	ds_read_b128 v[212:215], v199 offset:18432
	ds_read_b128 v[216:219], v199 offset:19456
	s_add_i32 m0, s52, 0x2000
	s_add_u32 s52, s30, 0x2000
	v_lshl_add_u64 v[174:175], s[30:31], 0, v[166:167]
	s_addc_u32 s53, s31, 0
	s_add_i32 s54, s54, s36
	global_load_lds_dwordx4 v[174:175], off
	ds_read_b128 v[220:223], v199 offset:20480
	ds_read_b128 v[224:227], v199 offset:21504
	ds_read_b128 v[228:231], v199 offset:22528
	v_lshl_add_u64 v[176:177], s[52:53], 0, v[0:1]
	s_mov_b32 m0, s54
	v_lshl_add_u64 v[200:201], s[34:35], 0, v[164:165]
	global_load_lds_dwordx4 v[176:177], off
	ds_read_b128 v[232:235], v199 offset:23552
	v_lshl_add_u64 v[176:177], s[52:53], 0, v[166:167]
	s_add_i32 m0, s54, 0x2000
	s_nop 0
	global_load_lds_dwordx4 v[176:177], off
	v_lshl_add_u64 v[176:177], s[34:35], 0, v[162:163]
	s_mov_b32 m0, s37
	s_nop 0
	global_load_lds_dwordx4 v[176:177], off
	s_mov_b32 m0, s38
	s_nop 0
	global_load_lds_dwordx4 v[200:201], off
	s_waitcnt vmcnt(8)
	s_waitcnt lgkmcnt(0)
	s_barrier
; #define PG8_STAGE(bufoff, gbase, voff) do { _Pragma("unroll") for (int _i = 0; _i < 2; ++_i) \
;         __builtin_amdgcn_global_load_lds((const unsigned*)((const char*)(gbase) + (voff)[_i]), (LAS unsigned*)(lds + (bufoff) + ldsw + _i * 8192), 16, 0, 0); } while (0)
; #define PG8_LDA(dst, b, h) do { _Pragma("unroll") for (int m = 0; m < 4; ++m) _Pragma("unroll") for (int k = 0; k < 2; ++k) dst[m][k] = *(const LAS bf16x8*)(lds + PG8_SA(b, h) + aoff + m * 2048 + k * 1024); } while (0)
; #define PG8_LDB(dst, b, h) do { _Pragma("unroll") for (int n = 0; n < 2; ++n) _Pragma("unroll") for (int k = 0; k < 2; ++k) dst[n][k] = *(const LAS bf16x8*)(lds + PG8_SB(b, h) + boff + n * 2048 + k * 1024); } while (0)
; #define PG8_MMA(ai, bj, At, Bt) do { __builtin_amdgcn_s_setprio(1); _Pragma("unroll") for (int m = 0; m < 4; ++m) _Pragma("unroll") for (int n = 0; n < 2; ++n) _Pragma("unroll") for (int k = 0; k < 2; ++k) \
;         acc[ai][bj][m][n] = __builtin_amdgcn_mfma_f32_16x16x32_bf16(Bt[n][k], At[m][k], acc[ai][bj][m][n], 0, 0, 0); __builtin_amdgcn_s_setprio(0); } while (0)
; #define PG8_WAIT_V(n) asm volatile("s_waitcnt vmcnt(" #n ")" ::: "memory")
; #define PG8_WAIT_L(n) asm volatile("s_waitcnt lgkmcnt(" #n ")" ::: "memory")
; #define PG8_BAR __builtin_amdgcn_s_barrier()
; #define PG8_SCHED __builtin_amdgcn_sched_barrier(0)
; template <class Epi>
; __device__ __forceinline__ void gemm_phase(LAS unsigned char* lds, const Gemm g, const StaticOrder& S, const Epi& E, const int tid) {
;     ...
;             PG8_WAIT_V(8); PG8_WAIT_L(0); PG8_BAR; PG8_MMA(1, 0, At, B0); PG8_MMA(1, 1, At, B1); PG8_BAR; PG8_SCHED;
;             PG8_LDB(B0, 1, 0); PG8_LDB(B1, 1, 1); PG8_SCHED; PG8_LDA(At, 1, 0); PG8_STAGE(PG8_SA(0, 1), a2 + hstep, voffA);
;             PG8_WAIT_V(8); PG8_WAIT_L(0); PG8_BAR; PG8_MMA(0, 0, At, B0); PG8_MMA(0, 1, At, B1); PG8_BAR; PG8_SCHED;
	s_setprio 1
	s_waitcnt lgkmcnt(0)
	v_mfma_f32_16x16x32_bf16 v[94:97], v[18:21], v[182:185], v[94:97]
	v_mfma_f32_16x16x32_bf16 v[90:93], v[26:29], v[182:185], v[90:93]
	v_mfma_f32_16x16x32_bf16 v[78:81], v[18:21], v[212:215], v[78:81]
	v_mfma_f32_16x16x32_bf16 v[74:77], v[26:29], v[212:215], v[74:77]
	v_mfma_f32_16x16x32_bf16 v[62:65], v[18:21], v[220:223], v[62:65]
	v_mfma_f32_16x16x32_bf16 v[58:61], v[26:29], v[220:223], v[58:61]
	v_mfma_f32_16x16x32_bf16 v[14:17], v[18:21], v[228:231], v[14:17]
	v_mfma_f32_16x16x32_bf16 v[10:13], v[26:29], v[228:231], v[10:13]
	v_mfma_f32_16x16x32_bf16 v[94:97], v[22:25], v[186:189], v[94:97]
	v_mfma_f32_16x16x32_bf16 v[90:93], v[30:33], v[186:189], v[90:93]
	v_mfma_f32_16x16x32_bf16 v[78:81], v[22:25], v[216:219], v[78:81]
	v_mfma_f32_16x16x32_bf16 v[74:77], v[30:33], v[216:219], v[74:77]
	v_mfma_f32_16x16x32_bf16 v[62:65], v[22:25], v[224:227], v[62:65]
	v_mfma_f32_16x16x32_bf16 v[58:61], v[30:33], v[224:227], v[58:61]
	v_mfma_f32_16x16x32_bf16 v[14:17], v[22:25], v[232:235], v[14:17]
	v_mfma_f32_16x16x32_bf16 v[10:13], v[30:33], v[232:235], v[10:13]
	s_setprio 0
	s_setprio 1
	v_mfma_f32_16x16x32_bf16 v[38:41], v[42:45], v[220:223], v[38:41]
	v_mfma_f32_16x16x32_bf16 v[34:37], v[50:53], v[220:223], v[34:37]
	v_mfma_f32_16x16x32_bf16 v[6:9], v[42:45], v[228:231], v[6:9]
	v_mfma_f32_16x16x32_bf16 v[2:5], v[50:53], v[228:231], v[2:5]
	v_mfma_f32_16x16x32_bf16 v[18:21], v[42:45], v[182:185], v[86:89]
	v_mfma_f32_16x16x32_bf16 v[22:25], v[50:53], v[182:185], v[82:85]
	v_mfma_f32_16x16x32_bf16 v[26:29], v[42:45], v[212:215], v[70:73]
	v_mfma_f32_16x16x32_bf16 v[30:33], v[50:53], v[212:215], v[66:69]
	v_mfma_f32_16x16x32_bf16 v[38:41], v[46:49], v[224:227], v[38:41]
	v_mfma_f32_16x16x32_bf16 v[34:37], v[54:57], v[224:227], v[34:37]
	v_mfma_f32_16x16x32_bf16 v[6:9], v[46:49], v[232:235], v[6:9]
	v_mfma_f32_16x16x32_bf16 v[2:5], v[54:57], v[232:235], v[2:5]
	v_mfma_f32_16x16x32_bf16 v[18:21], v[46:49], v[186:189], v[18:21]
	v_mfma_f32_16x16x32_bf16 v[22:25], v[54:57], v[186:189], v[22:25]
	v_mfma_f32_16x16x32_bf16 v[26:29], v[46:49], v[216:219], v[26:29]
	v_mfma_f32_16x16x32_bf16 v[30:33], v[54:57], v[216:219], v[30:33]
	s_setprio 0
	s_barrier
	s_add_i32 s52, 0, 0x18000
	s_add_i32 s53, 0, 0x1c000
	v_add_u32_e32 v54, s52, v193
	v_add_u32_e32 v66, s53, v193
	ds_read_b128 v[42:45], v54
	ds_read_b128 v[46:49], v54 offset:1024
	ds_read_b128 v[50:53], v54 offset:2048
	ds_read_b128 v[54:57], v54 offset:3072
	ds_read_b128 v[182:185], v66
	ds_read_b128 v[186:189], v66 offset:1024
	ds_read_b128 v[212:215], v66 offset:2048
	ds_read_b128 v[216:219], v66 offset:3072
	s_add_u32 s34, s34, 0x20000
	s_addc_u32 s35, s35, 0
	s_mov_b32 m0, s39
	v_lshl_add_u64 v[236:237], s[34:35], 0, v[162:163]
	ds_read_b128 v[66:69], v199 offset:32768
	global_load_lds_dwordx4 v[236:237], off
	ds_read_b128 v[70:73], v199 offset:33792
	ds_read_b128 v[82:85], v199 offset:34816
	ds_read_b128 v[86:89], v199 offset:35840
	v_lshl_add_u64 v[236:237], s[34:35], 0, v[164:165]
	s_mov_b32 m0, s44
	s_nop 0
	global_load_lds_dwordx4 v[236:237], off
	ds_read_b128 v[220:223], v199 offset:36864
	ds_read_b128 v[224:227], v199 offset:37888
	ds_read_b128 v[228:231], v199 offset:38912
	ds_read_b128 v[232:235], v199 offset:39936
	s_waitcnt vmcnt(8)
	s_waitcnt lgkmcnt(0)
	s_barrier
	s_setprio 1
	s_waitcnt lgkmcnt(0)
	v_mfma_f32_16x16x32_bf16 v[158:161], v[42:45], v[66:69], v[158:161]
	v_mfma_f32_16x16x32_bf16 v[154:157], v[50:53], v[66:69], v[154:157]
	v_mfma_f32_16x16x32_bf16 v[142:145], v[42:45], v[82:85], v[142:145]
	v_mfma_f32_16x16x32_bf16 v[138:141], v[50:53], v[82:85], v[138:141]
	v_mfma_f32_16x16x32_bf16 v[126:129], v[42:45], v[220:223], v[126:129]
	v_mfma_f32_16x16x32_bf16 v[122:125], v[50:53], v[220:223], v[122:125]
	v_mfma_f32_16x16x32_bf16 v[110:113], v[42:45], v[228:231], v[110:113]
	v_mfma_f32_16x16x32_bf16 v[106:109], v[50:53], v[228:231], v[106:109]
	v_mfma_f32_16x16x32_bf16 v[158:161], v[46:49], v[70:73], v[158:161]
	v_mfma_f32_16x16x32_bf16 v[154:157], v[54:57], v[70:73], v[154:157]
	v_mfma_f32_16x16x32_bf16 v[142:145], v[46:49], v[86:89], v[142:145]
	v_mfma_f32_16x16x32_bf16 v[138:141], v[54:57], v[86:89], v[138:141]
	v_mfma_f32_16x16x32_bf16 v[126:129], v[46:49], v[224:227], v[126:129]
	v_mfma_f32_16x16x32_bf16 v[122:125], v[54:57], v[224:227], v[122:125]
	v_mfma_f32_16x16x32_bf16 v[110:113], v[46:49], v[232:235], v[110:113]
	v_mfma_f32_16x16x32_bf16 v[106:109], v[54:57], v[232:235], v[106:109]
	s_setprio 0
	s_setprio 1
	v_mfma_f32_16x16x32_bf16 v[150:153], v[182:185], v[66:69], v[150:153]
	v_mfma_f32_16x16x32_bf16 v[66:69], v[212:215], v[66:69], v[146:149]
	v_mfma_f32_16x16x32_bf16 v[146:149], v[216:219], v[70:73], v[66:69]
	v_mfma_f32_16x16x32_bf16 v[66:69], v[182:185], v[82:85], v[134:137]
	v_mfma_f32_16x16x32_bf16 v[134:137], v[186:189], v[86:89], v[66:69]
	v_mfma_f32_16x16x32_bf16 v[66:69], v[212:215], v[82:85], v[130:133]
	v_mfma_f32_16x16x32_bf16 v[130:133], v[216:219], v[86:89], v[66:69]
	v_mfma_f32_16x16x32_bf16 v[66:69], v[182:185], v[220:223], v[118:121]
	v_mfma_f32_16x16x32_bf16 v[118:121], v[186:189], v[224:227], v[66:69]
	v_mfma_f32_16x16x32_bf16 v[66:69], v[212:215], v[220:223], v[114:117]
	v_mfma_f32_16x16x32_bf16 v[114:117], v[216:219], v[224:227], v[66:69]
	v_mfma_f32_16x16x32_bf16 v[66:69], v[182:185], v[228:231], v[102:105]
	v_mfma_f32_16x16x32_bf16 v[102:105], v[186:189], v[232:235], v[66:69]
	v_mfma_f32_16x16x32_bf16 v[66:69], v[212:215], v[228:231], v[98:101]
	v_mfma_f32_16x16x32_bf16 v[150:153], v[186:189], v[70:73], v[150:153]
	v_mfma_f32_16x16x32_bf16 v[98:101], v[216:219], v[232:235], v[66:69]
	s_setprio 0
	s_barrier
; #define PG8_STAGE(bufoff, gbase, voff) do { _Pragma("unroll") for (int _i = 0; _i < 2; ++_i) \
;         __builtin_amdgcn_global_load_lds((const unsigned*)((const char*)(gbase) + (voff)[_i]), (LAS unsigned*)(lds + (bufoff) + ldsw + _i * 8192), 16, 0, 0); } while (0)
; #define PG8_LDA(dst, b, h) do { _Pragma("unroll") for (int m = 0; m < 4; ++m) _Pragma("unroll") for (int k = 0; k < 2; ++k) dst[m][k] = *(const LAS bf16x8*)(lds + PG8_SA(b, h) + aoff + m * 2048 + k * 1024); } while (0)
; #define PG8_MMA(ai, bj, At, Bt) do { __builtin_amdgcn_s_setprio(1); _Pragma("unroll") for (int m = 0; m < 4; ++m) _Pragma("unroll") for (int n = 0; n < 2; ++n) _Pragma("unroll") for (int k = 0; k < 2; ++k) \
;         acc[ai][bj][m][n] = __builtin_amdgcn_mfma_f32_16x16x32_bf16(Bt[n][k], At[m][k], acc[ai][bj][m][n], 0, 0, 0); __builtin_amdgcn_s_setprio(0); } while (0)
; #define PG8_WAIT_V(n) asm volatile("s_waitcnt vmcnt(" #n ")" ::: "memory")
; #define PG8_WAIT_L(n) asm volatile("s_waitcnt lgkmcnt(" #n ")" ::: "memory")
; #define PG8_BAR __builtin_amdgcn_s_barrier()
; #define PG8_SCHED __builtin_amdgcn_sched_barrier(0)
; template <class Epi>
; __device__ __forceinline__ void gemm_phase(LAS unsigned char* lds, const Gemm g, const StaticOrder& S, const Epi& E, const int tid) {
;     ...
;             PG8_LDA(At, 1, 1); PG8_STAGE(PG8_SB(1, 0), b3, voffB); PG8_STAGE(PG8_SB(1, 1), b3 + bhs, voffB); PG8_STAGE(PG8_SA(1, 0), a3, voffA);
;             PG8_WAIT_V(8); PG8_WAIT_L(0); PG8_BAR; PG8_MMA(1, 0, At, B0); PG8_MMA(1, 1, At, B1); PG8_BAR; PG8_SCHED;
	s_add_i32 s34, s52, s36
	v_lshl_add_u64 v[82:83], v[172:173], 0, s[70:71]
	s_mov_b32 m0, s34
	s_nop 0
	ds_read_b128 v[66:69], v199 offset:49152
	global_load_lds_dwordx4 v[82:83], off
	ds_read_b128 v[70:73], v199 offset:50176
	ds_read_b128 v[220:223], v199 offset:51200
	ds_read_b128 v[224:227], v199 offset:52224
	s_add_i32 m0, s34, 0x2000
	s_add_u32 s30, s30, 0x2080
	v_lshl_add_u64 v[82:83], v[174:175], 0, s[70:71]
	s_addc_u32 s31, s31, 0
	s_add_i32 s34, s53, s36
	global_load_lds_dwordx4 v[82:83], off
	ds_read_b128 v[228:231], v199 offset:53248
	ds_read_b128 v[232:235], v199 offset:54272
	ds_read_b128 v[236:239], v199 offset:55296
	v_lshl_add_u64 v[82:83], s[30:31], 0, v[0:1]
	s_mov_b32 m0, s34
	s_nop 0
	global_load_lds_dwordx4 v[82:83], off
	ds_read_b128 v[240:243], v199 offset:56320
	v_lshl_add_u64 v[82:83], s[30:31], 0, v[166:167]
	s_add_i32 m0, s34, 0x2000
	s_nop 0
	global_load_lds_dwordx4 v[82:83], off
	v_lshl_add_u64 v[82:83], v[176:177], 0, s[70:71]
	s_mov_b32 m0, s45
	s_nop 0
	global_load_lds_dwordx4 v[82:83], off
	v_lshl_add_u64 v[82:83], v[200:201], 0, s[70:71]
	s_mov_b32 m0, s46
	s_nop 0
	global_load_lds_dwordx4 v[82:83], off
	s_waitcnt vmcnt(8)
	s_waitcnt lgkmcnt(0)
	s_barrier
	s_setprio 1
	s_waitcnt lgkmcnt(0)
	v_mfma_f32_16x16x32_bf16 v[82:85], v[42:45], v[66:69], v[94:97]
	v_mfma_f32_16x16x32_bf16 v[94:97], v[46:49], v[70:73], v[82:85]
	v_mfma_f32_16x16x32_bf16 v[82:85], v[50:53], v[66:69], v[90:93]
	v_mfma_f32_16x16x32_bf16 v[78:81], v[42:45], v[220:223], v[78:81]
	v_mfma_f32_16x16x32_bf16 v[74:77], v[50:53], v[220:223], v[74:77]
	v_mfma_f32_16x16x32_bf16 v[62:65], v[42:45], v[228:231], v[62:65]
	v_mfma_f32_16x16x32_bf16 v[58:61], v[50:53], v[228:231], v[58:61]
	v_mfma_f32_16x16x32_bf16 v[14:17], v[42:45], v[236:239], v[14:17]
	v_mfma_f32_16x16x32_bf16 v[10:13], v[50:53], v[236:239], v[10:13]
	v_mfma_f32_16x16x32_bf16 v[90:93], v[54:57], v[70:73], v[82:85]
	v_mfma_f32_16x16x32_bf16 v[78:81], v[46:49], v[224:227], v[78:81]
	v_mfma_f32_16x16x32_bf16 v[74:77], v[54:57], v[224:227], v[74:77]
	v_mfma_f32_16x16x32_bf16 v[62:65], v[46:49], v[232:235], v[62:65]
	v_mfma_f32_16x16x32_bf16 v[58:61], v[54:57], v[232:235], v[58:61]
	v_mfma_f32_16x16x32_bf16 v[14:17], v[46:49], v[240:243], v[14:17]
	v_mfma_f32_16x16x32_bf16 v[10:13], v[54:57], v[240:243], v[10:13]
	s_setprio 0
	s_setprio 1
	v_mfma_f32_16x16x32_bf16 v[18:21], v[182:185], v[66:69], v[18:21]
	v_mfma_f32_16x16x32_bf16 v[86:89], v[186:189], v[70:73], v[18:21]
	v_mfma_f32_16x16x32_bf16 v[18:21], v[212:215], v[66:69], v[22:25]
	v_mfma_f32_16x16x32_bf16 v[82:85], v[216:219], v[70:73], v[18:21]
	v_mfma_f32_16x16x32_bf16 v[18:21], v[182:185], v[220:223], v[26:29]
	v_mfma_f32_16x16x32_bf16 v[70:73], v[186:189], v[224:227], v[18:21]
	v_mfma_f32_16x16x32_bf16 v[18:21], v[212:215], v[220:223], v[30:33]
	v_mfma_f32_16x16x32_bf16 v[66:69], v[216:219], v[224:227], v[18:21]
	v_mfma_f32_16x16x32_bf16 v[18:21], v[182:185], v[228:231], v[38:41]
	v_mfma_f32_16x16x32_bf16 v[38:41], v[186:189], v[232:235], v[18:21]
	v_mfma_f32_16x16x32_bf16 v[18:21], v[212:215], v[228:231], v[34:37]
	v_mfma_f32_16x16x32_bf16 v[6:9], v[182:185], v[236:239], v[6:9]
	v_mfma_f32_16x16x32_bf16 v[2:5], v[212:215], v[236:239], v[2:5]
	v_mfma_f32_16x16x32_bf16 v[34:37], v[216:219], v[232:235], v[18:21]
	v_mfma_f32_16x16x32_bf16 v[6:9], v[186:189], v[240:243], v[6:9]
	v_mfma_f32_16x16x32_bf16 v[2:5], v[216:219], v[240:243], v[2:5]
	s_setprio 0
	s_barrier
	s_add_i32 s51, s51, 2
	s_add_u32 s49, s49, 0x100
	s_addc_u32 s50, s50, 0
	s_add_u32 s28, s28, 0x100
	s_addc_u32 s29, s29, 0
	s_cmp_gt_u32 s51, 5
	s_cbranch_scc0 .LBB0_206
	s_and_b64 vcc, exec, s[12:13]
	s_cbranch_vccz .LBB0_209
	s_barrier

; #define PG8_STAGE(bufoff, gbase, voff) do { _Pragma("unroll") for (int _i = 0; _i < 2; ++_i) \
;         __builtin_amdgcn_global_load_lds((const unsigned*)((const char*)(gbase) + (voff)[_i]), (LAS unsigned*)(lds + (bufoff) + ldsw + _i * 8192), 16, 0, 0); } while (0)
; #define PG8_LDA(dst, b, h) do { _Pragma("unroll") for (int m = 0; m < 4; ++m) _Pragma("unroll") for (int k = 0; k < 2; ++k) dst[m][k] = *(const LAS bf16x8*)(lds + PG8_SA(b, h) + aoff + m * 2048 + k * 1024); } while (0)
; #define PG8_LDB(dst, b, h) do { _Pragma("unroll") for (int n = 0; n < 2; ++n) _Pragma("unroll") for (int k = 0; k < 2; ++k) dst[n][k] = *(const LAS bf16x8*)(lds + PG8_SB(b, h) + boff + n * 2048 + k * 1024); } while (0)
; #define PG8_MMA(ai, bj, At, Bt) do { __builtin_amdgcn_s_setprio(1); _Pragma("unroll") for (int m = 0; m < 4; ++m) _Pragma("unroll") for (int n = 0; n < 2; ++n) _Pragma("unroll") for (int k = 0; k < 2; ++k) \
;         acc[ai][bj][m][n] = __builtin_amdgcn_mfma_f32_16x16x32_bf16(Bt[n][k], At[m][k], acc[ai][bj][m][n], 0, 0, 0); __builtin_amdgcn_s_setprio(0); } while (0)
; #define PG8_WAIT_V(n) asm volatile("s_waitcnt vmcnt(" #n ")" ::: "memory")
; #define PG8_WAIT_L(n) asm volatile("s_waitcnt lgkmcnt(" #n ")" ::: "memory")
; #define PG8_BAR __builtin_amdgcn_s_barrier()
; #define PG8_SCHED __builtin_amdgcn_sched_barrier(0)
; template <class Epi>
; __device__ __forceinline__ void gemm_phase(LAS unsigned char* lds, const Gemm g, const StaticOrder& S, const Epi& E, const int tid) {
;     ...
;             PG8_LDB(B0, 0, 0); PG8_LDB(B1, 0, 1); PG8_SCHED; PG8_LDA(At, 0, 0); PG8_STAGE(PG8_SA(1, 1), a1 + hstep, voffA);
;             PG8_WAIT_V(8); PG8_WAIT_L(0); PG8_BAR; PG8_MMA(0, 0, At, B0); PG8_MMA(0, 1, At, B1); PG8_BAR; PG8_SCHED;
;             PG8_LDA(At, 0, 1); PG8_STAGE(PG8_SB(0, 0), b2, voffB); PG8_STAGE(PG8_SB(0, 1), b2 + bhs, voffB); PG8_STAGE(PG8_SA(0, 0), a2, voffA);
;             PG8_WAIT_V(8); PG8_WAIT_L(0); PG8_BAR; PG8_MMA(1, 0, At, B0); PG8_MMA(1, 1, At, B1); PG8_BAR; PG8_SCHED;
.LBB0_261:
	s_add_u32 s30, s28, 0xfff80080
	s_addc_u32 s31, s29, -1
	s_add_i32 s49, 0, 0x10000
	s_cmp_eq_u32 s48, 28
	s_cselect_b32 s35, s19, s31
	s_cselect_b32 s34, s44, s30
	v_add_u32_e32 v142, s49, v149
	s_cselect_b32 s31, s17, s47
	s_cselect_b32 s30, s45, s46
	s_add_i32 s52, 0, 0x14000
	ds_read_b128 v[156:159], v142
	ds_read_b128 v[160:163], v142 offset:1024
	ds_read_b128 v[164:167], v142 offset:2048
	ds_read_b128 v[178:181], v142 offset:3072
	v_add_u32_e32 v142, s52, v149
	ds_read_b128 v[182:185], v142
	ds_read_b128 v[186:189], v142 offset:1024
	ds_read_b128 v[190:193], v142 offset:2048
	ds_read_b128 v[194:197], v142 offset:3072
	v_lshl_add_u64 v[142:143], s[28:29], 0, v[140:141]
	s_add_i32 m0, s2, 0xc000
	ds_read_b128 v[198:201], v154
	global_load_lds_dwordx4 v[142:143], off
	ds_read_b128 v[212:215], v154 offset:1024
	ds_read_b128 v[216:219], v154 offset:2048
	ds_read_b128 v[220:223], v154 offset:3072
	v_lshl_add_u64 v[142:143], s[28:29], 0, v[138:139]
	s_add_i32 m0, s2, 0xe000
	s_nop 0
	global_load_lds_dwordx4 v[142:143], off
	ds_read_b128 v[224:227], v154 offset:4096
	ds_read_b128 v[228:231], v154 offset:5120
	ds_read_b128 v[232:235], v154 offset:6144
	ds_read_b128 v[236:239], v154 offset:7168
	s_waitcnt vmcnt(8)
	s_waitcnt lgkmcnt(0)
	s_barrier
	s_setprio 1
	s_waitcnt lgkmcnt(0)
	v_mfma_f32_16x16x32_bf16 v[126:129], v[156:159], v[198:201], v[126:129]
	v_mfma_f32_16x16x32_bf16 v[122:125], v[164:167], v[198:201], v[122:125]
	v_mfma_f32_16x16x32_bf16 v[110:113], v[156:159], v[216:219], v[110:113]
	v_mfma_f32_16x16x32_bf16 v[106:109], v[164:167], v[216:219], v[106:109]
	v_mfma_f32_16x16x32_bf16 v[94:97], v[156:159], v[224:227], v[94:97]
	v_mfma_f32_16x16x32_bf16 v[90:93], v[164:167], v[224:227], v[90:93]
	v_mfma_f32_16x16x32_bf16 v[78:81], v[156:159], v[232:235], v[78:81]
	v_mfma_f32_16x16x32_bf16 v[74:77], v[164:167], v[232:235], v[74:77]
	v_mfma_f32_16x16x32_bf16 v[126:129], v[160:163], v[212:215], v[126:129]
	v_mfma_f32_16x16x32_bf16 v[122:125], v[178:181], v[212:215], v[122:125]
	v_mfma_f32_16x16x32_bf16 v[110:113], v[160:163], v[220:223], v[110:113]
	v_mfma_f32_16x16x32_bf16 v[106:109], v[178:181], v[220:223], v[106:109]
	v_mfma_f32_16x16x32_bf16 v[94:97], v[160:163], v[228:231], v[94:97]
	v_mfma_f32_16x16x32_bf16 v[90:93], v[178:181], v[228:231], v[90:93]
	v_mfma_f32_16x16x32_bf16 v[78:81], v[160:163], v[236:239], v[78:81]
	v_mfma_f32_16x16x32_bf16 v[74:77], v[178:181], v[236:239], v[74:77]
	s_setprio 0
	s_setprio 1
	v_mfma_f32_16x16x32_bf16 v[118:121], v[182:185], v[198:201], v[118:121]
	v_mfma_f32_16x16x32_bf16 v[114:117], v[190:193], v[198:201], v[114:117]
	v_mfma_f32_16x16x32_bf16 v[102:105], v[182:185], v[216:219], v[102:105]
	v_mfma_f32_16x16x32_bf16 v[98:101], v[190:193], v[216:219], v[98:101]
	v_mfma_f32_16x16x32_bf16 v[86:89], v[182:185], v[224:227], v[86:89]
	v_mfma_f32_16x16x32_bf16 v[82:85], v[190:193], v[224:227], v[82:85]
	v_mfma_f32_16x16x32_bf16 v[70:73], v[182:185], v[232:235], v[70:73]
	v_mfma_f32_16x16x32_bf16 v[66:69], v[190:193], v[232:235], v[66:69]
	v_mfma_f32_16x16x32_bf16 v[118:121], v[186:189], v[212:215], v[118:121]
	v_mfma_f32_16x16x32_bf16 v[114:117], v[194:197], v[212:215], v[114:117]
	v_mfma_f32_16x16x32_bf16 v[102:105], v[186:189], v[220:223], v[102:105]
	v_mfma_f32_16x16x32_bf16 v[98:101], v[194:197], v[220:223], v[98:101]
	v_mfma_f32_16x16x32_bf16 v[86:89], v[186:189], v[228:231], v[86:89]
	v_mfma_f32_16x16x32_bf16 v[82:85], v[194:197], v[228:231], v[82:85]
	v_mfma_f32_16x16x32_bf16 v[70:73], v[186:189], v[236:239], v[70:73]
	v_mfma_f32_16x16x32_bf16 v[66:69], v[194:197], v[236:239], v[66:69]
	s_setprio 0
	s_barrier
	s_add_i32 s49, s49, s36
	v_lshl_add_u64 v[142:143], s[30:31], 0, v[0:1]
	s_mov_b32 m0, s49
	ds_read_b128 v[198:201], v154 offset:16384
	global_load_lds_dwordx4 v[142:143], off
	ds_read_b128 v[212:215], v154 offset:17408
	ds_read_b128 v[216:219], v154 offset:18432
	ds_read_b128 v[220:223], v154 offset:19456
	s_add_i32 m0, s49, 0x2000
	s_add_u32 s50, s30, 0x8000
	v_lshl_add_u64 v[168:169], s[30:31], 0, v[134:135]
	s_addc_u32 s51, s31, 0
	s_add_i32 s49, s52, s36
	global_load_lds_dwordx4 v[168:169], off
	ds_read_b128 v[224:227], v154 offset:20480
	ds_read_b128 v[228:231], v154 offset:21504
	ds_read_b128 v[232:235], v154 offset:22528
	v_lshl_add_u64 v[172:173], s[50:51], 0, v[0:1]
	s_mov_b32 m0, s49
	v_lshl_add_u64 v[174:175], s[34:35], 0, v[132:133]
	global_load_lds_dwordx4 v[172:173], off
	ds_read_b128 v[236:239], v154 offset:23552
	v_lshl_add_u64 v[172:173], s[50:51], 0, v[134:135]
	s_add_i32 m0, s49, 0x2000
	s_nop 0
	global_load_lds_dwordx4 v[172:173], off
	v_lshl_add_u64 v[172:173], s[34:35], 0, v[130:131]
	s_mov_b32 m0, s2
	s_nop 0
	global_load_lds_dwordx4 v[172:173], off
	s_mov_b32 m0, s27
	s_nop 0
	global_load_lds_dwordx4 v[174:175], off
	s_waitcnt vmcnt(8)
	s_waitcnt lgkmcnt(0)
	s_barrier
; #define PG8_STAGE(bufoff, gbase, voff) do { _Pragma("unroll") for (int _i = 0; _i < 2; ++_i) \
;         __builtin_amdgcn_global_load_lds((const unsigned*)((const char*)(gbase) + (voff)[_i]), (LAS unsigned*)(lds + (bufoff) + ldsw + _i * 8192), 16, 0, 0); } while (0)
; #define PG8_LDA(dst, b, h) do { _Pragma("unroll") for (int m = 0; m < 4; ++m) _Pragma("unroll") for (int k = 0; k < 2; ++k) dst[m][k] = *(const LAS bf16x8*)(lds + PG8_SA(b, h) + aoff + m * 2048 + k * 1024); } while (0)
; #define PG8_LDB(dst, b, h) do { _Pragma("unroll") for (int n = 0; n < 2; ++n) _Pragma("unroll") for (int k = 0; k < 2; ++k) dst[n][k] = *(const LAS bf16x8*)(lds + PG8_SB(b, h) + boff + n * 2048 + k * 1024); } while (0)
; #define PG8_MMA(ai, bj, At, Bt) do { __builtin_amdgcn_s_setprio(1); _Pragma("unroll") for (int m = 0; m < 4; ++m) _Pragma("unroll") for (int n = 0; n < 2; ++n) _Pragma("unroll") for (int k = 0; k < 2; ++k) \
;         acc[ai][bj][m][n] = __builtin_amdgcn_mfma_f32_16x16x32_bf16(Bt[n][k], At[m][k], acc[ai][bj][m][n], 0, 0, 0); __builtin_amdgcn_s_setprio(0); } while (0)
; #define PG8_WAIT_V(n) asm volatile("s_waitcnt vmcnt(" #n ")" ::: "memory")
; #define PG8_WAIT_L(n) asm volatile("s_waitcnt lgkmcnt(" #n ")" ::: "memory")
; #define PG8_BAR __builtin_amdgcn_s_barrier()
; #define PG8_SCHED __builtin_amdgcn_sched_barrier(0)
; template <class Epi>
; __device__ __forceinline__ void gemm_phase(LAS unsigned char* lds, const Gemm g, const StaticOrder& S, const Epi& E, const int tid) {
;     ...
;             PG8_WAIT_V(8); PG8_WAIT_L(0); PG8_BAR; PG8_MMA(1, 0, At, B0); PG8_MMA(1, 1, At, B1); PG8_BAR; PG8_SCHED;
;             PG8_LDB(B0, 1, 0); PG8_LDB(B1, 1, 1); PG8_SCHED; PG8_LDA(At, 1, 0); PG8_STAGE(PG8_SA(0, 1), a2 + hstep, voffA);
;             PG8_WAIT_V(8); PG8_WAIT_L(0); PG8_BAR; PG8_MMA(0, 0, At, B0); PG8_MMA(0, 1, At, B1); PG8_BAR; PG8_SCHED;
	s_setprio 1
	s_waitcnt lgkmcnt(0)
	v_mfma_f32_16x16x32_bf16 v[62:65], v[156:159], v[198:201], v[62:65]
	v_mfma_f32_16x16x32_bf16 v[58:61], v[164:167], v[198:201], v[58:61]
	v_mfma_f32_16x16x32_bf16 v[46:49], v[156:159], v[216:219], v[46:49]
	v_mfma_f32_16x16x32_bf16 v[42:45], v[164:167], v[216:219], v[42:45]
	v_mfma_f32_16x16x32_bf16 v[30:33], v[156:159], v[224:227], v[30:33]
	v_mfma_f32_16x16x32_bf16 v[26:29], v[164:167], v[224:227], v[26:29]
	v_mfma_f32_16x16x32_bf16 v[14:17], v[156:159], v[232:235], v[14:17]
	v_mfma_f32_16x16x32_bf16 v[10:13], v[164:167], v[232:235], v[10:13]
	v_mfma_f32_16x16x32_bf16 v[62:65], v[160:163], v[212:215], v[62:65]
	v_mfma_f32_16x16x32_bf16 v[58:61], v[178:181], v[212:215], v[58:61]
	v_mfma_f32_16x16x32_bf16 v[46:49], v[160:163], v[220:223], v[46:49]
	v_mfma_f32_16x16x32_bf16 v[42:45], v[178:181], v[220:223], v[42:45]
	v_mfma_f32_16x16x32_bf16 v[30:33], v[160:163], v[228:231], v[30:33]
	v_mfma_f32_16x16x32_bf16 v[26:29], v[178:181], v[228:231], v[26:29]
	v_mfma_f32_16x16x32_bf16 v[14:17], v[160:163], v[236:239], v[14:17]
	v_mfma_f32_16x16x32_bf16 v[10:13], v[178:181], v[236:239], v[10:13]
	s_setprio 0
	s_setprio 1
	v_mfma_f32_16x16x32_bf16 v[54:57], v[182:185], v[198:201], v[54:57]
	v_mfma_f32_16x16x32_bf16 v[50:53], v[190:193], v[198:201], v[50:53]
	v_mfma_f32_16x16x32_bf16 v[38:41], v[182:185], v[216:219], v[38:41]
	v_mfma_f32_16x16x32_bf16 v[34:37], v[190:193], v[216:219], v[34:37]
	v_mfma_f32_16x16x32_bf16 v[22:25], v[182:185], v[224:227], v[22:25]
	v_mfma_f32_16x16x32_bf16 v[18:21], v[190:193], v[224:227], v[18:21]
	v_mfma_f32_16x16x32_bf16 v[6:9], v[182:185], v[232:235], v[6:9]
	v_mfma_f32_16x16x32_bf16 v[2:5], v[190:193], v[232:235], v[2:5]
	v_mfma_f32_16x16x32_bf16 v[54:57], v[186:189], v[212:215], v[54:57]
	v_mfma_f32_16x16x32_bf16 v[50:53], v[194:197], v[212:215], v[50:53]
	v_mfma_f32_16x16x32_bf16 v[38:41], v[186:189], v[220:223], v[38:41]
	v_mfma_f32_16x16x32_bf16 v[34:37], v[194:197], v[220:223], v[34:37]
	v_mfma_f32_16x16x32_bf16 v[22:25], v[186:189], v[228:231], v[22:25]
	v_mfma_f32_16x16x32_bf16 v[18:21], v[194:197], v[228:231], v[18:21]
	v_mfma_f32_16x16x32_bf16 v[6:9], v[186:189], v[236:239], v[6:9]
	v_mfma_f32_16x16x32_bf16 v[2:5], v[194:197], v[236:239], v[2:5]
	s_setprio 0
	s_barrier
	s_add_i32 s49, 0, 0x18000
	v_add_u32_e32 v155, s49, v149
	s_add_i32 s50, 0, 0x1c000
	ds_read_b128 v[156:159], v155
	ds_read_b128 v[160:163], v155 offset:1024
	ds_read_b128 v[164:167], v155 offset:2048
	ds_read_b128 v[178:181], v155 offset:3072
	v_add_u32_e32 v155, s50, v149
	ds_read_b128 v[182:185], v155
	ds_read_b128 v[186:189], v155 offset:1024
	ds_read_b128 v[190:193], v155 offset:2048
	ds_read_b128 v[194:197], v155 offset:3072
	s_add_u32 s34, s34, 0x80000
	s_addc_u32 s35, s35, 0
	s_mov_b32 m0, s37
	v_lshl_add_u64 v[176:177], s[34:35], 0, v[130:131]
	ds_read_b128 v[198:201], v154 offset:32768
	global_load_lds_dwordx4 v[176:177], off
	ds_read_b128 v[212:215], v154 offset:33792
	ds_read_b128 v[216:219], v154 offset:34816
	ds_read_b128 v[220:223], v154 offset:35840
	v_lshl_add_u64 v[176:177], s[34:35], 0, v[132:133]
	s_mov_b32 m0, s38
	s_nop 0
	global_load_lds_dwordx4 v[176:177], off
	ds_read_b128 v[224:227], v154 offset:36864
	ds_read_b128 v[228:231], v154 offset:37888
	ds_read_b128 v[232:235], v154 offset:38912
	ds_read_b128 v[236:239], v154 offset:39936
	s_waitcnt vmcnt(8)
	s_waitcnt lgkmcnt(0)
	s_barrier
	s_setprio 1
	s_waitcnt lgkmcnt(0)
	v_mfma_f32_16x16x32_bf16 v[126:129], v[156:159], v[198:201], v[126:129]
	v_mfma_f32_16x16x32_bf16 v[122:125], v[164:167], v[198:201], v[122:125]
	v_mfma_f32_16x16x32_bf16 v[110:113], v[156:159], v[216:219], v[110:113]
	v_mfma_f32_16x16x32_bf16 v[106:109], v[164:167], v[216:219], v[106:109]
	v_mfma_f32_16x16x32_bf16 v[94:97], v[156:159], v[224:227], v[94:97]
	v_mfma_f32_16x16x32_bf16 v[90:93], v[164:167], v[224:227], v[90:93]
	v_mfma_f32_16x16x32_bf16 v[78:81], v[156:159], v[232:235], v[78:81]
	v_mfma_f32_16x16x32_bf16 v[74:77], v[164:167], v[232:235], v[74:77]
	v_mfma_f32_16x16x32_bf16 v[126:129], v[160:163], v[212:215], v[126:129]
	v_mfma_f32_16x16x32_bf16 v[122:125], v[178:181], v[212:215], v[122:125]
	v_mfma_f32_16x16x32_bf16 v[110:113], v[160:163], v[220:223], v[110:113]
	v_mfma_f32_16x16x32_bf16 v[106:109], v[178:181], v[220:223], v[106:109]
	v_mfma_f32_16x16x32_bf16 v[94:97], v[160:163], v[228:231], v[94:97]
	v_mfma_f32_16x16x32_bf16 v[90:93], v[178:181], v[228:231], v[90:93]
	v_mfma_f32_16x16x32_bf16 v[78:81], v[160:163], v[236:239], v[78:81]
	v_mfma_f32_16x16x32_bf16 v[74:77], v[178:181], v[236:239], v[74:77]
	s_setprio 0
	s_setprio 1
	v_mfma_f32_16x16x32_bf16 v[118:121], v[182:185], v[198:201], v[118:121]
	v_mfma_f32_16x16x32_bf16 v[114:117], v[190:193], v[198:201], v[114:117]
	v_mfma_f32_16x16x32_bf16 v[102:105], v[182:185], v[216:219], v[102:105]
	v_mfma_f32_16x16x32_bf16 v[98:101], v[190:193], v[216:219], v[98:101]
	v_mfma_f32_16x16x32_bf16 v[86:89], v[182:185], v[224:227], v[86:89]
	v_mfma_f32_16x16x32_bf16 v[82:85], v[190:193], v[224:227], v[82:85]
	v_mfma_f32_16x16x32_bf16 v[70:73], v[182:185], v[232:235], v[70:73]
	v_mfma_f32_16x16x32_bf16 v[66:69], v[190:193], v[232:235], v[66:69]
	v_mfma_f32_16x16x32_bf16 v[118:121], v[186:189], v[212:215], v[118:121]
	v_mfma_f32_16x16x32_bf16 v[114:117], v[194:197], v[212:215], v[114:117]
	v_mfma_f32_16x16x32_bf16 v[102:105], v[186:189], v[220:223], v[102:105]
	v_mfma_f32_16x16x32_bf16 v[98:101], v[194:197], v[220:223], v[98:101]
	v_mfma_f32_16x16x32_bf16 v[86:89], v[186:189], v[228:231], v[86:89]
	v_mfma_f32_16x16x32_bf16 v[82:85], v[194:197], v[228:231], v[82:85]
	v_mfma_f32_16x16x32_bf16 v[70:73], v[186:189], v[236:239], v[70:73]
	v_mfma_f32_16x16x32_bf16 v[66:69], v[194:197], v[236:239], v[66:69]
	s_setprio 0
	s_barrier
; #define PG8_STAGE(bufoff, gbase, voff) do { _Pragma("unroll") for (int _i = 0; _i < 2; ++_i) \
;         __builtin_amdgcn_global_load_lds((const unsigned*)((const char*)(gbase) + (voff)[_i]), (LAS unsigned*)(lds + (bufoff) + ldsw + _i * 8192), 16, 0, 0); } while (0)
; #define PG8_LDA(dst, b, h) do { _Pragma("unroll") for (int m = 0; m < 4; ++m) _Pragma("unroll") for (int k = 0; k < 2; ++k) dst[m][k] = *(const LAS bf16x8*)(lds + PG8_SA(b, h) + aoff + m * 2048 + k * 1024); } while (0)
; #define PG8_MMA(ai, bj, At, Bt) do { __builtin_amdgcn_s_setprio(1); _Pragma("unroll") for (int m = 0; m < 4; ++m) _Pragma("unroll") for (int n = 0; n < 2; ++n) _Pragma("unroll") for (int k = 0; k < 2; ++k) \
;         acc[ai][bj][m][n] = __builtin_amdgcn_mfma_f32_16x16x32_bf16(Bt[n][k], At[m][k], acc[ai][bj][m][n], 0, 0, 0); __builtin_amdgcn_s_setprio(0); } while (0)
; #define PG8_WAIT_V(n) asm volatile("s_waitcnt vmcnt(" #n ")" ::: "memory")
; #define PG8_WAIT_L(n) asm volatile("s_waitcnt lgkmcnt(" #n ")" ::: "memory")
; #define PG8_BAR __builtin_amdgcn_s_barrier()
; #define PG8_SCHED __builtin_amdgcn_sched_barrier(0)
; template <class Epi>
; __device__ __forceinline__ void gemm_phase(LAS unsigned char* lds, const Gemm g, const StaticOrder& S, const Epi& E, const int tid) {
;     ...
;             PG8_LDA(At, 1, 1); PG8_STAGE(PG8_SB(1, 0), b3, voffB); PG8_STAGE(PG8_SB(1, 1), b3 + bhs, voffB); PG8_STAGE(PG8_SA(1, 0), a3, voffA);
;             PG8_WAIT_V(8); PG8_WAIT_L(0); PG8_BAR; PG8_MMA(1, 0, At, B0); PG8_MMA(1, 1, At, B1); PG8_BAR; PG8_SCHED;
	s_add_i32 s34, s49, s36
	v_lshl_add_u64 v[142:143], v[142:143], 0, s[70:71]
	s_mov_b32 m0, s34
	ds_read_b128 v[198:201], v154 offset:49152
	global_load_lds_dwordx4 v[142:143], off
	ds_read_b128 v[212:215], v154 offset:50176
	ds_read_b128 v[216:219], v154 offset:51200
	ds_read_b128 v[220:223], v154 offset:52224
	s_add_i32 m0, s34, 0x2000
	s_add_u32 s30, s30, 0x8080
	v_lshl_add_u64 v[142:143], v[168:169], 0, s[70:71]
	s_addc_u32 s31, s31, 0
	s_add_i32 s34, s50, s36
	global_load_lds_dwordx4 v[142:143], off
	ds_read_b128 v[224:227], v154 offset:53248
	ds_read_b128 v[228:231], v154 offset:54272
	ds_read_b128 v[232:235], v154 offset:55296
	v_lshl_add_u64 v[142:143], s[30:31], 0, v[0:1]
	s_mov_b32 m0, s34
	s_nop 0
	global_load_lds_dwordx4 v[142:143], off
	ds_read_b128 v[236:239], v154 offset:56320
	v_lshl_add_u64 v[142:143], s[30:31], 0, v[134:135]
	s_add_i32 m0, s34, 0x2000
	s_nop 0
	global_load_lds_dwordx4 v[142:143], off
	v_lshl_add_u64 v[142:143], v[172:173], 0, s[70:71]
	s_mov_b32 m0, s39
	s_nop 0
	global_load_lds_dwordx4 v[142:143], off
	v_lshl_add_u64 v[142:143], v[174:175], 0, s[70:71]
	s_mov_b32 m0, s40
	s_nop 0
	global_load_lds_dwordx4 v[142:143], off
	s_waitcnt vmcnt(8)
	s_waitcnt lgkmcnt(0)
	s_barrier
	s_setprio 1
	s_waitcnt lgkmcnt(0)
	v_mfma_f32_16x16x32_bf16 v[62:65], v[156:159], v[198:201], v[62:65]
	v_mfma_f32_16x16x32_bf16 v[58:61], v[164:167], v[198:201], v[58:61]
	v_mfma_f32_16x16x32_bf16 v[46:49], v[156:159], v[216:219], v[46:49]
	v_mfma_f32_16x16x32_bf16 v[42:45], v[164:167], v[216:219], v[42:45]
	v_mfma_f32_16x16x32_bf16 v[30:33], v[156:159], v[224:227], v[30:33]
	v_mfma_f32_16x16x32_bf16 v[26:29], v[164:167], v[224:227], v[26:29]
	v_mfma_f32_16x16x32_bf16 v[14:17], v[156:159], v[232:235], v[14:17]
	v_mfma_f32_16x16x32_bf16 v[10:13], v[164:167], v[232:235], v[10:13]
	v_mfma_f32_16x16x32_bf16 v[62:65], v[160:163], v[212:215], v[62:65]
	v_mfma_f32_16x16x32_bf16 v[58:61], v[178:181], v[212:215], v[58:61]
	v_mfma_f32_16x16x32_bf16 v[46:49], v[160:163], v[220:223], v[46:49]
	v_mfma_f32_16x16x32_bf16 v[42:45], v[178:181], v[220:223], v[42:45]
	v_mfma_f32_16x16x32_bf16 v[30:33], v[160:163], v[228:231], v[30:33]
	v_mfma_f32_16x16x32_bf16 v[26:29], v[178:181], v[228:231], v[26:29]
	v_mfma_f32_16x16x32_bf16 v[14:17], v[160:163], v[236:239], v[14:17]
	v_mfma_f32_16x16x32_bf16 v[10:13], v[178:181], v[236:239], v[10:13]
	s_setprio 0
	s_setprio 1
	v_mfma_f32_16x16x32_bf16 v[54:57], v[182:185], v[198:201], v[54:57]
	v_mfma_f32_16x16x32_bf16 v[50:53], v[190:193], v[198:201], v[50:53]
	v_mfma_f32_16x16x32_bf16 v[38:41], v[182:185], v[216:219], v[38:41]
	v_mfma_f32_16x16x32_bf16 v[34:37], v[190:193], v[216:219], v[34:37]
	v_mfma_f32_16x16x32_bf16 v[22:25], v[182:185], v[224:227], v[22:25]
	v_mfma_f32_16x16x32_bf16 v[18:21], v[190:193], v[224:227], v[18:21]
	v_mfma_f32_16x16x32_bf16 v[6:9], v[182:185], v[232:235], v[6:9]
	v_mfma_f32_16x16x32_bf16 v[2:5], v[190:193], v[232:235], v[2:5]
	v_mfma_f32_16x16x32_bf16 v[54:57], v[186:189], v[212:215], v[54:57]
	v_mfma_f32_16x16x32_bf16 v[50:53], v[194:197], v[212:215], v[50:53]
	v_mfma_f32_16x16x32_bf16 v[38:41], v[186:189], v[220:223], v[38:41]
	v_mfma_f32_16x16x32_bf16 v[34:37], v[194:197], v[220:223], v[34:37]
	v_mfma_f32_16x16x32_bf16 v[22:25], v[186:189], v[228:231], v[22:25]
	v_mfma_f32_16x16x32_bf16 v[18:21], v[194:197], v[228:231], v[18:21]
	v_mfma_f32_16x16x32_bf16 v[6:9], v[186:189], v[236:239], v[6:9]
	v_mfma_f32_16x16x32_bf16 v[2:5], v[194:197], v[236:239], v[2:5]
	s_setprio 0
	s_barrier
	s_add_i32 s48, s48, 2
	s_add_u32 s46, s46, 0x100
	s_addc_u32 s47, s47, 0
	s_add_u32 s28, s28, 0x100
	s_addc_u32 s29, s29, 0
	s_cmp_gt_u32 s48, 29
	s_cbranch_scc0 .LBB0_261
	s_and_b64 vcc, exec, s[14:15]
	s_cbranch_vccz .LBB0_264
	s_barrier

; #define PG8_STAGE(bufoff, gbase, voff) do { _Pragma("unroll") for (int _i = 0; _i < 2; ++_i) \
;         __builtin_amdgcn_global_load_lds((const unsigned*)((const char*)(gbase) + (voff)[_i]), (LAS unsigned*)(lds + (bufoff) + ldsw + _i * 8192), 16, 0, 0); } while (0)
; #define PG8_LDA(dst, b, h) do { _Pragma("unroll") for (int m = 0; m < 4; ++m) _Pragma("unroll") for (int k = 0; k < 2; ++k) dst[m][k] = *(const LAS bf16x8*)(lds + PG8_SA(b, h) + aoff + m * 2048 + k * 1024); } while (0)
; #define PG8_LDB(dst, b, h) do { _Pragma("unroll") for (int n = 0; n < 2; ++n) _Pragma("unroll") for (int k = 0; k < 2; ++k) dst[n][k] = *(const LAS bf16x8*)(lds + PG8_SB(b, h) + boff + n * 2048 + k * 1024); } while (0)
; #define PG8_MMA(ai, bj, At, Bt) do { __builtin_amdgcn_s_setprio(1); _Pragma("unroll") for (int m = 0; m < 4; ++m) _Pragma("unroll") for (int n = 0; n < 2; ++n) _Pragma("unroll") for (int k = 0; k < 2; ++k) \
;         acc[ai][bj][m][n] = __builtin_amdgcn_mfma_f32_16x16x32_bf16(Bt[n][k], At[m][k], acc[ai][bj][m][n], 0, 0, 0); __builtin_amdgcn_s_setprio(0); } while (0)
; #define PG8_WAIT_V(n) asm volatile("s_waitcnt vmcnt(" #n ")" ::: "memory")
; #define PG8_WAIT_L(n) asm volatile("s_waitcnt lgkmcnt(" #n ")" ::: "memory")
; #define PG8_BAR __builtin_amdgcn_s_barrier()
; #define PG8_SCHED __builtin_amdgcn_sched_barrier(0)
; template <class Epi>
; __device__ __forceinline__ void gemm_phase(LAS unsigned char* lds, const Gemm g, const StaticOrder& S, const Epi& E, const int tid) {
;     ...
;             PG8_LDB(B0, 0, 0); PG8_LDB(B1, 0, 1); PG8_SCHED; PG8_LDA(At, 0, 0); PG8_STAGE(PG8_SA(1, 1), a1 + hstep, voffA);
;             PG8_WAIT_V(8); PG8_WAIT_L(0); PG8_BAR; PG8_MMA(0, 0, At, B0); PG8_MMA(0, 1, At, B1); PG8_BAR; PG8_SCHED;
;             PG8_LDA(At, 0, 1); PG8_STAGE(PG8_SB(0, 0), b2, voffB); PG8_STAGE(PG8_SB(0, 1), b2 + bhs, voffB); PG8_STAGE(PG8_SA(0, 0), a2, voffA);
;             PG8_WAIT_V(8); PG8_WAIT_L(0); PG8_BAR; PG8_MMA(1, 0, At, B0); PG8_MMA(1, 1, At, B1); PG8_BAR; PG8_SCHED;
.LBB0_314:
	s_add_u32 s40, s6, 0xfff80080
	s_addc_u32 s41, s7, -1
	s_add_i32 s56, 0, 0x10000
	s_cmp_eq_u32 s55, 28
	s_cselect_b32 s43, s27, s41
	s_cselect_b32 s42, s39, s40
	s_cselect_b32 s41, s25, s54
	s_cselect_b32 s40, s52, s53
	s_add_i32 s58, 0, 0x14000
	v_add_u32_e32 v46, s56, v212
	v_add_u32_e32 v70, s58, v212
	ds_read_b128 v[34:37], v46
	ds_read_b128 v[38:41], v46 offset:1024
	ds_read_b128 v[42:45], v46 offset:2048
	ds_read_b128 v[46:49], v46 offset:3072
	ds_read_b128 v[58:61], v70
	ds_read_b128 v[62:65], v70 offset:1024
	ds_read_b128 v[66:69], v70 offset:2048
	ds_read_b128 v[70:73], v70 offset:3072
	v_lshl_add_u64 v[172:173], s[6:7], 0, v[188:189]
	s_add_i32 m0, s44, 0xc000
	ds_read_b128 v[162:165], v220
	global_load_lds_dwordx4 v[172:173], off
	ds_read_b128 v[166:169], v220 offset:1024
	ds_read_b128 v[190:193], v220 offset:2048
	ds_read_b128 v[194:197], v220 offset:3072
	v_lshl_add_u64 v[172:173], s[6:7], 0, v[186:187]
	s_add_i32 m0, s44, 0xe000
	s_nop 0
	global_load_lds_dwordx4 v[172:173], off
	ds_read_b128 v[198:201], v220 offset:4096
	ds_read_b128 v[222:225], v220 offset:5120
	ds_read_b128 v[226:229], v220 offset:6144
	ds_read_b128 v[230:233], v220 offset:7168
	s_waitcnt vmcnt(8)
	s_waitcnt lgkmcnt(0)
	s_barrier
	s_setprio 1
	s_waitcnt lgkmcnt(0)
	v_mfma_f32_16x16x32_bf16 v[158:161], v[34:37], v[162:165], v[158:161]
	v_mfma_f32_16x16x32_bf16 v[154:157], v[42:45], v[162:165], v[154:157]
	v_mfma_f32_16x16x32_bf16 v[142:145], v[34:37], v[190:193], v[142:145]
	v_mfma_f32_16x16x32_bf16 v[138:141], v[42:45], v[190:193], v[138:141]
	v_mfma_f32_16x16x32_bf16 v[126:129], v[34:37], v[198:201], v[126:129]
	v_mfma_f32_16x16x32_bf16 v[122:125], v[42:45], v[198:201], v[122:125]
	v_mfma_f32_16x16x32_bf16 v[110:113], v[34:37], v[226:229], v[110:113]
	v_mfma_f32_16x16x32_bf16 v[106:109], v[42:45], v[226:229], v[106:109]
	v_mfma_f32_16x16x32_bf16 v[158:161], v[38:41], v[166:169], v[158:161]
	v_mfma_f32_16x16x32_bf16 v[154:157], v[46:49], v[166:169], v[154:157]
	v_mfma_f32_16x16x32_bf16 v[142:145], v[38:41], v[194:197], v[142:145]
	v_mfma_f32_16x16x32_bf16 v[138:141], v[46:49], v[194:197], v[138:141]
	v_mfma_f32_16x16x32_bf16 v[126:129], v[38:41], v[222:225], v[126:129]
	v_mfma_f32_16x16x32_bf16 v[122:125], v[46:49], v[222:225], v[122:125]
	v_mfma_f32_16x16x32_bf16 v[110:113], v[38:41], v[230:233], v[110:113]
	v_mfma_f32_16x16x32_bf16 v[106:109], v[46:49], v[230:233], v[106:109]
	s_setprio 0
	s_setprio 1
	v_mfma_f32_16x16x32_bf16 v[150:153], v[58:61], v[162:165], v[150:153]
	v_mfma_f32_16x16x32_bf16 v[146:149], v[66:69], v[162:165], v[146:149]
	v_mfma_f32_16x16x32_bf16 v[134:137], v[58:61], v[190:193], v[134:137]
	v_mfma_f32_16x16x32_bf16 v[130:133], v[66:69], v[190:193], v[130:133]
	v_mfma_f32_16x16x32_bf16 v[118:121], v[58:61], v[198:201], v[118:121]
	v_mfma_f32_16x16x32_bf16 v[114:117], v[66:69], v[198:201], v[114:117]
	v_mfma_f32_16x16x32_bf16 v[102:105], v[58:61], v[226:229], v[102:105]
	v_mfma_f32_16x16x32_bf16 v[98:101], v[66:69], v[226:229], v[98:101]
	v_mfma_f32_16x16x32_bf16 v[150:153], v[62:65], v[166:169], v[150:153]
	v_mfma_f32_16x16x32_bf16 v[146:149], v[70:73], v[166:169], v[146:149]
	v_mfma_f32_16x16x32_bf16 v[134:137], v[62:65], v[194:197], v[134:137]
	v_mfma_f32_16x16x32_bf16 v[130:133], v[70:73], v[194:197], v[130:133]
	v_mfma_f32_16x16x32_bf16 v[118:121], v[62:65], v[222:225], v[118:121]
	v_mfma_f32_16x16x32_bf16 v[114:117], v[70:73], v[222:225], v[114:117]
	v_mfma_f32_16x16x32_bf16 v[102:105], v[62:65], v[230:233], v[102:105]
	v_mfma_f32_16x16x32_bf16 v[98:101], v[70:73], v[230:233], v[98:101]
	s_setprio 0
	s_barrier
	s_add_i32 s56, s56, s33
	v_lshl_add_u64 v[172:173], s[40:41], 0, v[0:1]
	s_mov_b32 m0, s56
	ds_read_b128 v[162:165], v220 offset:16384
	global_load_lds_dwordx4 v[172:173], off
	ds_read_b128 v[166:169], v220 offset:17408
	ds_read_b128 v[190:193], v220 offset:18432
	ds_read_b128 v[194:197], v220 offset:19456
	s_add_i32 m0, s56, 0x2000
	s_add_u32 s56, s40, 0x8000
	v_lshl_add_u64 v[174:175], s[40:41], 0, v[182:183]
	s_addc_u32 s57, s41, 0
	s_add_i32 s58, s58, s33
	global_load_lds_dwordx4 v[174:175], off
	ds_read_b128 v[198:201], v220 offset:20480
	ds_read_b128 v[222:225], v220 offset:21504
	ds_read_b128 v[226:229], v220 offset:22528
	v_lshl_add_u64 v[176:177], s[56:57], 0, v[0:1]
	s_mov_b32 m0, s58
	v_lshl_add_u64 v[238:239], s[42:43], 0, v[180:181]
	global_load_lds_dwordx4 v[176:177], off
	ds_read_b128 v[230:233], v220 offset:23552
	v_lshl_add_u64 v[176:177], s[56:57], 0, v[182:183]
	s_add_i32 m0, s58, 0x2000
	s_nop 0
	global_load_lds_dwordx4 v[176:177], off
	v_lshl_add_u64 v[176:177], s[42:43], 0, v[178:179]
	s_mov_b32 m0, s44
	s_nop 0
	global_load_lds_dwordx4 v[176:177], off
	s_mov_b32 m0, s45
	s_nop 0
	global_load_lds_dwordx4 v[238:239], off
	s_waitcnt vmcnt(8)
	s_waitcnt lgkmcnt(0)
	s_barrier
; #define PG8_STAGE(bufoff, gbase, voff) do { _Pragma("unroll") for (int _i = 0; _i < 2; ++_i) \
;         __builtin_amdgcn_global_load_lds((const unsigned*)((const char*)(gbase) + (voff)[_i]), (LAS unsigned*)(lds + (bufoff) + ldsw + _i * 8192), 16, 0, 0); } while (0)
; #define PG8_LDA(dst, b, h) do { _Pragma("unroll") for (int m = 0; m < 4; ++m) _Pragma("unroll") for (int k = 0; k < 2; ++k) dst[m][k] = *(const LAS bf16x8*)(lds + PG8_SA(b, h) + aoff + m * 2048 + k * 1024); } while (0)
; #define PG8_LDB(dst, b, h) do { _Pragma("unroll") for (int n = 0; n < 2; ++n) _Pragma("unroll") for (int k = 0; k < 2; ++k) dst[n][k] = *(const LAS bf16x8*)(lds + PG8_SB(b, h) + boff + n * 2048 + k * 1024); } while (0)
; #define PG8_MMA(ai, bj, At, Bt) do { __builtin_amdgcn_s_setprio(1); _Pragma("unroll") for (int m = 0; m < 4; ++m) _Pragma("unroll") for (int n = 0; n < 2; ++n) _Pragma("unroll") for (int k = 0; k < 2; ++k) \
;         acc[ai][bj][m][n] = __builtin_amdgcn_mfma_f32_16x16x32_bf16(Bt[n][k], At[m][k], acc[ai][bj][m][n], 0, 0, 0); __builtin_amdgcn_s_setprio(0); } while (0)
; #define PG8_WAIT_V(n) asm volatile("s_waitcnt vmcnt(" #n ")" ::: "memory")
; #define PG8_WAIT_L(n) asm volatile("s_waitcnt lgkmcnt(" #n ")" ::: "memory")
; #define PG8_BAR __builtin_amdgcn_s_barrier()
; #define PG8_SCHED __builtin_amdgcn_sched_barrier(0)
; template <class Epi>
; __device__ __forceinline__ void gemm_phase(LAS unsigned char* lds, const Gemm g, const StaticOrder& S, const Epi& E, const int tid) {
;     ...
;             PG8_WAIT_V(8); PG8_WAIT_L(0); PG8_BAR; PG8_MMA(1, 0, At, B0); PG8_MMA(1, 1, At, B1); PG8_BAR; PG8_SCHED;
;             PG8_LDB(B0, 1, 0); PG8_LDB(B1, 1, 1); PG8_SCHED; PG8_LDA(At, 1, 0); PG8_STAGE(PG8_SA(0, 1), a2 + hstep, voffA);
;             PG8_WAIT_V(8); PG8_WAIT_L(0); PG8_BAR; PG8_MMA(0, 0, At, B0); PG8_MMA(0, 1, At, B1); PG8_BAR; PG8_SCHED;
	s_setprio 1
	s_waitcnt lgkmcnt(0)
	v_mfma_f32_16x16x32_bf16 v[94:97], v[34:37], v[162:165], v[94:97]
	v_mfma_f32_16x16x32_bf16 v[90:93], v[42:45], v[162:165], v[90:93]
	v_mfma_f32_16x16x32_bf16 v[78:81], v[34:37], v[190:193], v[78:81]
	v_mfma_f32_16x16x32_bf16 v[74:77], v[42:45], v[190:193], v[74:77]
	v_mfma_f32_16x16x32_bf16 v[30:33], v[34:37], v[198:201], v[30:33]
	v_mfma_f32_16x16x32_bf16 v[26:29], v[42:45], v[198:201], v[26:29]
	v_mfma_f32_16x16x32_bf16 v[14:17], v[34:37], v[226:229], v[14:17]
	v_mfma_f32_16x16x32_bf16 v[10:13], v[42:45], v[226:229], v[10:13]
	v_mfma_f32_16x16x32_bf16 v[94:97], v[38:41], v[166:169], v[94:97]
	v_mfma_f32_16x16x32_bf16 v[90:93], v[46:49], v[166:169], v[90:93]
	v_mfma_f32_16x16x32_bf16 v[78:81], v[38:41], v[194:197], v[78:81]
	v_mfma_f32_16x16x32_bf16 v[74:77], v[46:49], v[194:197], v[74:77]
	v_mfma_f32_16x16x32_bf16 v[30:33], v[38:41], v[222:225], v[30:33]
	v_mfma_f32_16x16x32_bf16 v[26:29], v[46:49], v[222:225], v[26:29]
	v_mfma_f32_16x16x32_bf16 v[14:17], v[38:41], v[230:233], v[14:17]
	v_mfma_f32_16x16x32_bf16 v[10:13], v[46:49], v[230:233], v[10:13]
	s_setprio 0
	s_setprio 1
	v_mfma_f32_16x16x32_bf16 v[22:25], v[58:61], v[198:201], v[22:25]
	v_mfma_f32_16x16x32_bf16 v[18:21], v[66:69], v[198:201], v[18:21]
	v_mfma_f32_16x16x32_bf16 v[6:9], v[58:61], v[226:229], v[6:9]
	v_mfma_f32_16x16x32_bf16 v[2:5], v[66:69], v[226:229], v[2:5]
	v_mfma_f32_16x16x32_bf16 v[34:37], v[58:61], v[162:165], v[86:89]
	v_mfma_f32_16x16x32_bf16 v[38:41], v[66:69], v[162:165], v[82:85]
	v_mfma_f32_16x16x32_bf16 v[42:45], v[58:61], v[190:193], v[54:57]
	v_mfma_f32_16x16x32_bf16 v[46:49], v[66:69], v[190:193], v[50:53]
	v_mfma_f32_16x16x32_bf16 v[22:25], v[62:65], v[222:225], v[22:25]
	v_mfma_f32_16x16x32_bf16 v[18:21], v[70:73], v[222:225], v[18:21]
	v_mfma_f32_16x16x32_bf16 v[6:9], v[62:65], v[230:233], v[6:9]
	v_mfma_f32_16x16x32_bf16 v[2:5], v[70:73], v[230:233], v[2:5]
	v_mfma_f32_16x16x32_bf16 v[34:37], v[62:65], v[166:169], v[34:37]
	v_mfma_f32_16x16x32_bf16 v[38:41], v[70:73], v[166:169], v[38:41]
	v_mfma_f32_16x16x32_bf16 v[42:45], v[62:65], v[194:197], v[42:45]
	v_mfma_f32_16x16x32_bf16 v[46:49], v[70:73], v[194:197], v[46:49]
	s_setprio 0
	s_barrier
	s_add_i32 s56, 0, 0x18000
	s_add_i32 s57, 0, 0x1c000
	v_add_u32_e32 v62, s56, v212
	v_add_u32_e32 v82, s57, v212
	ds_read_b128 v[50:53], v62
	ds_read_b128 v[54:57], v62 offset:1024
	ds_read_b128 v[58:61], v62 offset:2048
	ds_read_b128 v[62:65], v62 offset:3072
	ds_read_b128 v[66:69], v82
	ds_read_b128 v[70:73], v82 offset:1024
	ds_read_b128 v[162:165], v82 offset:2048
	ds_read_b128 v[166:169], v82 offset:3072
	s_add_u32 s42, s42, 0x80000
	s_addc_u32 s43, s43, 0
	s_mov_b32 m0, s46
	v_lshl_add_u64 v[234:235], s[42:43], 0, v[178:179]
	ds_read_b128 v[82:85], v220 offset:32768
	global_load_lds_dwordx4 v[234:235], off
	ds_read_b128 v[86:89], v220 offset:33792
	ds_read_b128 v[190:193], v220 offset:34816
	ds_read_b128 v[194:197], v220 offset:35840
	v_lshl_add_u64 v[234:235], s[42:43], 0, v[180:181]
	s_mov_b32 m0, s47
	s_nop 0
	global_load_lds_dwordx4 v[234:235], off
	ds_read_b128 v[198:201], v220 offset:36864
	ds_read_b128 v[222:225], v220 offset:37888
	ds_read_b128 v[226:229], v220 offset:38912
	ds_read_b128 v[230:233], v220 offset:39936
	s_waitcnt vmcnt(8)
	s_waitcnt lgkmcnt(0)
	s_barrier
	s_setprio 1
	s_waitcnt lgkmcnt(0)
	v_mfma_f32_16x16x32_bf16 v[158:161], v[50:53], v[82:85], v[158:161]
	v_mfma_f32_16x16x32_bf16 v[154:157], v[58:61], v[82:85], v[154:157]
	v_mfma_f32_16x16x32_bf16 v[142:145], v[50:53], v[190:193], v[142:145]
	v_mfma_f32_16x16x32_bf16 v[138:141], v[58:61], v[190:193], v[138:141]
	v_mfma_f32_16x16x32_bf16 v[126:129], v[50:53], v[198:201], v[126:129]
	v_mfma_f32_16x16x32_bf16 v[122:125], v[58:61], v[198:201], v[122:125]
	v_mfma_f32_16x16x32_bf16 v[110:113], v[50:53], v[226:229], v[110:113]
	v_mfma_f32_16x16x32_bf16 v[106:109], v[58:61], v[226:229], v[106:109]
	v_mfma_f32_16x16x32_bf16 v[158:161], v[54:57], v[86:89], v[158:161]
	v_mfma_f32_16x16x32_bf16 v[154:157], v[62:65], v[86:89], v[154:157]
	v_mfma_f32_16x16x32_bf16 v[142:145], v[54:57], v[194:197], v[142:145]
	v_mfma_f32_16x16x32_bf16 v[138:141], v[62:65], v[194:197], v[138:141]
	v_mfma_f32_16x16x32_bf16 v[126:129], v[54:57], v[222:225], v[126:129]
	v_mfma_f32_16x16x32_bf16 v[122:125], v[62:65], v[222:225], v[122:125]
	v_mfma_f32_16x16x32_bf16 v[110:113], v[54:57], v[230:233], v[110:113]
	v_mfma_f32_16x16x32_bf16 v[106:109], v[62:65], v[230:233], v[106:109]
	s_setprio 0
	s_setprio 1
	v_mfma_f32_16x16x32_bf16 v[150:153], v[66:69], v[82:85], v[150:153]
	v_mfma_f32_16x16x32_bf16 v[82:85], v[162:165], v[82:85], v[146:149]
	v_mfma_f32_16x16x32_bf16 v[146:149], v[166:169], v[86:89], v[82:85]
	v_mfma_f32_16x16x32_bf16 v[82:85], v[66:69], v[190:193], v[134:137]
	v_mfma_f32_16x16x32_bf16 v[134:137], v[70:73], v[194:197], v[82:85]
	v_mfma_f32_16x16x32_bf16 v[82:85], v[162:165], v[190:193], v[130:133]
	v_mfma_f32_16x16x32_bf16 v[130:133], v[166:169], v[194:197], v[82:85]
	v_mfma_f32_16x16x32_bf16 v[82:85], v[66:69], v[198:201], v[118:121]
	v_mfma_f32_16x16x32_bf16 v[118:121], v[70:73], v[222:225], v[82:85]
	v_mfma_f32_16x16x32_bf16 v[82:85], v[162:165], v[198:201], v[114:117]
	v_mfma_f32_16x16x32_bf16 v[114:117], v[166:169], v[222:225], v[82:85]
	v_mfma_f32_16x16x32_bf16 v[82:85], v[66:69], v[226:229], v[102:105]
	v_mfma_f32_16x16x32_bf16 v[102:105], v[70:73], v[230:233], v[82:85]
	v_mfma_f32_16x16x32_bf16 v[82:85], v[162:165], v[226:229], v[98:101]
	v_mfma_f32_16x16x32_bf16 v[150:153], v[70:73], v[86:89], v[150:153]
	v_mfma_f32_16x16x32_bf16 v[98:101], v[166:169], v[230:233], v[82:85]
	s_setprio 0
	s_barrier
; #define PG8_STAGE(bufoff, gbase, voff) do { _Pragma("unroll") for (int _i = 0; _i < 2; ++_i) \
;         __builtin_amdgcn_global_load_lds((const unsigned*)((const char*)(gbase) + (voff)[_i]), (LAS unsigned*)(lds + (bufoff) + ldsw + _i * 8192), 16, 0, 0); } while (0)
; #define PG8_LDA(dst, b, h) do { _Pragma("unroll") for (int m = 0; m < 4; ++m) _Pragma("unroll") for (int k = 0; k < 2; ++k) dst[m][k] = *(const LAS bf16x8*)(lds + PG8_SA(b, h) + aoff + m * 2048 + k * 1024); } while (0)
; #define PG8_MMA(ai, bj, At, Bt) do { __builtin_amdgcn_s_setprio(1); _Pragma("unroll") for (int m = 0; m < 4; ++m) _Pragma("unroll") for (int n = 0; n < 2; ++n) _Pragma("unroll") for (int k = 0; k < 2; ++k) \
;         acc[ai][bj][m][n] = __builtin_amdgcn_mfma_f32_16x16x32_bf16(Bt[n][k], At[m][k], acc[ai][bj][m][n], 0, 0, 0); __builtin_amdgcn_s_setprio(0); } while (0)
; #define PG8_WAIT_V(n) asm volatile("s_waitcnt vmcnt(" #n ")" ::: "memory")
; #define PG8_WAIT_L(n) asm volatile("s_waitcnt lgkmcnt(" #n ")" ::: "memory")
; #define PG8_BAR __builtin_amdgcn_s_barrier()
; #define PG8_SCHED __builtin_amdgcn_sched_barrier(0)
; template <class Epi>
; __device__ __forceinline__ void gemm_phase(LAS unsigned char* lds, const Gemm g, const StaticOrder& S, const Epi& E, const int tid) {
;     ...
;             PG8_LDA(At, 1, 1); PG8_STAGE(PG8_SB(1, 0), b3, voffB); PG8_STAGE(PG8_SB(1, 1), b3 + bhs, voffB); PG8_STAGE(PG8_SA(1, 0), a3, voffA);
;             PG8_WAIT_V(8); PG8_WAIT_L(0); PG8_BAR; PG8_MMA(1, 0, At, B0); PG8_MMA(1, 1, At, B1); PG8_BAR; PG8_SCHED;
	s_add_i32 s42, s56, s33
	v_lshl_add_u64 v[86:87], v[172:173], 0, s[70:71]
	s_mov_b32 m0, s42
	s_nop 0
	ds_read_b128 v[82:85], v220 offset:49152
	global_load_lds_dwordx4 v[86:87], off
	ds_read_b128 v[190:193], v220 offset:50176
	ds_read_b128 v[194:197], v220 offset:51200
	ds_read_b128 v[198:201], v220 offset:52224
	s_add_i32 m0, s42, 0x2000
	s_add_u32 s40, s40, 0x8080
	v_lshl_add_u64 v[86:87], v[174:175], 0, s[70:71]
	s_addc_u32 s41, s41, 0
	s_add_i32 s42, s57, s33
	global_load_lds_dwordx4 v[86:87], off
	ds_read_b128 v[222:225], v220 offset:53248
	ds_read_b128 v[226:229], v220 offset:54272
	ds_read_b128 v[230:233], v220 offset:55296
	v_lshl_add_u64 v[86:87], s[40:41], 0, v[0:1]
	s_mov_b32 m0, s42
	s_nop 0
	global_load_lds_dwordx4 v[86:87], off
	ds_read_b128 v[234:237], v220 offset:56320
	v_lshl_add_u64 v[86:87], s[40:41], 0, v[182:183]
	s_add_i32 m0, s42, 0x2000
	s_nop 0
	global_load_lds_dwordx4 v[86:87], off
	v_lshl_add_u64 v[86:87], v[176:177], 0, s[70:71]
	s_mov_b32 m0, s48
	s_nop 0
	global_load_lds_dwordx4 v[86:87], off
	v_lshl_add_u64 v[86:87], v[238:239], 0, s[70:71]
	s_mov_b32 m0, s49
	s_nop 0
	global_load_lds_dwordx4 v[86:87], off
	s_waitcnt vmcnt(8)
	s_waitcnt lgkmcnt(0)
	s_barrier
	s_setprio 1
	s_waitcnt lgkmcnt(0)
	v_mfma_f32_16x16x32_bf16 v[86:89], v[50:53], v[82:85], v[94:97]
	v_mfma_f32_16x16x32_bf16 v[94:97], v[54:57], v[190:193], v[86:89]
	v_mfma_f32_16x16x32_bf16 v[86:89], v[58:61], v[82:85], v[90:93]
	v_mfma_f32_16x16x32_bf16 v[78:81], v[50:53], v[194:197], v[78:81]
	v_mfma_f32_16x16x32_bf16 v[74:77], v[58:61], v[194:197], v[74:77]
	v_mfma_f32_16x16x32_bf16 v[30:33], v[50:53], v[222:225], v[30:33]
	v_mfma_f32_16x16x32_bf16 v[26:29], v[58:61], v[222:225], v[26:29]
	v_mfma_f32_16x16x32_bf16 v[14:17], v[50:53], v[230:233], v[14:17]
	v_mfma_f32_16x16x32_bf16 v[10:13], v[58:61], v[230:233], v[10:13]
	v_mfma_f32_16x16x32_bf16 v[90:93], v[62:65], v[190:193], v[86:89]
	v_mfma_f32_16x16x32_bf16 v[78:81], v[54:57], v[198:201], v[78:81]
	v_mfma_f32_16x16x32_bf16 v[74:77], v[62:65], v[198:201], v[74:77]
	v_mfma_f32_16x16x32_bf16 v[30:33], v[54:57], v[226:229], v[30:33]
	v_mfma_f32_16x16x32_bf16 v[26:29], v[62:65], v[226:229], v[26:29]
	v_mfma_f32_16x16x32_bf16 v[14:17], v[54:57], v[234:237], v[14:17]
	v_mfma_f32_16x16x32_bf16 v[10:13], v[62:65], v[234:237], v[10:13]
	s_setprio 0
	s_setprio 1
	v_mfma_f32_16x16x32_bf16 v[34:37], v[66:69], v[82:85], v[34:37]
	v_mfma_f32_16x16x32_bf16 v[86:89], v[70:73], v[190:193], v[34:37]
	v_mfma_f32_16x16x32_bf16 v[34:37], v[162:165], v[82:85], v[38:41]
	v_mfma_f32_16x16x32_bf16 v[82:85], v[166:169], v[190:193], v[34:37]
	v_mfma_f32_16x16x32_bf16 v[34:37], v[66:69], v[194:197], v[42:45]
	v_mfma_f32_16x16x32_bf16 v[54:57], v[70:73], v[198:201], v[34:37]
	v_mfma_f32_16x16x32_bf16 v[34:37], v[162:165], v[194:197], v[46:49]
	v_mfma_f32_16x16x32_bf16 v[22:25], v[66:69], v[222:225], v[22:25]
	v_mfma_f32_16x16x32_bf16 v[18:21], v[162:165], v[222:225], v[18:21]
	v_mfma_f32_16x16x32_bf16 v[6:9], v[66:69], v[230:233], v[6:9]
	v_mfma_f32_16x16x32_bf16 v[2:5], v[162:165], v[230:233], v[2:5]
	v_mfma_f32_16x16x32_bf16 v[50:53], v[166:169], v[198:201], v[34:37]
	v_mfma_f32_16x16x32_bf16 v[22:25], v[70:73], v[226:229], v[22:25]
	v_mfma_f32_16x16x32_bf16 v[18:21], v[166:169], v[226:229], v[18:21]
	v_mfma_f32_16x16x32_bf16 v[6:9], v[70:73], v[234:237], v[6:9]
	v_mfma_f32_16x16x32_bf16 v[2:5], v[166:169], v[234:237], v[2:5]
	s_setprio 0
	s_barrier
	s_add_i32 s55, s55, 2
	s_add_u32 s53, s53, 0x100
	s_addc_u32 s54, s54, 0
	s_add_u32 s6, s6, 0x100
	s_addc_u32 s7, s7, 0
	s_cmp_gt_u32 s55, 29
	s_cbranch_scc0 .LBB0_314
	s_and_b64 vcc, exec, s[22:23]
	s_cbranch_vccz .LBB0_317
	s_barrier

; #define PG8_STAGE(bufoff, gbase, voff) do { _Pragma("unroll") for (int _i = 0; _i < 2; ++_i) \
;         __builtin_amdgcn_global_load_lds((const unsigned*)((const char*)(gbase) + (voff)[_i]), (LAS unsigned*)(lds + (bufoff) + ldsw + _i * 8192), 16, 0, 0); } while (0)
; #define PG8_LDA(dst, b, h) do { _Pragma("unroll") for (int m = 0; m < 4; ++m) _Pragma("unroll") for (int k = 0; k < 2; ++k) dst[m][k] = *(const LAS bf16x8*)(lds + PG8_SA(b, h) + aoff + m * 2048 + k * 1024); } while (0)
; #define PG8_LDB(dst, b, h) do { _Pragma("unroll") for (int n = 0; n < 2; ++n) _Pragma("unroll") for (int k = 0; k < 2; ++k) dst[n][k] = *(const LAS bf16x8*)(lds + PG8_SB(b, h) + boff + n * 2048 + k * 1024); } while (0)
; #define PG8_MMA(ai, bj, At, Bt) do { __builtin_amdgcn_s_setprio(1); _Pragma("unroll") for (int m = 0; m < 4; ++m) _Pragma("unroll") for (int n = 0; n < 2; ++n) _Pragma("unroll") for (int k = 0; k < 2; ++k) \
;         acc[ai][bj][m][n] = __builtin_amdgcn_mfma_f32_16x16x32_bf16(Bt[n][k], At[m][k], acc[ai][bj][m][n], 0, 0, 0); __builtin_amdgcn_s_setprio(0); } while (0)
; #define PG8_WAIT_V(n) asm volatile("s_waitcnt vmcnt(" #n ")" ::: "memory")
; #define PG8_WAIT_L(n) asm volatile("s_waitcnt lgkmcnt(" #n ")" ::: "memory")
; #define PG8_BAR __builtin_amdgcn_s_barrier()
; #define PG8_SCHED __builtin_amdgcn_sched_barrier(0)
; template <class Epi>
; __device__ __forceinline__ void gemm_phase(LAS unsigned char* lds, const Gemm g, const StaticOrder& S, const Epi& E, const int tid) {
;     ...
;             PG8_LDB(B0, 0, 0); PG8_LDB(B1, 0, 1); PG8_SCHED; PG8_LDA(At, 0, 0); PG8_STAGE(PG8_SA(1, 1), a1 + hstep, voffA);
;             PG8_WAIT_V(8); PG8_WAIT_L(0); PG8_BAR; PG8_MMA(0, 0, At, B0); PG8_MMA(0, 1, At, B1); PG8_BAR; PG8_SCHED;
;             PG8_LDA(At, 0, 1); PG8_STAGE(PG8_SB(0, 0), b2, voffB); PG8_STAGE(PG8_SB(0, 1), b2 + bhs, voffB); PG8_STAGE(PG8_SA(0, 0), a2, voffA);
;             PG8_WAIT_V(8); PG8_WAIT_L(0); PG8_BAR; PG8_MMA(1, 0, At, B0); PG8_MMA(1, 1, At, B1); PG8_BAR; PG8_SCHED;
.LBB0_454:
	s_add_i32 s13, 0, 0x10000
	v_add_u32_e32 v0, s13, v153
	s_add_i32 s36, 0, 0x14000
	ds_read_b128 v[132:135], v0
	ds_read_b128 v[136:139], v0 offset:1024
	ds_read_b128 v[156:159], v0 offset:2048
	ds_read_b128 v[160:163], v0 offset:3072
	v_add_u32_e32 v0, s36, v153
	ds_read_b128 v[164:167], v0
	ds_read_b128 v[178:181], v0 offset:1024
	ds_read_b128 v[182:185], v0 offset:2048
	ds_read_b128 v[186:189], v0 offset:3072
	s_add_u32 s34, s34, 0x40000
	s_addc_u32 s35, s35, 0
	v_lshl_add_u64 v[2:3], s[34:35], 0, v[140:141]
	s_add_i32 m0, s43, 0xc000
	ds_read_b128 v[190:193], v155
	global_load_lds_dwordx4 v[2:3], off
	ds_read_b128 v[194:197], v155 offset:1024
	ds_read_b128 v[198:201], v155 offset:2048
	ds_read_b128 v[212:215], v155 offset:3072
	v_lshl_add_u64 v[2:3], s[34:35], 0, v[144:145]
	s_add_i32 m0, s43, 0xe000
	s_nop 0
	global_load_lds_dwordx4 v[2:3], off
	ds_read_b128 v[216:219], v155 offset:4096
	ds_read_b128 v[220:223], v155 offset:5120
	ds_read_b128 v[224:227], v155 offset:6144
	ds_read_b128 v[228:231], v155 offset:7168
	s_waitcnt vmcnt(8)
	s_waitcnt lgkmcnt(0)
	s_barrier
	s_setprio 1
	s_waitcnt lgkmcnt(0)
	v_mfma_f32_16x16x32_bf16 v[128:131], v[132:135], v[190:193], v[128:131]
	v_mfma_f32_16x16x32_bf16 v[124:127], v[156:159], v[190:193], v[124:127]
	v_mfma_f32_16x16x32_bf16 v[112:115], v[132:135], v[198:201], v[112:115]
	v_mfma_f32_16x16x32_bf16 v[108:111], v[156:159], v[198:201], v[108:111]
	v_mfma_f32_16x16x32_bf16 v[96:99], v[132:135], v[216:219], v[96:99]
	v_mfma_f32_16x16x32_bf16 v[92:95], v[156:159], v[216:219], v[92:95]
	v_mfma_f32_16x16x32_bf16 v[80:83], v[132:135], v[224:227], v[80:83]
	v_mfma_f32_16x16x32_bf16 v[76:79], v[156:159], v[224:227], v[76:79]
	v_mfma_f32_16x16x32_bf16 v[128:131], v[136:139], v[194:197], v[128:131]
	v_mfma_f32_16x16x32_bf16 v[124:127], v[160:163], v[194:197], v[124:127]
	v_mfma_f32_16x16x32_bf16 v[112:115], v[136:139], v[212:215], v[112:115]
	v_mfma_f32_16x16x32_bf16 v[108:111], v[160:163], v[212:215], v[108:111]
	v_mfma_f32_16x16x32_bf16 v[96:99], v[136:139], v[220:223], v[96:99]
	v_mfma_f32_16x16x32_bf16 v[92:95], v[160:163], v[220:223], v[92:95]
	v_mfma_f32_16x16x32_bf16 v[80:83], v[136:139], v[228:231], v[80:83]
	v_mfma_f32_16x16x32_bf16 v[76:79], v[160:163], v[228:231], v[76:79]
	s_setprio 0
	s_setprio 1
	v_mfma_f32_16x16x32_bf16 v[120:123], v[164:167], v[190:193], v[120:123]
	v_mfma_f32_16x16x32_bf16 v[116:119], v[182:185], v[190:193], v[116:119]
	v_mfma_f32_16x16x32_bf16 v[104:107], v[164:167], v[198:201], v[104:107]
	v_mfma_f32_16x16x32_bf16 v[100:103], v[182:185], v[198:201], v[100:103]
	v_mfma_f32_16x16x32_bf16 v[88:91], v[164:167], v[216:219], v[88:91]
	v_mfma_f32_16x16x32_bf16 v[84:87], v[182:185], v[216:219], v[84:87]
	v_mfma_f32_16x16x32_bf16 v[72:75], v[164:167], v[224:227], v[72:75]
	v_mfma_f32_16x16x32_bf16 v[68:71], v[182:185], v[224:227], v[68:71]
	v_mfma_f32_16x16x32_bf16 v[120:123], v[178:181], v[194:197], v[120:123]
	v_mfma_f32_16x16x32_bf16 v[116:119], v[186:189], v[194:197], v[116:119]
	v_mfma_f32_16x16x32_bf16 v[104:107], v[178:181], v[212:215], v[104:107]
	v_mfma_f32_16x16x32_bf16 v[100:103], v[186:189], v[212:215], v[100:103]
	v_mfma_f32_16x16x32_bf16 v[88:91], v[178:181], v[220:223], v[88:91]
	v_mfma_f32_16x16x32_bf16 v[84:87], v[186:189], v[220:223], v[84:87]
	v_mfma_f32_16x16x32_bf16 v[72:75], v[178:181], v[228:231], v[72:75]
	v_mfma_f32_16x16x32_bf16 v[68:71], v[186:189], v[228:231], v[68:71]
	s_setprio 0
	s_barrier
	s_add_i32 s13, s13, s42
	v_lshl_add_u64 v[168:169], s[28:29], 0, v[142:143]
	s_mov_b32 m0, s13
	ds_read_b128 v[190:193], v155 offset:16384
	global_load_lds_dwordx4 v[168:169], off
	ds_read_b128 v[194:197], v155 offset:17408
	ds_read_b128 v[198:201], v155 offset:18432
	ds_read_b128 v[212:215], v155 offset:19456
	s_add_i32 m0, s13, 0x2000
	s_add_u32 s34, s28, 0x4000
	v_lshl_add_u64 v[172:173], s[28:29], 0, v[146:147]
	s_addc_u32 s35, s29, 0
	s_add_i32 s13, s36, s42
	global_load_lds_dwordx4 v[172:173], off
	ds_read_b128 v[216:219], v155 offset:20480
	ds_read_b128 v[220:223], v155 offset:21504
	ds_read_b128 v[224:227], v155 offset:22528
	v_lshl_add_u64 v[2:3], s[34:35], 0, v[142:143]
	s_mov_b32 m0, s13
	v_lshl_add_u64 v[174:175], s[30:31], 0, v[140:141]
	global_load_lds_dwordx4 v[2:3], off
	ds_read_b128 v[228:231], v155 offset:23552
	v_lshl_add_u64 v[2:3], s[34:35], 0, v[146:147]
	s_add_i32 m0, s13, 0x2000
	v_lshl_add_u64 v[176:177], s[30:31], 0, v[144:145]
	global_load_lds_dwordx4 v[2:3], off
	s_mov_b32 m0, s43
	s_nop 0
	global_load_lds_dwordx4 v[174:175], off
	s_mov_b32 m0, s44
	s_nop 0
	global_load_lds_dwordx4 v[176:177], off
	s_waitcnt vmcnt(8)
	s_waitcnt lgkmcnt(0)
	s_barrier
; #define PG8_STAGE(bufoff, gbase, voff) do { _Pragma("unroll") for (int _i = 0; _i < 2; ++_i) \
;         __builtin_amdgcn_global_load_lds((const unsigned*)((const char*)(gbase) + (voff)[_i]), (LAS unsigned*)(lds + (bufoff) + ldsw + _i * 8192), 16, 0, 0); } while (0)
; #define PG8_LDA(dst, b, h) do { _Pragma("unroll") for (int m = 0; m < 4; ++m) _Pragma("unroll") for (int k = 0; k < 2; ++k) dst[m][k] = *(const LAS bf16x8*)(lds + PG8_SA(b, h) + aoff + m * 2048 + k * 1024); } while (0)
; #define PG8_LDB(dst, b, h) do { _Pragma("unroll") for (int n = 0; n < 2; ++n) _Pragma("unroll") for (int k = 0; k < 2; ++k) dst[n][k] = *(const LAS bf16x8*)(lds + PG8_SB(b, h) + boff + n * 2048 + k * 1024); } while (0)
; #define PG8_MMA(ai, bj, At, Bt) do { __builtin_amdgcn_s_setprio(1); _Pragma("unroll") for (int m = 0; m < 4; ++m) _Pragma("unroll") for (int n = 0; n < 2; ++n) _Pragma("unroll") for (int k = 0; k < 2; ++k) \
;         acc[ai][bj][m][n] = __builtin_amdgcn_mfma_f32_16x16x32_bf16(Bt[n][k], At[m][k], acc[ai][bj][m][n], 0, 0, 0); __builtin_amdgcn_s_setprio(0); } while (0)
; #define PG8_WAIT_V(n) asm volatile("s_waitcnt vmcnt(" #n ")" ::: "memory")
; #define PG8_WAIT_L(n) asm volatile("s_waitcnt lgkmcnt(" #n ")" ::: "memory")
; #define PG8_BAR __builtin_amdgcn_s_barrier()
; #define PG8_SCHED __builtin_amdgcn_sched_barrier(0)
; template <class Epi>
; __device__ __forceinline__ void gemm_phase(LAS unsigned char* lds, const Gemm g, const StaticOrder& S, const Epi& E, const int tid) {
;     ...
;             PG8_WAIT_V(8); PG8_WAIT_L(0); PG8_BAR; PG8_MMA(1, 0, At, B0); PG8_MMA(1, 1, At, B1); PG8_BAR; PG8_SCHED;
;             PG8_LDB(B0, 1, 0); PG8_LDB(B1, 1, 1); PG8_SCHED; PG8_LDA(At, 1, 0); PG8_STAGE(PG8_SA(0, 1), a2 + hstep, voffA);
;             PG8_WAIT_V(8); PG8_WAIT_L(0); PG8_BAR; PG8_MMA(0, 0, At, B0); PG8_MMA(0, 1, At, B1); PG8_BAR; PG8_SCHED;
	s_setprio 1
	s_waitcnt lgkmcnt(0)
	v_mfma_f32_16x16x32_bf16 v[64:67], v[132:135], v[190:193], v[64:67]
	v_mfma_f32_16x16x32_bf16 v[60:63], v[156:159], v[190:193], v[60:63]
	v_mfma_f32_16x16x32_bf16 v[48:51], v[132:135], v[198:201], v[48:51]
	v_mfma_f32_16x16x32_bf16 v[44:47], v[156:159], v[198:201], v[44:47]
	v_mfma_f32_16x16x32_bf16 v[32:35], v[132:135], v[216:219], v[32:35]
	v_mfma_f32_16x16x32_bf16 v[28:31], v[156:159], v[216:219], v[28:31]
	v_mfma_f32_16x16x32_bf16 v[16:19], v[132:135], v[224:227], v[16:19]
	v_mfma_f32_16x16x32_bf16 v[12:15], v[156:159], v[224:227], v[12:15]
	v_mfma_f32_16x16x32_bf16 v[64:67], v[136:139], v[194:197], v[64:67]
	v_mfma_f32_16x16x32_bf16 v[60:63], v[160:163], v[194:197], v[60:63]
	v_mfma_f32_16x16x32_bf16 v[48:51], v[136:139], v[212:215], v[48:51]
	v_mfma_f32_16x16x32_bf16 v[44:47], v[160:163], v[212:215], v[44:47]
	v_mfma_f32_16x16x32_bf16 v[32:35], v[136:139], v[220:223], v[32:35]
	v_mfma_f32_16x16x32_bf16 v[28:31], v[160:163], v[220:223], v[28:31]
	v_mfma_f32_16x16x32_bf16 v[16:19], v[136:139], v[228:231], v[16:19]
	v_mfma_f32_16x16x32_bf16 v[12:15], v[160:163], v[228:231], v[12:15]
	s_setprio 0
	s_setprio 1
	v_mfma_f32_16x16x32_bf16 v[56:59], v[164:167], v[190:193], v[56:59]
	v_mfma_f32_16x16x32_bf16 v[52:55], v[182:185], v[190:193], v[52:55]
	v_mfma_f32_16x16x32_bf16 v[40:43], v[164:167], v[198:201], v[40:43]
	v_mfma_f32_16x16x32_bf16 v[36:39], v[182:185], v[198:201], v[36:39]
	v_mfma_f32_16x16x32_bf16 v[24:27], v[164:167], v[216:219], v[24:27]
	v_mfma_f32_16x16x32_bf16 v[20:23], v[182:185], v[216:219], v[20:23]
	v_mfma_f32_16x16x32_bf16 v[8:11], v[164:167], v[224:227], v[8:11]
	v_mfma_f32_16x16x32_bf16 v[2:5], v[182:185], v[224:227], v[4:7]
	v_mfma_f32_16x16x32_bf16 v[56:59], v[178:181], v[194:197], v[56:59]
	v_mfma_f32_16x16x32_bf16 v[52:55], v[186:189], v[194:197], v[52:55]
	v_mfma_f32_16x16x32_bf16 v[40:43], v[178:181], v[212:215], v[40:43]
	v_mfma_f32_16x16x32_bf16 v[36:39], v[186:189], v[212:215], v[36:39]
	v_mfma_f32_16x16x32_bf16 v[24:27], v[178:181], v[220:223], v[24:27]
	v_mfma_f32_16x16x32_bf16 v[20:23], v[186:189], v[220:223], v[20:23]
	v_mfma_f32_16x16x32_bf16 v[8:11], v[178:181], v[228:231], v[8:11]
	v_mfma_f32_16x16x32_bf16 v[2:5], v[186:189], v[228:231], v[2:5]
	s_setprio 0
	s_barrier
	s_add_i32 s13, 0, 0x18000
	v_add_u32_e32 v0, s13, v153
	s_add_i32 s34, 0, 0x1c000
	ds_read_b128 v[132:135], v0
	ds_read_b128 v[136:139], v0 offset:1024
	ds_read_b128 v[156:159], v0 offset:2048
	ds_read_b128 v[160:163], v0 offset:3072
	v_add_u32_e32 v0, s34, v153
	ds_read_b128 v[164:167], v0
	ds_read_b128 v[178:181], v0 offset:1024
	ds_read_b128 v[182:185], v0 offset:2048
	ds_read_b128 v[186:189], v0 offset:3072
	s_add_u32 s30, s30, 0x40000
	s_addc_u32 s31, s31, 0
	s_mov_b32 m0, s45
	v_lshl_add_u64 v[6:7], s[30:31], 0, v[140:141]
	ds_read_b128 v[190:193], v155 offset:32768
	global_load_lds_dwordx4 v[6:7], off
	ds_read_b128 v[194:197], v155 offset:33792
	ds_read_b128 v[198:201], v155 offset:34816
	ds_read_b128 v[212:215], v155 offset:35840
	v_lshl_add_u64 v[6:7], s[30:31], 0, v[144:145]
	s_mov_b32 m0, s46
	s_nop 0
	global_load_lds_dwordx4 v[6:7], off
	ds_read_b128 v[216:219], v155 offset:36864
	ds_read_b128 v[220:223], v155 offset:37888
	ds_read_b128 v[224:227], v155 offset:38912
	ds_read_b128 v[228:231], v155 offset:39936
	s_waitcnt vmcnt(8)
	s_waitcnt lgkmcnt(0)
	s_barrier
	s_setprio 1
	s_waitcnt lgkmcnt(0)
	v_mfma_f32_16x16x32_bf16 v[128:131], v[132:135], v[190:193], v[128:131]
	v_mfma_f32_16x16x32_bf16 v[124:127], v[156:159], v[190:193], v[124:127]
	v_mfma_f32_16x16x32_bf16 v[112:115], v[132:135], v[198:201], v[112:115]
	v_mfma_f32_16x16x32_bf16 v[108:111], v[156:159], v[198:201], v[108:111]
	v_mfma_f32_16x16x32_bf16 v[96:99], v[132:135], v[216:219], v[96:99]
	v_mfma_f32_16x16x32_bf16 v[92:95], v[156:159], v[216:219], v[92:95]
	v_mfma_f32_16x16x32_bf16 v[80:83], v[132:135], v[224:227], v[80:83]
	v_mfma_f32_16x16x32_bf16 v[76:79], v[156:159], v[224:227], v[76:79]
	v_mfma_f32_16x16x32_bf16 v[128:131], v[136:139], v[194:197], v[128:131]
	v_mfma_f32_16x16x32_bf16 v[124:127], v[160:163], v[194:197], v[124:127]
	v_mfma_f32_16x16x32_bf16 v[112:115], v[136:139], v[212:215], v[112:115]
	v_mfma_f32_16x16x32_bf16 v[108:111], v[160:163], v[212:215], v[108:111]
	v_mfma_f32_16x16x32_bf16 v[96:99], v[136:139], v[220:223], v[96:99]
	v_mfma_f32_16x16x32_bf16 v[92:95], v[160:163], v[220:223], v[92:95]
	v_mfma_f32_16x16x32_bf16 v[80:83], v[136:139], v[228:231], v[80:83]
	v_mfma_f32_16x16x32_bf16 v[76:79], v[160:163], v[228:231], v[76:79]
	s_setprio 0
	s_setprio 1
	v_mfma_f32_16x16x32_bf16 v[120:123], v[164:167], v[190:193], v[120:123]
	v_mfma_f32_16x16x32_bf16 v[116:119], v[182:185], v[190:193], v[116:119]
	v_mfma_f32_16x16x32_bf16 v[104:107], v[164:167], v[198:201], v[104:107]
	v_mfma_f32_16x16x32_bf16 v[100:103], v[182:185], v[198:201], v[100:103]
	v_mfma_f32_16x16x32_bf16 v[88:91], v[164:167], v[216:219], v[88:91]
	v_mfma_f32_16x16x32_bf16 v[84:87], v[182:185], v[216:219], v[84:87]
	v_mfma_f32_16x16x32_bf16 v[72:75], v[164:167], v[224:227], v[72:75]
	v_mfma_f32_16x16x32_bf16 v[68:71], v[182:185], v[224:227], v[68:71]
	v_mfma_f32_16x16x32_bf16 v[120:123], v[178:181], v[194:197], v[120:123]
	v_mfma_f32_16x16x32_bf16 v[116:119], v[186:189], v[194:197], v[116:119]
	v_mfma_f32_16x16x32_bf16 v[104:107], v[178:181], v[212:215], v[104:107]
	v_mfma_f32_16x16x32_bf16 v[100:103], v[186:189], v[212:215], v[100:103]
	v_mfma_f32_16x16x32_bf16 v[88:91], v[178:181], v[220:223], v[88:91]
	v_mfma_f32_16x16x32_bf16 v[84:87], v[186:189], v[220:223], v[84:87]
	v_mfma_f32_16x16x32_bf16 v[72:75], v[178:181], v[228:231], v[72:75]
	v_mfma_f32_16x16x32_bf16 v[68:71], v[186:189], v[228:231], v[68:71]
	s_setprio 0
	s_barrier
; #define PG8_STAGE(bufoff, gbase, voff) do { _Pragma("unroll") for (int _i = 0; _i < 2; ++_i) \
;         __builtin_amdgcn_global_load_lds((const unsigned*)((const char*)(gbase) + (voff)[_i]), (LAS unsigned*)(lds + (bufoff) + ldsw + _i * 8192), 16, 0, 0); } while (0)
; #define PG8_LDA(dst, b, h) do { _Pragma("unroll") for (int m = 0; m < 4; ++m) _Pragma("unroll") for (int k = 0; k < 2; ++k) dst[m][k] = *(const LAS bf16x8*)(lds + PG8_SA(b, h) + aoff + m * 2048 + k * 1024); } while (0)
; #define PG8_MMA(ai, bj, At, Bt) do { __builtin_amdgcn_s_setprio(1); _Pragma("unroll") for (int m = 0; m < 4; ++m) _Pragma("unroll") for (int n = 0; n < 2; ++n) _Pragma("unroll") for (int k = 0; k < 2; ++k) \
;         acc[ai][bj][m][n] = __builtin_amdgcn_mfma_f32_16x16x32_bf16(Bt[n][k], At[m][k], acc[ai][bj][m][n], 0, 0, 0); __builtin_amdgcn_s_setprio(0); } while (0)
; #define PG8_WAIT_V(n) asm volatile("s_waitcnt vmcnt(" #n ")" ::: "memory")
; #define PG8_WAIT_L(n) asm volatile("s_waitcnt lgkmcnt(" #n ")" ::: "memory")
; #define PG8_BAR __builtin_amdgcn_s_barrier()
; #define PG8_SCHED __builtin_amdgcn_sched_barrier(0)
; template <class Epi>
; __device__ __forceinline__ void gemm_phase(LAS unsigned char* lds, const Gemm g, const StaticOrder& S, const Epi& E, const int tid) {
;     ...
;             PG8_LDA(At, 1, 1); PG8_STAGE(PG8_SB(1, 0), b3, voffB); PG8_STAGE(PG8_SB(1, 1), b3 + bhs, voffB); PG8_STAGE(PG8_SA(1, 0), a3, voffA);
;             PG8_WAIT_V(8); PG8_WAIT_L(0); PG8_BAR; PG8_MMA(1, 0, At, B0); PG8_MMA(1, 1, At, B1); PG8_BAR; PG8_SCHED;
	s_add_i32 s13, s13, s42
	v_lshl_add_u64 v[6:7], v[168:169], 0, s[70:71]
	s_mov_b32 m0, s13
	ds_read_b128 v[190:193], v155 offset:49152
	global_load_lds_dwordx4 v[6:7], off
	ds_read_b128 v[194:197], v155 offset:50176
	ds_read_b128 v[198:201], v155 offset:51200
	ds_read_b128 v[212:215], v155 offset:52224
	s_add_i32 m0, s13, 0x2000
	s_add_u32 s28, s28, 0x4080
	v_lshl_add_u64 v[6:7], v[172:173], 0, s[70:71]
	s_addc_u32 s29, s29, 0
	s_add_i32 s13, s34, s42
	global_load_lds_dwordx4 v[6:7], off
	ds_read_b128 v[216:219], v155 offset:53248
	ds_read_b128 v[220:223], v155 offset:54272
	ds_read_b128 v[224:227], v155 offset:55296
	v_lshl_add_u64 v[6:7], s[28:29], 0, v[142:143]
	s_mov_b32 m0, s13
	s_nop 0
	global_load_lds_dwordx4 v[6:7], off
	ds_read_b128 v[228:231], v155 offset:56320
	v_lshl_add_u64 v[6:7], s[28:29], 0, v[146:147]
	s_add_i32 m0, s13, 0x2000
	s_nop 0
	global_load_lds_dwordx4 v[6:7], off
	v_lshl_add_u64 v[6:7], v[174:175], 0, s[70:71]
	s_mov_b32 m0, s47
	s_nop 0
	global_load_lds_dwordx4 v[6:7], off
	v_lshl_add_u64 v[6:7], v[176:177], 0, s[70:71]
	s_mov_b32 m0, s48
	s_nop 0
	global_load_lds_dwordx4 v[6:7], off
	s_waitcnt vmcnt(8)
	s_waitcnt lgkmcnt(0)
	s_barrier
	s_setprio 1
	s_waitcnt lgkmcnt(0)
	v_mfma_f32_16x16x32_bf16 v[64:67], v[132:135], v[190:193], v[64:67]
	v_mfma_f32_16x16x32_bf16 v[60:63], v[156:159], v[190:193], v[60:63]
	v_mfma_f32_16x16x32_bf16 v[48:51], v[132:135], v[198:201], v[48:51]
	v_mfma_f32_16x16x32_bf16 v[44:47], v[156:159], v[198:201], v[44:47]
	v_mfma_f32_16x16x32_bf16 v[32:35], v[132:135], v[216:219], v[32:35]
	v_mfma_f32_16x16x32_bf16 v[28:31], v[156:159], v[216:219], v[28:31]
	v_mfma_f32_16x16x32_bf16 v[16:19], v[132:135], v[224:227], v[16:19]
	v_mfma_f32_16x16x32_bf16 v[12:15], v[156:159], v[224:227], v[12:15]
	v_mfma_f32_16x16x32_bf16 v[64:67], v[136:139], v[194:197], v[64:67]
	v_mfma_f32_16x16x32_bf16 v[60:63], v[160:163], v[194:197], v[60:63]
	v_mfma_f32_16x16x32_bf16 v[48:51], v[136:139], v[212:215], v[48:51]
	v_mfma_f32_16x16x32_bf16 v[44:47], v[160:163], v[212:215], v[44:47]
	v_mfma_f32_16x16x32_bf16 v[32:35], v[136:139], v[220:223], v[32:35]
	v_mfma_f32_16x16x32_bf16 v[28:31], v[160:163], v[220:223], v[28:31]
	v_mfma_f32_16x16x32_bf16 v[16:19], v[136:139], v[228:231], v[16:19]
	v_mfma_f32_16x16x32_bf16 v[12:15], v[160:163], v[228:231], v[12:15]
	s_setprio 0
	s_setprio 1
	v_mfma_f32_16x16x32_bf16 v[56:59], v[164:167], v[190:193], v[56:59]
	v_mfma_f32_16x16x32_bf16 v[52:55], v[182:185], v[190:193], v[52:55]
	v_mfma_f32_16x16x32_bf16 v[40:43], v[164:167], v[198:201], v[40:43]
	v_mfma_f32_16x16x32_bf16 v[36:39], v[182:185], v[198:201], v[36:39]
	v_mfma_f32_16x16x32_bf16 v[24:27], v[164:167], v[216:219], v[24:27]
	v_mfma_f32_16x16x32_bf16 v[20:23], v[182:185], v[216:219], v[20:23]
	v_mfma_f32_16x16x32_bf16 v[6:9], v[164:167], v[224:227], v[8:11]
	v_mfma_f32_16x16x32_bf16 v[2:5], v[182:185], v[224:227], v[2:5]
	v_mfma_f32_16x16x32_bf16 v[56:59], v[178:181], v[194:197], v[56:59]
	v_mfma_f32_16x16x32_bf16 v[52:55], v[186:189], v[194:197], v[52:55]
	v_mfma_f32_16x16x32_bf16 v[40:43], v[178:181], v[212:215], v[40:43]
	v_mfma_f32_16x16x32_bf16 v[36:39], v[186:189], v[212:215], v[36:39]
	v_mfma_f32_16x16x32_bf16 v[24:27], v[178:181], v[220:223], v[24:27]
	v_mfma_f32_16x16x32_bf16 v[20:23], v[186:189], v[220:223], v[20:23]
	v_mfma_f32_16x16x32_bf16 v[8:11], v[178:181], v[228:231], v[6:9]
	v_mfma_f32_16x16x32_bf16 v[4:7], v[186:189], v[228:231], v[2:5]
	s_setprio 0
	s_barrier
	s_add_i32 s2, s2, 2
	s_add_u32 s24, s24, 0x100
	s_addc_u32 s25, s25, 0
	s_add_u32 s26, s26, 0x100
	s_addc_u32 s27, s27, 0
	s_cmp_gt_u32 s11, 29
	s_cbranch_scc1 .LBB0_467

; #define PG8_STAGE(bufoff, gbase, voff) do { _Pragma("unroll") for (int _i = 0; _i < 2; ++_i) \
;         __builtin_amdgcn_global_load_lds((const unsigned*)((const char*)(gbase) + (voff)[_i]), (LAS unsigned*)(lds + (bufoff) + ldsw + _i * 8192), 16, 0, 0); } while (0)
; #define PG8_LDA(dst, b, h) do { _Pragma("unroll") for (int m = 0; m < 4; ++m) _Pragma("unroll") for (int k = 0; k < 2; ++k) dst[m][k] = *(const LAS bf16x8*)(lds + PG8_SA(b, h) + aoff + m * 2048 + k * 1024); } while (0)
; #define PG8_LDB(dst, b, h) do { _Pragma("unroll") for (int n = 0; n < 2; ++n) _Pragma("unroll") for (int k = 0; k < 2; ++k) dst[n][k] = *(const LAS bf16x8*)(lds + PG8_SB(b, h) + boff + n * 2048 + k * 1024); } while (0)
; #define PG8_MMA(ai, bj, At, Bt) do { __builtin_amdgcn_s_setprio(1); _Pragma("unroll") for (int m = 0; m < 4; ++m) _Pragma("unroll") for (int n = 0; n < 2; ++n) _Pragma("unroll") for (int k = 0; k < 2; ++k) \
;         acc[ai][bj][m][n] = __builtin_amdgcn_mfma_f32_16x16x32_bf16(Bt[n][k], At[m][k], acc[ai][bj][m][n], 0, 0, 0); __builtin_amdgcn_s_setprio(0); } while (0)
; #define PG8_WAIT_V(n) asm volatile("s_waitcnt vmcnt(" #n ")" ::: "memory")
; #define PG8_WAIT_L(n) asm volatile("s_waitcnt lgkmcnt(" #n ")" ::: "memory")
; #define PG8_BAR __builtin_amdgcn_s_barrier()
; #define PG8_SCHED __builtin_amdgcn_sched_barrier(0)
; template <class Epi>
; __device__ __forceinline__ void gemm_phase(LAS unsigned char* lds, const Gemm g, const StaticOrder& S, const Epi& E, const int tid) {
;     ...
;             PG8_LDB(B0, 0, 0); PG8_LDB(B1, 0, 1); PG8_SCHED; PG8_LDA(At, 0, 0); PG8_STAGE(PG8_SA(1, 1), a1 + hstep, voffA);
;             PG8_WAIT_V(8); PG8_WAIT_L(0); PG8_BAR; PG8_MMA(0, 0, At, B0); PG8_MMA(0, 1, At, B1); PG8_BAR; PG8_SCHED;
;             PG8_LDA(At, 0, 1); PG8_STAGE(PG8_SB(0, 0), b2, voffB); PG8_STAGE(PG8_SB(0, 1), b2 + bhs, voffB); PG8_STAGE(PG8_SA(0, 0), a2, voffA);
;             PG8_WAIT_V(8); PG8_WAIT_L(0); PG8_BAR; PG8_MMA(1, 0, At, B0); PG8_MMA(1, 1, At, B1); PG8_BAR; PG8_SCHED;
.LBB0_546:
	s_add_u32 s28, s26, 0xfff80080
	s_addc_u32 s29, s27, -1
	s_add_i32 s44, 0, 0x10000
	s_cmp_eq_u32 s39, 28
	s_cselect_b32 s35, s19, s29
	s_cselect_b32 s34, s31, s28
	v_add_u32_e32 v0, s44, v149
	s_cselect_b32 s29, s17, s38
	s_cselect_b32 s28, s33, s37
	s_add_i32 s46, 0, 0x14000
	ds_read_b128 v[150:153], v0
	ds_read_b128 v[154:157], v0 offset:1024
	ds_read_b128 v[158:161], v0 offset:2048
	ds_read_b128 v[186:189], v0 offset:3072
	v_add_u32_e32 v0, s46, v149
	ds_read_b128 v[190:193], v0
	ds_read_b128 v[194:197], v0 offset:1024
	ds_read_b128 v[198:201], v0 offset:2048
	ds_read_b128 v[212:215], v0 offset:3072
	v_lshl_add_u64 v[162:163], s[26:27], 0, v[146:147]
	s_add_i32 m0, s57, 0xc000
	ds_read_b128 v[216:219], v184
	global_load_lds_dwordx4 v[162:163], off
	ds_read_b128 v[220:223], v184 offset:1024
	ds_read_b128 v[224:227], v184 offset:2048
	ds_read_b128 v[228:231], v184 offset:3072
	v_lshl_add_u64 v[162:163], s[26:27], 0, v[144:145]
	s_add_i32 m0, s57, 0xe000
	s_nop 0
	global_load_lds_dwordx4 v[162:163], off
	ds_read_b128 v[232:235], v184 offset:4096
	ds_read_b128 v[236:239], v184 offset:5120
	ds_read_b128 v[240:243], v184 offset:6144
	ds_read_b128 v[244:247], v184 offset:7168
	s_waitcnt vmcnt(8)
	s_waitcnt lgkmcnt(0)
	s_barrier
	s_setprio 1
	s_waitcnt lgkmcnt(0)
	v_mfma_f32_16x16x32_bf16 v[126:129], v[150:153], v[216:219], v[126:129]
	v_mfma_f32_16x16x32_bf16 v[122:125], v[158:161], v[216:219], v[122:125]
	v_mfma_f32_16x16x32_bf16 v[110:113], v[150:153], v[224:227], v[110:113]
	v_mfma_f32_16x16x32_bf16 v[106:109], v[158:161], v[224:227], v[106:109]
	v_mfma_f32_16x16x32_bf16 v[94:97], v[150:153], v[232:235], v[94:97]
	v_mfma_f32_16x16x32_bf16 v[90:93], v[158:161], v[232:235], v[90:93]
	v_mfma_f32_16x16x32_bf16 v[78:81], v[150:153], v[240:243], v[78:81]
	v_mfma_f32_16x16x32_bf16 v[74:77], v[158:161], v[240:243], v[74:77]
	v_mfma_f32_16x16x32_bf16 v[126:129], v[154:157], v[220:223], v[126:129]
	v_mfma_f32_16x16x32_bf16 v[122:125], v[186:189], v[220:223], v[122:125]
	v_mfma_f32_16x16x32_bf16 v[110:113], v[154:157], v[228:231], v[110:113]
	v_mfma_f32_16x16x32_bf16 v[106:109], v[186:189], v[228:231], v[106:109]
	v_mfma_f32_16x16x32_bf16 v[94:97], v[154:157], v[236:239], v[94:97]
	v_mfma_f32_16x16x32_bf16 v[90:93], v[186:189], v[236:239], v[90:93]
	v_mfma_f32_16x16x32_bf16 v[78:81], v[154:157], v[244:247], v[78:81]
	v_mfma_f32_16x16x32_bf16 v[74:77], v[186:189], v[244:247], v[74:77]
	s_setprio 0
	s_setprio 1
	v_mfma_f32_16x16x32_bf16 v[118:121], v[190:193], v[216:219], v[118:121]
	v_mfma_f32_16x16x32_bf16 v[114:117], v[198:201], v[216:219], v[114:117]
	v_mfma_f32_16x16x32_bf16 v[102:105], v[190:193], v[224:227], v[102:105]
	v_mfma_f32_16x16x32_bf16 v[98:101], v[198:201], v[224:227], v[98:101]
	v_mfma_f32_16x16x32_bf16 v[86:89], v[190:193], v[232:235], v[86:89]
	v_mfma_f32_16x16x32_bf16 v[82:85], v[198:201], v[232:235], v[82:85]
	v_mfma_f32_16x16x32_bf16 v[70:73], v[190:193], v[240:243], v[70:73]
	v_mfma_f32_16x16x32_bf16 v[66:69], v[198:201], v[240:243], v[66:69]
	v_mfma_f32_16x16x32_bf16 v[118:121], v[194:197], v[220:223], v[118:121]
	v_mfma_f32_16x16x32_bf16 v[114:117], v[212:215], v[220:223], v[114:117]
	v_mfma_f32_16x16x32_bf16 v[102:105], v[194:197], v[228:231], v[102:105]
	v_mfma_f32_16x16x32_bf16 v[98:101], v[212:215], v[228:231], v[98:101]
	v_mfma_f32_16x16x32_bf16 v[86:89], v[194:197], v[236:239], v[86:89]
	v_mfma_f32_16x16x32_bf16 v[82:85], v[212:215], v[236:239], v[82:85]
	v_mfma_f32_16x16x32_bf16 v[70:73], v[194:197], v[244:247], v[70:73]
	v_mfma_f32_16x16x32_bf16 v[66:69], v[212:215], v[244:247], v[66:69]
	s_setprio 0
	s_barrier
	s_add_i32 s44, s44, s56
	v_lshl_add_u64 v[162:163], s[28:29], 0, v[132:133]
	s_mov_b32 m0, s44
	ds_read_b128 v[216:219], v184 offset:16384
	global_load_lds_dwordx4 v[162:163], off
	ds_read_b128 v[220:223], v184 offset:17408
	ds_read_b128 v[224:227], v184 offset:18432
	ds_read_b128 v[228:231], v184 offset:19456
	s_add_i32 m0, s44, 0x2000
	s_add_u32 s44, s28, 0x8000
	v_lshl_add_u64 v[248:249], s[28:29], 0, v[136:137]
	s_addc_u32 s45, s29, 0
	s_add_i32 s46, s46, s56
	global_load_lds_dwordx4 v[248:249], off
	ds_read_b128 v[232:235], v184 offset:20480
	ds_read_b128 v[236:239], v184 offset:21504
	ds_read_b128 v[240:243], v184 offset:22528
	v_lshl_add_u64 v[172:173], s[44:45], 0, v[132:133]
	s_mov_b32 m0, s46
	v_lshl_add_u64 v[174:175], s[34:35], 0, v[134:135]
	global_load_lds_dwordx4 v[172:173], off
	ds_read_b128 v[244:247], v184 offset:23552
	v_lshl_add_u64 v[172:173], s[44:45], 0, v[136:137]
	s_add_i32 m0, s46, 0x2000
	s_nop 0
	global_load_lds_dwordx4 v[172:173], off
	v_lshl_add_u64 v[172:173], s[34:35], 0, v[130:131]
	s_mov_b32 m0, s57
	s_nop 0
	global_load_lds_dwordx4 v[172:173], off
	s_mov_b32 m0, s58
	s_nop 0
	global_load_lds_dwordx4 v[174:175], off
	s_waitcnt vmcnt(8)
	s_waitcnt lgkmcnt(0)
	s_barrier
; #define PG8_STAGE(bufoff, gbase, voff) do { _Pragma("unroll") for (int _i = 0; _i < 2; ++_i) \
;         __builtin_amdgcn_global_load_lds((const unsigned*)((const char*)(gbase) + (voff)[_i]), (LAS unsigned*)(lds + (bufoff) + ldsw + _i * 8192), 16, 0, 0); } while (0)
; #define PG8_LDA(dst, b, h) do { _Pragma("unroll") for (int m = 0; m < 4; ++m) _Pragma("unroll") for (int k = 0; k < 2; ++k) dst[m][k] = *(const LAS bf16x8*)(lds + PG8_SA(b, h) + aoff + m * 2048 + k * 1024); } while (0)
; #define PG8_LDB(dst, b, h) do { _Pragma("unroll") for (int n = 0; n < 2; ++n) _Pragma("unroll") for (int k = 0; k < 2; ++k) dst[n][k] = *(const LAS bf16x8*)(lds + PG8_SB(b, h) + boff + n * 2048 + k * 1024); } while (0)
; #define PG8_MMA(ai, bj, At, Bt) do { __builtin_amdgcn_s_setprio(1); _Pragma("unroll") for (int m = 0; m < 4; ++m) _Pragma("unroll") for (int n = 0; n < 2; ++n) _Pragma("unroll") for (int k = 0; k < 2; ++k) \
;         acc[ai][bj][m][n] = __builtin_amdgcn_mfma_f32_16x16x32_bf16(Bt[n][k], At[m][k], acc[ai][bj][m][n], 0, 0, 0); __builtin_amdgcn_s_setprio(0); } while (0)
; #define PG8_WAIT_V(n) asm volatile("s_waitcnt vmcnt(" #n ")" ::: "memory")
; #define PG8_WAIT_L(n) asm volatile("s_waitcnt lgkmcnt(" #n ")" ::: "memory")
; #define PG8_BAR __builtin_amdgcn_s_barrier()
; #define PG8_SCHED __builtin_amdgcn_sched_barrier(0)
; template <class Epi>
; __device__ __forceinline__ void gemm_phase(LAS unsigned char* lds, const Gemm g, const StaticOrder& S, const Epi& E, const int tid) {
;     ...
;             PG8_WAIT_V(8); PG8_WAIT_L(0); PG8_BAR; PG8_MMA(1, 0, At, B0); PG8_MMA(1, 1, At, B1); PG8_BAR; PG8_SCHED;
;             PG8_LDB(B0, 1, 0); PG8_LDB(B1, 1, 1); PG8_SCHED; PG8_LDA(At, 1, 0); PG8_STAGE(PG8_SA(0, 1), a2 + hstep, voffA);
;             PG8_WAIT_V(8); PG8_WAIT_L(0); PG8_BAR; PG8_MMA(0, 0, At, B0); PG8_MMA(0, 1, At, B1); PG8_BAR; PG8_SCHED;
	s_setprio 1
	s_waitcnt lgkmcnt(0)
	v_mfma_f32_16x16x32_bf16 v[62:65], v[150:153], v[216:219], v[62:65]
	v_mfma_f32_16x16x32_bf16 v[58:61], v[158:161], v[216:219], v[58:61]
	v_mfma_f32_16x16x32_bf16 v[46:49], v[150:153], v[224:227], v[46:49]
	v_mfma_f32_16x16x32_bf16 v[42:45], v[158:161], v[224:227], v[42:45]
	v_mfma_f32_16x16x32_bf16 v[30:33], v[150:153], v[232:235], v[30:33]
	v_mfma_f32_16x16x32_bf16 v[26:29], v[158:161], v[232:235], v[26:29]
	v_mfma_f32_16x16x32_bf16 v[14:17], v[150:153], v[240:243], v[14:17]
	v_mfma_f32_16x16x32_bf16 v[10:13], v[158:161], v[240:243], v[10:13]
	v_mfma_f32_16x16x32_bf16 v[62:65], v[154:157], v[220:223], v[62:65]
	v_mfma_f32_16x16x32_bf16 v[58:61], v[186:189], v[220:223], v[58:61]
	v_mfma_f32_16x16x32_bf16 v[46:49], v[154:157], v[228:231], v[46:49]
	v_mfma_f32_16x16x32_bf16 v[42:45], v[186:189], v[228:231], v[42:45]
	v_mfma_f32_16x16x32_bf16 v[30:33], v[154:157], v[236:239], v[30:33]
	v_mfma_f32_16x16x32_bf16 v[26:29], v[186:189], v[236:239], v[26:29]
	v_mfma_f32_16x16x32_bf16 v[14:17], v[154:157], v[244:247], v[14:17]
	v_mfma_f32_16x16x32_bf16 v[10:13], v[186:189], v[244:247], v[10:13]
	s_setprio 0
	s_setprio 1
	v_mfma_f32_16x16x32_bf16 v[54:57], v[190:193], v[216:219], v[54:57]
	v_mfma_f32_16x16x32_bf16 v[50:53], v[198:201], v[216:219], v[50:53]
	v_mfma_f32_16x16x32_bf16 v[38:41], v[190:193], v[224:227], v[38:41]
	v_mfma_f32_16x16x32_bf16 v[34:37], v[198:201], v[224:227], v[34:37]
	v_mfma_f32_16x16x32_bf16 v[22:25], v[190:193], v[232:235], v[22:25]
	v_mfma_f32_16x16x32_bf16 v[18:21], v[198:201], v[232:235], v[18:21]
	v_mfma_f32_16x16x32_bf16 v[6:9], v[190:193], v[240:243], v[6:9]
	v_mfma_f32_16x16x32_bf16 v[2:5], v[198:201], v[240:243], v[2:5]
	v_mfma_f32_16x16x32_bf16 v[54:57], v[194:197], v[220:223], v[54:57]
	v_mfma_f32_16x16x32_bf16 v[50:53], v[212:215], v[220:223], v[50:53]
	v_mfma_f32_16x16x32_bf16 v[38:41], v[194:197], v[228:231], v[38:41]
	v_mfma_f32_16x16x32_bf16 v[34:37], v[212:215], v[228:231], v[34:37]
	v_mfma_f32_16x16x32_bf16 v[22:25], v[194:197], v[236:239], v[22:25]
	v_mfma_f32_16x16x32_bf16 v[18:21], v[212:215], v[236:239], v[18:21]
	v_mfma_f32_16x16x32_bf16 v[6:9], v[194:197], v[244:247], v[6:9]
	v_mfma_f32_16x16x32_bf16 v[2:5], v[212:215], v[244:247], v[2:5]
	s_setprio 0
	s_barrier
	s_add_i32 s44, 0, 0x18000
	v_add_u32_e32 v0, s44, v149
	s_add_i32 s45, 0, 0x1c000
	ds_read_b128 v[150:153], v0
	ds_read_b128 v[154:157], v0 offset:1024
	ds_read_b128 v[158:161], v0 offset:2048
	ds_read_b128 v[186:189], v0 offset:3072
	v_add_u32_e32 v0, s45, v149
	ds_read_b128 v[190:193], v0
	ds_read_b128 v[194:197], v0 offset:1024
	ds_read_b128 v[198:201], v0 offset:2048
	ds_read_b128 v[212:215], v0 offset:3072
	s_add_u32 s34, s34, 0x80000
	s_addc_u32 s35, s35, 0
	s_mov_b32 m0, s59
	v_lshl_add_u64 v[176:177], s[34:35], 0, v[130:131]
	ds_read_b128 v[216:219], v184 offset:32768
	global_load_lds_dwordx4 v[176:177], off
	ds_read_b128 v[220:223], v184 offset:33792
	ds_read_b128 v[224:227], v184 offset:34816
	ds_read_b128 v[228:231], v184 offset:35840
	v_lshl_add_u64 v[176:177], s[34:35], 0, v[134:135]
	s_mov_b32 m0, s60
	s_nop 0
	global_load_lds_dwordx4 v[176:177], off
	ds_read_b128 v[232:235], v184 offset:36864
	ds_read_b128 v[236:239], v184 offset:37888
	ds_read_b128 v[240:243], v184 offset:38912
	ds_read_b128 v[244:247], v184 offset:39936
	s_waitcnt vmcnt(8)
	s_waitcnt lgkmcnt(0)
	s_barrier
	s_setprio 1
	s_waitcnt lgkmcnt(0)
	v_mfma_f32_16x16x32_bf16 v[126:129], v[150:153], v[216:219], v[126:129]
	v_mfma_f32_16x16x32_bf16 v[122:125], v[158:161], v[216:219], v[122:125]
	v_mfma_f32_16x16x32_bf16 v[110:113], v[150:153], v[224:227], v[110:113]
	v_mfma_f32_16x16x32_bf16 v[106:109], v[158:161], v[224:227], v[106:109]
	v_mfma_f32_16x16x32_bf16 v[94:97], v[150:153], v[232:235], v[94:97]
	v_mfma_f32_16x16x32_bf16 v[90:93], v[158:161], v[232:235], v[90:93]
	v_mfma_f32_16x16x32_bf16 v[78:81], v[150:153], v[240:243], v[78:81]
	v_mfma_f32_16x16x32_bf16 v[74:77], v[158:161], v[240:243], v[74:77]
	v_mfma_f32_16x16x32_bf16 v[126:129], v[154:157], v[220:223], v[126:129]
	v_mfma_f32_16x16x32_bf16 v[122:125], v[186:189], v[220:223], v[122:125]
	v_mfma_f32_16x16x32_bf16 v[110:113], v[154:157], v[228:231], v[110:113]
	v_mfma_f32_16x16x32_bf16 v[106:109], v[186:189], v[228:231], v[106:109]
	v_mfma_f32_16x16x32_bf16 v[94:97], v[154:157], v[236:239], v[94:97]
	v_mfma_f32_16x16x32_bf16 v[90:93], v[186:189], v[236:239], v[90:93]
	v_mfma_f32_16x16x32_bf16 v[78:81], v[154:157], v[244:247], v[78:81]
	v_mfma_f32_16x16x32_bf16 v[74:77], v[186:189], v[244:247], v[74:77]
	s_setprio 0
	s_setprio 1
	v_mfma_f32_16x16x32_bf16 v[118:121], v[190:193], v[216:219], v[118:121]
	v_mfma_f32_16x16x32_bf16 v[114:117], v[198:201], v[216:219], v[114:117]
	v_mfma_f32_16x16x32_bf16 v[102:105], v[190:193], v[224:227], v[102:105]
	v_mfma_f32_16x16x32_bf16 v[98:101], v[198:201], v[224:227], v[98:101]
	v_mfma_f32_16x16x32_bf16 v[86:89], v[190:193], v[232:235], v[86:89]
	v_mfma_f32_16x16x32_bf16 v[82:85], v[198:201], v[232:235], v[82:85]
	v_mfma_f32_16x16x32_bf16 v[70:73], v[190:193], v[240:243], v[70:73]
	v_mfma_f32_16x16x32_bf16 v[66:69], v[198:201], v[240:243], v[66:69]
	v_mfma_f32_16x16x32_bf16 v[118:121], v[194:197], v[220:223], v[118:121]
	v_mfma_f32_16x16x32_bf16 v[114:117], v[212:215], v[220:223], v[114:117]
	v_mfma_f32_16x16x32_bf16 v[102:105], v[194:197], v[228:231], v[102:105]
	v_mfma_f32_16x16x32_bf16 v[98:101], v[212:215], v[228:231], v[98:101]
	v_mfma_f32_16x16x32_bf16 v[86:89], v[194:197], v[236:239], v[86:89]
	v_mfma_f32_16x16x32_bf16 v[82:85], v[212:215], v[236:239], v[82:85]
	v_mfma_f32_16x16x32_bf16 v[70:73], v[194:197], v[244:247], v[70:73]
	v_mfma_f32_16x16x32_bf16 v[66:69], v[212:215], v[244:247], v[66:69]
	s_setprio 0
	s_barrier
; #define PG8_STAGE(bufoff, gbase, voff) do { _Pragma("unroll") for (int _i = 0; _i < 2; ++_i) \
;         __builtin_amdgcn_global_load_lds((const unsigned*)((const char*)(gbase) + (voff)[_i]), (LAS unsigned*)(lds + (bufoff) + ldsw + _i * 8192), 16, 0, 0); } while (0)
; #define PG8_LDA(dst, b, h) do { _Pragma("unroll") for (int m = 0; m < 4; ++m) _Pragma("unroll") for (int k = 0; k < 2; ++k) dst[m][k] = *(const LAS bf16x8*)(lds + PG8_SA(b, h) + aoff + m * 2048 + k * 1024); } while (0)
; #define PG8_MMA(ai, bj, At, Bt) do { __builtin_amdgcn_s_setprio(1); _Pragma("unroll") for (int m = 0; m < 4; ++m) _Pragma("unroll") for (int n = 0; n < 2; ++n) _Pragma("unroll") for (int k = 0; k < 2; ++k) \
;         acc[ai][bj][m][n] = __builtin_amdgcn_mfma_f32_16x16x32_bf16(Bt[n][k], At[m][k], acc[ai][bj][m][n], 0, 0, 0); __builtin_amdgcn_s_setprio(0); } while (0)
; #define PG8_WAIT_V(n) asm volatile("s_waitcnt vmcnt(" #n ")" ::: "memory")
; #define PG8_WAIT_L(n) asm volatile("s_waitcnt lgkmcnt(" #n ")" ::: "memory")
; #define PG8_BAR __builtin_amdgcn_s_barrier()
; #define PG8_SCHED __builtin_amdgcn_sched_barrier(0)
; template <class Epi>
; __device__ __forceinline__ void gemm_phase(LAS unsigned char* lds, const Gemm g, const StaticOrder& S, const Epi& E, const int tid) {
;     ...
;             PG8_LDA(At, 1, 1); PG8_STAGE(PG8_SB(1, 0), b3, voffB); PG8_STAGE(PG8_SB(1, 1), b3 + bhs, voffB); PG8_STAGE(PG8_SA(1, 0), a3, voffA);
;             PG8_WAIT_V(8); PG8_WAIT_L(0); PG8_BAR; PG8_MMA(1, 0, At, B0); PG8_MMA(1, 1, At, B1); PG8_BAR; PG8_SCHED;
	s_add_i32 s34, s44, s56
	v_lshl_add_u64 v[162:163], v[162:163], 0, s[70:71]
	s_mov_b32 m0, s34
	ds_read_b128 v[216:219], v184 offset:49152
	global_load_lds_dwordx4 v[162:163], off
	ds_read_b128 v[220:223], v184 offset:50176
	ds_read_b128 v[224:227], v184 offset:51200
	ds_read_b128 v[228:231], v184 offset:52224
	s_add_i32 m0, s34, 0x2000
	s_add_u32 s28, s28, 0x8080
	v_lshl_add_u64 v[162:163], v[248:249], 0, s[70:71]
	s_addc_u32 s29, s29, 0
	s_add_i32 s34, s45, s56
	global_load_lds_dwordx4 v[162:163], off
	ds_read_b128 v[232:235], v184 offset:53248
	ds_read_b128 v[236:239], v184 offset:54272
	ds_read_b128 v[240:243], v184 offset:55296
	v_lshl_add_u64 v[162:163], s[28:29], 0, v[132:133]
	s_mov_b32 m0, s34
	s_nop 0
	global_load_lds_dwordx4 v[162:163], off
	ds_read_b128 v[244:247], v184 offset:56320
	v_lshl_add_u64 v[162:163], s[28:29], 0, v[136:137]
	s_add_i32 m0, s34, 0x2000
	s_nop 0
	global_load_lds_dwordx4 v[162:163], off
	v_lshl_add_u64 v[162:163], v[172:173], 0, s[70:71]
	s_mov_b32 m0, s61
	s_nop 0
	global_load_lds_dwordx4 v[162:163], off
	v_lshl_add_u64 v[162:163], v[174:175], 0, s[70:71]
	s_mov_b32 m0, s62
	s_nop 0
	global_load_lds_dwordx4 v[162:163], off
	s_waitcnt vmcnt(8)
	s_waitcnt lgkmcnt(0)
	s_barrier
	s_setprio 1
	s_waitcnt lgkmcnt(0)
	v_mfma_f32_16x16x32_bf16 v[62:65], v[150:153], v[216:219], v[62:65]
	v_mfma_f32_16x16x32_bf16 v[58:61], v[158:161], v[216:219], v[58:61]
	v_mfma_f32_16x16x32_bf16 v[46:49], v[150:153], v[224:227], v[46:49]
	v_mfma_f32_16x16x32_bf16 v[42:45], v[158:161], v[224:227], v[42:45]
	v_mfma_f32_16x16x32_bf16 v[30:33], v[150:153], v[232:235], v[30:33]
	v_mfma_f32_16x16x32_bf16 v[26:29], v[158:161], v[232:235], v[26:29]
	v_mfma_f32_16x16x32_bf16 v[14:17], v[150:153], v[240:243], v[14:17]
	v_mfma_f32_16x16x32_bf16 v[10:13], v[158:161], v[240:243], v[10:13]
	v_mfma_f32_16x16x32_bf16 v[62:65], v[154:157], v[220:223], v[62:65]
	v_mfma_f32_16x16x32_bf16 v[58:61], v[186:189], v[220:223], v[58:61]
	v_mfma_f32_16x16x32_bf16 v[46:49], v[154:157], v[228:231], v[46:49]
	v_mfma_f32_16x16x32_bf16 v[42:45], v[186:189], v[228:231], v[42:45]
	v_mfma_f32_16x16x32_bf16 v[30:33], v[154:157], v[236:239], v[30:33]
	v_mfma_f32_16x16x32_bf16 v[26:29], v[186:189], v[236:239], v[26:29]
	v_mfma_f32_16x16x32_bf16 v[14:17], v[154:157], v[244:247], v[14:17]
	v_mfma_f32_16x16x32_bf16 v[10:13], v[186:189], v[244:247], v[10:13]
	s_setprio 0
	s_setprio 1
	v_mfma_f32_16x16x32_bf16 v[54:57], v[190:193], v[216:219], v[54:57]
	v_mfma_f32_16x16x32_bf16 v[50:53], v[198:201], v[216:219], v[50:53]
	v_mfma_f32_16x16x32_bf16 v[38:41], v[190:193], v[224:227], v[38:41]
	v_mfma_f32_16x16x32_bf16 v[34:37], v[198:201], v[224:227], v[34:37]
	v_mfma_f32_16x16x32_bf16 v[22:25], v[190:193], v[232:235], v[22:25]
	v_mfma_f32_16x16x32_bf16 v[18:21], v[198:201], v[232:235], v[18:21]
	v_mfma_f32_16x16x32_bf16 v[6:9], v[190:193], v[240:243], v[6:9]
	v_mfma_f32_16x16x32_bf16 v[2:5], v[198:201], v[240:243], v[2:5]
	v_mfma_f32_16x16x32_bf16 v[54:57], v[194:197], v[220:223], v[54:57]
	v_mfma_f32_16x16x32_bf16 v[50:53], v[212:215], v[220:223], v[50:53]
	v_mfma_f32_16x16x32_bf16 v[38:41], v[194:197], v[228:231], v[38:41]
	v_mfma_f32_16x16x32_bf16 v[34:37], v[212:215], v[228:231], v[34:37]
	v_mfma_f32_16x16x32_bf16 v[22:25], v[194:197], v[236:239], v[22:25]
	v_mfma_f32_16x16x32_bf16 v[18:21], v[212:215], v[236:239], v[18:21]
	v_mfma_f32_16x16x32_bf16 v[6:9], v[194:197], v[244:247], v[6:9]
	v_mfma_f32_16x16x32_bf16 v[2:5], v[212:215], v[244:247], v[2:5]
	s_setprio 0
	s_barrier
	s_add_i32 s39, s39, 2
	s_add_u32 s37, s37, 0x100
	s_addc_u32 s38, s38, 0
	s_add_u32 s26, s26, 0x100
	s_addc_u32 s27, s27, 0
	s_cmp_gt_u32 s39, 29
	s_cbranch_scc0 .LBB0_546
	s_and_b64 vcc, exec, s[14:15]
	s_cbranch_vccz .LBB0_549
	s_barrier

; #define PG8_STAGE(bufoff, gbase, voff) do { _Pragma("unroll") for (int _i = 0; _i < 2; ++_i) \
;         __builtin_amdgcn_global_load_lds((const unsigned*)((const char*)(gbase) + (voff)[_i]), (LAS unsigned*)(lds + (bufoff) + ldsw + _i * 8192), 16, 0, 0); } while (0)
; #define PG8_LDA(dst, b, h) do { _Pragma("unroll") for (int m = 0; m < 4; ++m) _Pragma("unroll") for (int k = 0; k < 2; ++k) dst[m][k] = *(const LAS bf16x8*)(lds + PG8_SA(b, h) + aoff + m * 2048 + k * 1024); } while (0)
; #define PG8_LDB(dst, b, h) do { _Pragma("unroll") for (int n = 0; n < 2; ++n) _Pragma("unroll") for (int k = 0; k < 2; ++k) dst[n][k] = *(const LAS bf16x8*)(lds + PG8_SB(b, h) + boff + n * 2048 + k * 1024); } while (0)
; #define PG8_MMA(ai, bj, At, Bt) do { __builtin_amdgcn_s_setprio(1); _Pragma("unroll") for (int m = 0; m < 4; ++m) _Pragma("unroll") for (int n = 0; n < 2; ++n) _Pragma("unroll") for (int k = 0; k < 2; ++k) \
;         acc[ai][bj][m][n] = __builtin_amdgcn_mfma_f32_16x16x32_bf16(Bt[n][k], At[m][k], acc[ai][bj][m][n], 0, 0, 0); __builtin_amdgcn_s_setprio(0); } while (0)
; #define PG8_WAIT_V(n) asm volatile("s_waitcnt vmcnt(" #n ")" ::: "memory")
; #define PG8_WAIT_L(n) asm volatile("s_waitcnt lgkmcnt(" #n ")" ::: "memory")
; #define PG8_BAR __builtin_amdgcn_s_barrier()
; #define PG8_SCHED __builtin_amdgcn_sched_barrier(0)
; template <class Epi>
; __device__ __forceinline__ void gemm_phase(LAS unsigned char* lds, const Gemm g, const StaticOrder& S, const Epi& E, const int tid) {
;     ...
;             PG8_LDB(B0, 0, 0); PG8_LDB(B1, 0, 1); PG8_SCHED; PG8_LDA(At, 0, 0); PG8_STAGE(PG8_SA(1, 1), a1 + hstep, voffA);
;             PG8_WAIT_V(8); PG8_WAIT_L(0); PG8_BAR; PG8_MMA(0, 0, At, B0); PG8_MMA(0, 1, At, B1); PG8_BAR; PG8_SCHED;
;             PG8_LDA(At, 0, 1); PG8_STAGE(PG8_SB(0, 0), b2, voffB); PG8_STAGE(PG8_SB(0, 1), b2 + bhs, voffB); PG8_STAGE(PG8_SA(0, 0), a2, voffA);
;             PG8_WAIT_V(8); PG8_WAIT_L(0); PG8_BAR; PG8_MMA(1, 0, At, B0); PG8_MMA(1, 1, At, B1); PG8_BAR; PG8_SCHED;
.LBB0_844:
	s_add_u32 s28, s26, 0xfff80080
	s_addc_u32 s29, s27, -1
	s_add_i32 s48, 0, 0x10000
	s_cmp_eq_u32 s47, 28
	s_cselect_b32 s31, s15, s29
	s_cselect_b32 s30, s43, s28
	v_add_u32_e32 v145, s48, v142
	s_cselect_b32 s29, s13, s46
	s_cselect_b32 s28, s44, s45
	s_add_i32 s50, 0, 0x14000
	ds_read_b128 v[146:149], v145
	ds_read_b128 v[150:153], v145 offset:1024
	ds_read_b128 v[154:157], v145 offset:2048
	ds_read_b128 v[158:161], v145 offset:3072
	v_add_u32_e32 v145, s50, v142
	ds_read_b128 v[162:165], v145
	ds_read_b128 v[166:169], v145 offset:1024
	ds_read_b128 v[178:181], v145 offset:2048
	ds_read_b128 v[182:185], v145 offset:3072
	v_lshl_add_u64 v[172:173], s[26:27], 0, v[138:139]
	s_add_i32 m0, s23, 0xc000
	ds_read_b128 v[186:189], v144
	global_load_lds_dwordx4 v[172:173], off
	ds_read_b128 v[190:193], v144 offset:1024
	ds_read_b128 v[194:197], v144 offset:2048
	ds_read_b128 v[198:201], v144 offset:3072
	v_lshl_add_u64 v[172:173], s[26:27], 0, v[136:137]
	s_add_i32 m0, s23, 0xe000
	s_nop 0
	global_load_lds_dwordx4 v[172:173], off
	ds_read_b128 v[212:215], v144 offset:4096
	ds_read_b128 v[216:219], v144 offset:5120
	ds_read_b128 v[220:223], v144 offset:6144
	ds_read_b128 v[224:227], v144 offset:7168
	s_waitcnt vmcnt(8)
	s_waitcnt lgkmcnt(0)
	s_barrier
	s_setprio 1
	s_waitcnt lgkmcnt(0)
	v_mfma_f32_16x16x32_bf16 v[126:129], v[146:149], v[186:189], v[126:129]
	v_mfma_f32_16x16x32_bf16 v[122:125], v[154:157], v[186:189], v[122:125]
	v_mfma_f32_16x16x32_bf16 v[118:121], v[146:149], v[194:197], v[118:121]
	v_mfma_f32_16x16x32_bf16 v[110:113], v[154:157], v[194:197], v[110:113]
	v_mfma_f32_16x16x32_bf16 v[102:105], v[146:149], v[212:215], v[102:105]
	v_mfma_f32_16x16x32_bf16 v[94:97], v[154:157], v[212:215], v[94:97]
	v_mfma_f32_16x16x32_bf16 v[86:89], v[146:149], v[220:223], v[86:89]
	v_mfma_f32_16x16x32_bf16 v[78:81], v[154:157], v[220:223], v[78:81]
	v_mfma_f32_16x16x32_bf16 v[126:129], v[150:153], v[190:193], v[126:129]
	v_mfma_f32_16x16x32_bf16 v[122:125], v[158:161], v[190:193], v[122:125]
	v_mfma_f32_16x16x32_bf16 v[118:121], v[150:153], v[198:201], v[118:121]
	v_mfma_f32_16x16x32_bf16 v[110:113], v[158:161], v[198:201], v[110:113]
	v_mfma_f32_16x16x32_bf16 v[102:105], v[150:153], v[216:219], v[102:105]
	v_mfma_f32_16x16x32_bf16 v[94:97], v[158:161], v[216:219], v[94:97]
	v_mfma_f32_16x16x32_bf16 v[86:89], v[150:153], v[224:227], v[86:89]
	v_mfma_f32_16x16x32_bf16 v[78:81], v[158:161], v[224:227], v[78:81]
	s_setprio 0
	s_setprio 1
	v_mfma_f32_16x16x32_bf16 v[114:117], v[162:165], v[186:189], v[114:117]
	v_mfma_f32_16x16x32_bf16 v[106:109], v[178:181], v[186:189], v[106:109]
	v_mfma_f32_16x16x32_bf16 v[98:101], v[162:165], v[194:197], v[98:101]
	v_mfma_f32_16x16x32_bf16 v[90:93], v[178:181], v[194:197], v[90:93]
	v_mfma_f32_16x16x32_bf16 v[82:85], v[162:165], v[212:215], v[82:85]
	v_mfma_f32_16x16x32_bf16 v[74:77], v[178:181], v[212:215], v[74:77]
	v_mfma_f32_16x16x32_bf16 v[70:73], v[162:165], v[220:223], v[70:73]
	v_mfma_f32_16x16x32_bf16 v[66:69], v[178:181], v[220:223], v[66:69]
	v_mfma_f32_16x16x32_bf16 v[114:117], v[166:169], v[190:193], v[114:117]
	v_mfma_f32_16x16x32_bf16 v[106:109], v[182:185], v[190:193], v[106:109]
	v_mfma_f32_16x16x32_bf16 v[98:101], v[166:169], v[198:201], v[98:101]
	v_mfma_f32_16x16x32_bf16 v[90:93], v[182:185], v[198:201], v[90:93]
	v_mfma_f32_16x16x32_bf16 v[82:85], v[166:169], v[216:219], v[82:85]
	v_mfma_f32_16x16x32_bf16 v[74:77], v[182:185], v[216:219], v[74:77]
	v_mfma_f32_16x16x32_bf16 v[70:73], v[166:169], v[224:227], v[70:73]
	v_mfma_f32_16x16x32_bf16 v[66:69], v[182:185], v[224:227], v[66:69]
	s_setprio 0
	s_barrier
	s_add_i32 s48, s48, s37
	v_lshl_add_u64 v[172:173], s[28:29], 0, v[0:1]
	s_mov_b32 m0, s48
	ds_read_b128 v[186:189], v144 offset:16384
	global_load_lds_dwordx4 v[172:173], off
	ds_read_b128 v[190:193], v144 offset:17408
	ds_read_b128 v[194:197], v144 offset:18432
	ds_read_b128 v[198:201], v144 offset:19456
	s_add_i32 m0, s48, 0x2000
	s_add_u32 s48, s28, 0x8000
	v_lshl_add_u64 v[174:175], s[28:29], 0, v[134:135]
	s_addc_u32 s49, s29, 0
	s_add_i32 s50, s50, s37
	global_load_lds_dwordx4 v[174:175], off
	ds_read_b128 v[212:215], v144 offset:20480
	ds_read_b128 v[216:219], v144 offset:21504
	ds_read_b128 v[220:223], v144 offset:22528
	v_lshl_add_u64 v[176:177], s[48:49], 0, v[0:1]
	s_mov_b32 m0, s50
	v_lshl_add_u64 v[228:229], s[30:31], 0, v[132:133]
	global_load_lds_dwordx4 v[176:177], off
	ds_read_b128 v[224:227], v144 offset:23552
	v_lshl_add_u64 v[176:177], s[48:49], 0, v[134:135]
	s_add_i32 m0, s50, 0x2000
	s_nop 0
	global_load_lds_dwordx4 v[176:177], off
	v_lshl_add_u64 v[176:177], s[30:31], 0, v[130:131]
	s_mov_b32 m0, s23
	s_nop 0
	global_load_lds_dwordx4 v[176:177], off
	s_mov_b32 m0, s25
	s_nop 0
	global_load_lds_dwordx4 v[228:229], off
	s_waitcnt vmcnt(8)
	s_waitcnt lgkmcnt(0)
	s_barrier
; #define PG8_STAGE(bufoff, gbase, voff) do { _Pragma("unroll") for (int _i = 0; _i < 2; ++_i) \
;         __builtin_amdgcn_global_load_lds((const unsigned*)((const char*)(gbase) + (voff)[_i]), (LAS unsigned*)(lds + (bufoff) + ldsw + _i * 8192), 16, 0, 0); } while (0)
; #define PG8_LDA(dst, b, h) do { _Pragma("unroll") for (int m = 0; m < 4; ++m) _Pragma("unroll") for (int k = 0; k < 2; ++k) dst[m][k] = *(const LAS bf16x8*)(lds + PG8_SA(b, h) + aoff + m * 2048 + k * 1024); } while (0)
; #define PG8_LDB(dst, b, h) do { _Pragma("unroll") for (int n = 0; n < 2; ++n) _Pragma("unroll") for (int k = 0; k < 2; ++k) dst[n][k] = *(const LAS bf16x8*)(lds + PG8_SB(b, h) + boff + n * 2048 + k * 1024); } while (0)
; #define PG8_MMA(ai, bj, At, Bt) do { __builtin_amdgcn_s_setprio(1); _Pragma("unroll") for (int m = 0; m < 4; ++m) _Pragma("unroll") for (int n = 0; n < 2; ++n) _Pragma("unroll") for (int k = 0; k < 2; ++k) \
;         acc[ai][bj][m][n] = __builtin_amdgcn_mfma_f32_16x16x32_bf16(Bt[n][k], At[m][k], acc[ai][bj][m][n], 0, 0, 0); __builtin_amdgcn_s_setprio(0); } while (0)
; #define PG8_WAIT_V(n) asm volatile("s_waitcnt vmcnt(" #n ")" ::: "memory")
; #define PG8_WAIT_L(n) asm volatile("s_waitcnt lgkmcnt(" #n ")" ::: "memory")
; #define PG8_BAR __builtin_amdgcn_s_barrier()
; #define PG8_SCHED __builtin_amdgcn_sched_barrier(0)
; template <class Epi>
; __device__ __forceinline__ void gemm_phase(LAS unsigned char* lds, const Gemm g, const StaticOrder& S, const Epi& E, const int tid) {
;     ...
;             PG8_WAIT_V(8); PG8_WAIT_L(0); PG8_BAR; PG8_MMA(1, 0, At, B0); PG8_MMA(1, 1, At, B1); PG8_BAR; PG8_SCHED;
;             PG8_LDB(B0, 1, 0); PG8_LDB(B1, 1, 1); PG8_SCHED; PG8_LDA(At, 1, 0); PG8_STAGE(PG8_SA(0, 1), a2 + hstep, voffA);
;             PG8_WAIT_V(8); PG8_WAIT_L(0); PG8_BAR; PG8_MMA(0, 0, At, B0); PG8_MMA(0, 1, At, B1); PG8_BAR; PG8_SCHED;
	s_setprio 1
	s_waitcnt lgkmcnt(0)
	v_mfma_f32_16x16x32_bf16 v[62:65], v[146:149], v[186:189], v[62:65]
	v_mfma_f32_16x16x32_bf16 v[58:61], v[154:157], v[186:189], v[58:61]
	v_mfma_f32_16x16x32_bf16 v[54:57], v[146:149], v[194:197], v[54:57]
	v_mfma_f32_16x16x32_bf16 v[46:49], v[154:157], v[194:197], v[46:49]
	v_mfma_f32_16x16x32_bf16 v[38:41], v[146:149], v[212:215], v[38:41]
	v_mfma_f32_16x16x32_bf16 v[30:33], v[154:157], v[212:215], v[30:33]
	v_mfma_f32_16x16x32_bf16 v[22:25], v[146:149], v[220:223], v[22:25]
	v_mfma_f32_16x16x32_bf16 v[14:17], v[154:157], v[220:223], v[14:17]
	v_mfma_f32_16x16x32_bf16 v[62:65], v[150:153], v[190:193], v[62:65]
	v_mfma_f32_16x16x32_bf16 v[58:61], v[158:161], v[190:193], v[58:61]
	v_mfma_f32_16x16x32_bf16 v[54:57], v[150:153], v[198:201], v[54:57]
	v_mfma_f32_16x16x32_bf16 v[46:49], v[158:161], v[198:201], v[46:49]
	v_mfma_f32_16x16x32_bf16 v[38:41], v[150:153], v[216:219], v[38:41]
	v_mfma_f32_16x16x32_bf16 v[30:33], v[158:161], v[216:219], v[30:33]
	v_mfma_f32_16x16x32_bf16 v[22:25], v[150:153], v[224:227], v[22:25]
	v_mfma_f32_16x16x32_bf16 v[14:17], v[158:161], v[224:227], v[14:17]
	s_setprio 0
	s_setprio 1
	v_mfma_f32_16x16x32_bf16 v[50:53], v[162:165], v[186:189], v[50:53]
	v_mfma_f32_16x16x32_bf16 v[42:45], v[178:181], v[186:189], v[42:45]
	v_mfma_f32_16x16x32_bf16 v[34:37], v[162:165], v[194:197], v[34:37]
	v_mfma_f32_16x16x32_bf16 v[26:29], v[178:181], v[194:197], v[26:29]
	v_mfma_f32_16x16x32_bf16 v[18:21], v[162:165], v[212:215], v[18:21]
	v_mfma_f32_16x16x32_bf16 v[10:13], v[178:181], v[212:215], v[10:13]
	v_mfma_f32_16x16x32_bf16 v[6:9], v[162:165], v[220:223], v[6:9]
	v_mfma_f32_16x16x32_bf16 v[2:5], v[178:181], v[220:223], v[2:5]
	v_mfma_f32_16x16x32_bf16 v[50:53], v[166:169], v[190:193], v[50:53]
	v_mfma_f32_16x16x32_bf16 v[42:45], v[182:185], v[190:193], v[42:45]
	v_mfma_f32_16x16x32_bf16 v[34:37], v[166:169], v[198:201], v[34:37]
	v_mfma_f32_16x16x32_bf16 v[26:29], v[182:185], v[198:201], v[26:29]
	v_mfma_f32_16x16x32_bf16 v[18:21], v[166:169], v[216:219], v[18:21]
	v_mfma_f32_16x16x32_bf16 v[10:13], v[182:185], v[216:219], v[10:13]
	v_mfma_f32_16x16x32_bf16 v[6:9], v[166:169], v[224:227], v[6:9]
	v_mfma_f32_16x16x32_bf16 v[2:5], v[182:185], v[224:227], v[2:5]
	s_setprio 0
	s_barrier
	s_add_i32 s48, 0, 0x18000
	v_add_u32_e32 v145, s48, v142
	s_add_i32 s49, 0, 0x1c000
	ds_read_b128 v[146:149], v145
	ds_read_b128 v[150:153], v145 offset:1024
	ds_read_b128 v[154:157], v145 offset:2048
	ds_read_b128 v[158:161], v145 offset:3072
	v_add_u32_e32 v145, s49, v142
	ds_read_b128 v[162:165], v145
	ds_read_b128 v[166:169], v145 offset:1024
	ds_read_b128 v[178:181], v145 offset:2048
	ds_read_b128 v[182:185], v145 offset:3072
	s_add_u32 s30, s30, 0x80000
	s_addc_u32 s31, s31, 0
	s_mov_b32 m0, s38
	v_lshl_add_u64 v[230:231], s[30:31], 0, v[130:131]
	ds_read_b128 v[186:189], v144 offset:32768
	global_load_lds_dwordx4 v[230:231], off
	ds_read_b128 v[190:193], v144 offset:33792
	ds_read_b128 v[194:197], v144 offset:34816
	ds_read_b128 v[198:201], v144 offset:35840
	v_lshl_add_u64 v[230:231], s[30:31], 0, v[132:133]
	s_mov_b32 m0, s39
	s_nop 0
	global_load_lds_dwordx4 v[230:231], off
	ds_read_b128 v[212:215], v144 offset:36864
	ds_read_b128 v[216:219], v144 offset:37888
	ds_read_b128 v[220:223], v144 offset:38912
	ds_read_b128 v[224:227], v144 offset:39936
	s_waitcnt vmcnt(8)
	s_waitcnt lgkmcnt(0)
	s_barrier
	s_setprio 1
	s_waitcnt lgkmcnt(0)
	v_mfma_f32_16x16x32_bf16 v[126:129], v[146:149], v[186:189], v[126:129]
	v_mfma_f32_16x16x32_bf16 v[122:125], v[154:157], v[186:189], v[122:125]
	v_mfma_f32_16x16x32_bf16 v[118:121], v[146:149], v[194:197], v[118:121]
	v_mfma_f32_16x16x32_bf16 v[110:113], v[154:157], v[194:197], v[110:113]
	v_mfma_f32_16x16x32_bf16 v[102:105], v[146:149], v[212:215], v[102:105]
	v_mfma_f32_16x16x32_bf16 v[94:97], v[154:157], v[212:215], v[94:97]
	v_mfma_f32_16x16x32_bf16 v[86:89], v[146:149], v[220:223], v[86:89]
	v_mfma_f32_16x16x32_bf16 v[78:81], v[154:157], v[220:223], v[78:81]
	v_mfma_f32_16x16x32_bf16 v[126:129], v[150:153], v[190:193], v[126:129]
	v_mfma_f32_16x16x32_bf16 v[122:125], v[158:161], v[190:193], v[122:125]
	v_mfma_f32_16x16x32_bf16 v[118:121], v[150:153], v[198:201], v[118:121]
	v_mfma_f32_16x16x32_bf16 v[110:113], v[158:161], v[198:201], v[110:113]
	v_mfma_f32_16x16x32_bf16 v[102:105], v[150:153], v[216:219], v[102:105]
	v_mfma_f32_16x16x32_bf16 v[94:97], v[158:161], v[216:219], v[94:97]
	v_mfma_f32_16x16x32_bf16 v[86:89], v[150:153], v[224:227], v[86:89]
	v_mfma_f32_16x16x32_bf16 v[78:81], v[158:161], v[224:227], v[78:81]
	s_setprio 0
	s_setprio 1
	v_mfma_f32_16x16x32_bf16 v[114:117], v[162:165], v[186:189], v[114:117]
	v_mfma_f32_16x16x32_bf16 v[106:109], v[178:181], v[186:189], v[106:109]
	v_mfma_f32_16x16x32_bf16 v[98:101], v[162:165], v[194:197], v[98:101]
	v_mfma_f32_16x16x32_bf16 v[90:93], v[178:181], v[194:197], v[90:93]
	v_mfma_f32_16x16x32_bf16 v[82:85], v[162:165], v[212:215], v[82:85]
	v_mfma_f32_16x16x32_bf16 v[74:77], v[178:181], v[212:215], v[74:77]
	v_mfma_f32_16x16x32_bf16 v[70:73], v[162:165], v[220:223], v[70:73]
	v_mfma_f32_16x16x32_bf16 v[66:69], v[178:181], v[220:223], v[66:69]
	v_mfma_f32_16x16x32_bf16 v[114:117], v[166:169], v[190:193], v[114:117]
	v_mfma_f32_16x16x32_bf16 v[106:109], v[182:185], v[190:193], v[106:109]
	v_mfma_f32_16x16x32_bf16 v[98:101], v[166:169], v[198:201], v[98:101]
	v_mfma_f32_16x16x32_bf16 v[90:93], v[182:185], v[198:201], v[90:93]
	v_mfma_f32_16x16x32_bf16 v[82:85], v[166:169], v[216:219], v[82:85]
	v_mfma_f32_16x16x32_bf16 v[74:77], v[182:185], v[216:219], v[74:77]
	v_mfma_f32_16x16x32_bf16 v[70:73], v[166:169], v[224:227], v[70:73]
	v_mfma_f32_16x16x32_bf16 v[66:69], v[182:185], v[224:227], v[66:69]
	s_setprio 0
	s_barrier
; #define PG8_STAGE(bufoff, gbase, voff) do { _Pragma("unroll") for (int _i = 0; _i < 2; ++_i) \
;         __builtin_amdgcn_global_load_lds((const unsigned*)((const char*)(gbase) + (voff)[_i]), (LAS unsigned*)(lds + (bufoff) + ldsw + _i * 8192), 16, 0, 0); } while (0)
; #define PG8_LDA(dst, b, h) do { _Pragma("unroll") for (int m = 0; m < 4; ++m) _Pragma("unroll") for (int k = 0; k < 2; ++k) dst[m][k] = *(const LAS bf16x8*)(lds + PG8_SA(b, h) + aoff + m * 2048 + k * 1024); } while (0)
; #define PG8_MMA(ai, bj, At, Bt) do { __builtin_amdgcn_s_setprio(1); _Pragma("unroll") for (int m = 0; m < 4; ++m) _Pragma("unroll") for (int n = 0; n < 2; ++n) _Pragma("unroll") for (int k = 0; k < 2; ++k) \
;         acc[ai][bj][m][n] = __builtin_amdgcn_mfma_f32_16x16x32_bf16(Bt[n][k], At[m][k], acc[ai][bj][m][n], 0, 0, 0); __builtin_amdgcn_s_setprio(0); } while (0)
; #define PG8_WAIT_V(n) asm volatile("s_waitcnt vmcnt(" #n ")" ::: "memory")
; #define PG8_WAIT_L(n) asm volatile("s_waitcnt lgkmcnt(" #n ")" ::: "memory")
; #define PG8_BAR __builtin_amdgcn_s_barrier()
; #define PG8_SCHED __builtin_amdgcn_sched_barrier(0)
; template <class Epi>
; __device__ __forceinline__ void gemm_phase(LAS unsigned char* lds, const Gemm g, const StaticOrder& S, const Epi& E, const int tid) {
;     ...
;             PG8_LDA(At, 1, 1); PG8_STAGE(PG8_SB(1, 0), b3, voffB); PG8_STAGE(PG8_SB(1, 1), b3 + bhs, voffB); PG8_STAGE(PG8_SA(1, 0), a3, voffA);
;             PG8_WAIT_V(8); PG8_WAIT_L(0); PG8_BAR; PG8_MMA(1, 0, At, B0); PG8_MMA(1, 1, At, B1); PG8_BAR; PG8_SCHED;
	s_add_i32 s30, s48, s37
	v_lshl_add_u64 v[172:173], v[172:173], 0, s[70:71]
	s_mov_b32 m0, s30
	ds_read_b128 v[186:189], v144 offset:49152
	global_load_lds_dwordx4 v[172:173], off
	ds_read_b128 v[190:193], v144 offset:50176
	ds_read_b128 v[194:197], v144 offset:51200
	ds_read_b128 v[198:201], v144 offset:52224
	s_add_i32 m0, s30, 0x2000
	s_add_u32 s28, s28, 0x8080
	v_lshl_add_u64 v[172:173], v[174:175], 0, s[70:71]
	s_addc_u32 s29, s29, 0
	s_add_i32 s30, s49, s37
	global_load_lds_dwordx4 v[172:173], off
	ds_read_b128 v[212:215], v144 offset:53248
	ds_read_b128 v[216:219], v144 offset:54272
	ds_read_b128 v[220:223], v144 offset:55296
	v_lshl_add_u64 v[172:173], s[28:29], 0, v[0:1]
	s_mov_b32 m0, s30
	s_nop 0
	global_load_lds_dwordx4 v[172:173], off
	ds_read_b128 v[224:227], v144 offset:56320
	v_lshl_add_u64 v[172:173], s[28:29], 0, v[134:135]
	s_add_i32 m0, s30, 0x2000
	s_nop 0
	global_load_lds_dwordx4 v[172:173], off
	v_lshl_add_u64 v[172:173], v[176:177], 0, s[70:71]
	s_mov_b32 m0, s40
	s_nop 0
	global_load_lds_dwordx4 v[172:173], off
	v_lshl_add_u64 v[172:173], v[228:229], 0, s[70:71]
	s_mov_b32 m0, s41
	s_nop 0
	global_load_lds_dwordx4 v[172:173], off
	s_waitcnt vmcnt(8)
	s_waitcnt lgkmcnt(0)
	s_barrier
	s_setprio 1
	s_waitcnt lgkmcnt(0)
	v_mfma_f32_16x16x32_bf16 v[62:65], v[146:149], v[186:189], v[62:65]
	v_mfma_f32_16x16x32_bf16 v[58:61], v[154:157], v[186:189], v[58:61]
	v_mfma_f32_16x16x32_bf16 v[54:57], v[146:149], v[194:197], v[54:57]
	v_mfma_f32_16x16x32_bf16 v[46:49], v[154:157], v[194:197], v[46:49]
	v_mfma_f32_16x16x32_bf16 v[38:41], v[146:149], v[212:215], v[38:41]
	v_mfma_f32_16x16x32_bf16 v[30:33], v[154:157], v[212:215], v[30:33]
	v_mfma_f32_16x16x32_bf16 v[22:25], v[146:149], v[220:223], v[22:25]
	v_mfma_f32_16x16x32_bf16 v[14:17], v[154:157], v[220:223], v[14:17]
	v_mfma_f32_16x16x32_bf16 v[62:65], v[150:153], v[190:193], v[62:65]
	v_mfma_f32_16x16x32_bf16 v[58:61], v[158:161], v[190:193], v[58:61]
	v_mfma_f32_16x16x32_bf16 v[54:57], v[150:153], v[198:201], v[54:57]
	v_mfma_f32_16x16x32_bf16 v[46:49], v[158:161], v[198:201], v[46:49]
	v_mfma_f32_16x16x32_bf16 v[38:41], v[150:153], v[216:219], v[38:41]
	v_mfma_f32_16x16x32_bf16 v[30:33], v[158:161], v[216:219], v[30:33]
	v_mfma_f32_16x16x32_bf16 v[22:25], v[150:153], v[224:227], v[22:25]
	v_mfma_f32_16x16x32_bf16 v[14:17], v[158:161], v[224:227], v[14:17]
	s_setprio 0
	s_setprio 1
	v_mfma_f32_16x16x32_bf16 v[50:53], v[162:165], v[186:189], v[50:53]
	v_mfma_f32_16x16x32_bf16 v[42:45], v[178:181], v[186:189], v[42:45]
	v_mfma_f32_16x16x32_bf16 v[34:37], v[162:165], v[194:197], v[34:37]
	v_mfma_f32_16x16x32_bf16 v[26:29], v[178:181], v[194:197], v[26:29]
	v_mfma_f32_16x16x32_bf16 v[18:21], v[162:165], v[212:215], v[18:21]
	v_mfma_f32_16x16x32_bf16 v[10:13], v[178:181], v[212:215], v[10:13]
	v_mfma_f32_16x16x32_bf16 v[6:9], v[162:165], v[220:223], v[6:9]
	v_mfma_f32_16x16x32_bf16 v[2:5], v[178:181], v[220:223], v[2:5]
	v_mfma_f32_16x16x32_bf16 v[50:53], v[166:169], v[190:193], v[50:53]
	v_mfma_f32_16x16x32_bf16 v[42:45], v[182:185], v[190:193], v[42:45]
	v_mfma_f32_16x16x32_bf16 v[34:37], v[166:169], v[198:201], v[34:37]
	v_mfma_f32_16x16x32_bf16 v[26:29], v[182:185], v[198:201], v[26:29]
	v_mfma_f32_16x16x32_bf16 v[18:21], v[166:169], v[216:219], v[18:21]
	v_mfma_f32_16x16x32_bf16 v[10:13], v[182:185], v[216:219], v[10:13]
	v_mfma_f32_16x16x32_bf16 v[6:9], v[166:169], v[224:227], v[6:9]
	v_mfma_f32_16x16x32_bf16 v[2:5], v[182:185], v[224:227], v[2:5]
	s_setprio 0
	s_barrier
	s_add_i32 s47, s47, 2
	s_add_u32 s45, s45, 0x100
	s_addc_u32 s46, s46, 0
	s_add_u32 s26, s26, 0x100
	s_addc_u32 s27, s27, 0
	s_cmp_gt_u32 s47, 29
	s_cbranch_scc0 .LBB0_844
	s_and_b64 vcc, exec, s[10:11]
	s_cbranch_vccz .LBB0_847
	s_barrier

; #define PG8_STAGE(bufoff, gbase, voff) do { _Pragma("unroll") for (int _i = 0; _i < 2; ++_i) \
;         __builtin_amdgcn_global_load_lds((const unsigned*)((const char*)(gbase) + (voff)[_i]), (LAS unsigned*)(lds + (bufoff) + ldsw + _i * 8192), 16, 0, 0); } while (0)
; #define PG8_LDA(dst, b, h) do { _Pragma("unroll") for (int m = 0; m < 4; ++m) _Pragma("unroll") for (int k = 0; k < 2; ++k) dst[m][k] = *(const LAS bf16x8*)(lds + PG8_SA(b, h) + aoff + m * 2048 + k * 1024); } while (0)
; #define PG8_LDB(dst, b, h) do { _Pragma("unroll") for (int n = 0; n < 2; ++n) _Pragma("unroll") for (int k = 0; k < 2; ++k) dst[n][k] = *(const LAS bf16x8*)(lds + PG8_SB(b, h) + boff + n * 2048 + k * 1024); } while (0)
; #define PG8_MMA(ai, bj, At, Bt) do { __builtin_amdgcn_s_setprio(1); _Pragma("unroll") for (int m = 0; m < 4; ++m) _Pragma("unroll") for (int n = 0; n < 2; ++n) _Pragma("unroll") for (int k = 0; k < 2; ++k) \
;         acc[ai][bj][m][n] = __builtin_amdgcn_mfma_f32_16x16x32_bf16(Bt[n][k], At[m][k], acc[ai][bj][m][n], 0, 0, 0); __builtin_amdgcn_s_setprio(0); } while (0)
; #define PG8_WAIT_V(n) asm volatile("s_waitcnt vmcnt(" #n ")" ::: "memory")
; #define PG8_WAIT_L(n) asm volatile("s_waitcnt lgkmcnt(" #n ")" ::: "memory")
; #define PG8_BAR __builtin_amdgcn_s_barrier()
; #define PG8_SCHED __builtin_amdgcn_sched_barrier(0)
; template <class Epi>
; __device__ __forceinline__ void gemm_phase(LAS unsigned char* lds, const Gemm g, const StaticOrder& S, const Epi& E, const int tid) {
;     ...
;             PG8_LDB(B0, 0, 0); PG8_LDB(B1, 0, 1); PG8_SCHED; PG8_LDA(At, 0, 0); PG8_STAGE(PG8_SA(1, 1), a1 + hstep, voffA);
;             PG8_WAIT_V(8); PG8_WAIT_L(0); PG8_BAR; PG8_MMA(0, 0, At, B0); PG8_MMA(0, 1, At, B1); PG8_BAR; PG8_SCHED;
;             PG8_LDA(At, 0, 1); PG8_STAGE(PG8_SB(0, 0), b2, voffB); PG8_STAGE(PG8_SB(0, 1), b2 + bhs, voffB); PG8_STAGE(PG8_SA(0, 0), a2, voffA);
;             PG8_WAIT_V(8); PG8_WAIT_L(0); PG8_BAR; PG8_MMA(1, 0, At, B0); PG8_MMA(1, 1, At, B1); PG8_BAR; PG8_SCHED;
.LBB0_861:
	s_add_u32 s30, s28, 0xfff80080
	s_addc_u32 s31, s29, -1
	s_add_i32 s51, 0, 0x10000
	s_cmp_eq_u32 s50, 28
	s_cselect_b32 s35, s17, s31
	s_cselect_b32 s34, s46, s30
	v_add_u32_e32 v145, s51, v142
	s_cselect_b32 s31, s15, s49
	s_cselect_b32 s30, s47, s48
	s_add_i32 s54, 0, 0x14000
	ds_read_b128 v[146:149], v145
	ds_read_b128 v[150:153], v145 offset:1024
	ds_read_b128 v[154:157], v145 offset:2048
	ds_read_b128 v[158:161], v145 offset:3072
	v_add_u32_e32 v145, s54, v142
	ds_read_b128 v[162:165], v145
	ds_read_b128 v[166:169], v145 offset:1024
	ds_read_b128 v[178:181], v145 offset:2048
	ds_read_b128 v[182:185], v145 offset:3072
	v_lshl_add_u64 v[172:173], s[28:29], 0, v[138:139]
	s_add_i32 m0, s25, 0xc000
	ds_read_b128 v[186:189], v144
	global_load_lds_dwordx4 v[172:173], off
	ds_read_b128 v[190:193], v144 offset:1024
	ds_read_b128 v[194:197], v144 offset:2048
	ds_read_b128 v[198:201], v144 offset:3072
	v_lshl_add_u64 v[172:173], s[28:29], 0, v[136:137]
	s_add_i32 m0, s25, 0xe000
	s_nop 0
	global_load_lds_dwordx4 v[172:173], off
	ds_read_b128 v[212:215], v144 offset:4096
	ds_read_b128 v[216:219], v144 offset:5120
	ds_read_b128 v[220:223], v144 offset:6144
	ds_read_b128 v[224:227], v144 offset:7168
	s_waitcnt vmcnt(8)
	s_waitcnt lgkmcnt(0)
	s_barrier
	s_setprio 1
	s_waitcnt lgkmcnt(0)
	v_mfma_f32_16x16x32_bf16 v[126:129], v[146:149], v[186:189], v[126:129]
	v_mfma_f32_16x16x32_bf16 v[122:125], v[154:157], v[186:189], v[122:125]
	v_mfma_f32_16x16x32_bf16 v[118:121], v[146:149], v[194:197], v[118:121]
	v_mfma_f32_16x16x32_bf16 v[110:113], v[154:157], v[194:197], v[110:113]
	v_mfma_f32_16x16x32_bf16 v[102:105], v[146:149], v[212:215], v[102:105]
	v_mfma_f32_16x16x32_bf16 v[94:97], v[154:157], v[212:215], v[94:97]
	v_mfma_f32_16x16x32_bf16 v[86:89], v[146:149], v[220:223], v[86:89]
	v_mfma_f32_16x16x32_bf16 v[78:81], v[154:157], v[220:223], v[78:81]
	v_mfma_f32_16x16x32_bf16 v[126:129], v[150:153], v[190:193], v[126:129]
	v_mfma_f32_16x16x32_bf16 v[122:125], v[158:161], v[190:193], v[122:125]
	v_mfma_f32_16x16x32_bf16 v[118:121], v[150:153], v[198:201], v[118:121]
	v_mfma_f32_16x16x32_bf16 v[110:113], v[158:161], v[198:201], v[110:113]
	v_mfma_f32_16x16x32_bf16 v[102:105], v[150:153], v[216:219], v[102:105]
	v_mfma_f32_16x16x32_bf16 v[94:97], v[158:161], v[216:219], v[94:97]
	v_mfma_f32_16x16x32_bf16 v[86:89], v[150:153], v[224:227], v[86:89]
	v_mfma_f32_16x16x32_bf16 v[78:81], v[158:161], v[224:227], v[78:81]
	s_setprio 0
	s_setprio 1
	v_mfma_f32_16x16x32_bf16 v[114:117], v[162:165], v[186:189], v[114:117]
	v_mfma_f32_16x16x32_bf16 v[106:109], v[178:181], v[186:189], v[106:109]
	v_mfma_f32_16x16x32_bf16 v[98:101], v[162:165], v[194:197], v[98:101]
	v_mfma_f32_16x16x32_bf16 v[90:93], v[178:181], v[194:197], v[90:93]
	v_mfma_f32_16x16x32_bf16 v[82:85], v[162:165], v[212:215], v[82:85]
	v_mfma_f32_16x16x32_bf16 v[74:77], v[178:181], v[212:215], v[74:77]
	v_mfma_f32_16x16x32_bf16 v[70:73], v[162:165], v[220:223], v[70:73]
	v_mfma_f32_16x16x32_bf16 v[66:69], v[178:181], v[220:223], v[66:69]
	v_mfma_f32_16x16x32_bf16 v[114:117], v[166:169], v[190:193], v[114:117]
	v_mfma_f32_16x16x32_bf16 v[106:109], v[182:185], v[190:193], v[106:109]
	v_mfma_f32_16x16x32_bf16 v[98:101], v[166:169], v[198:201], v[98:101]
	v_mfma_f32_16x16x32_bf16 v[90:93], v[182:185], v[198:201], v[90:93]
	v_mfma_f32_16x16x32_bf16 v[82:85], v[166:169], v[216:219], v[82:85]
	v_mfma_f32_16x16x32_bf16 v[74:77], v[182:185], v[216:219], v[74:77]
	v_mfma_f32_16x16x32_bf16 v[70:73], v[166:169], v[224:227], v[70:73]
	v_mfma_f32_16x16x32_bf16 v[66:69], v[182:185], v[224:227], v[66:69]
	s_setprio 0
	s_barrier
	s_add_i32 s51, s51, s40
	v_lshl_add_u64 v[172:173], s[30:31], 0, v[0:1]
	s_mov_b32 m0, s51
	ds_read_b128 v[186:189], v144 offset:16384
	global_load_lds_dwordx4 v[172:173], off
	ds_read_b128 v[190:193], v144 offset:17408
	ds_read_b128 v[194:197], v144 offset:18432
	ds_read_b128 v[198:201], v144 offset:19456
	s_add_i32 m0, s51, 0x2000
	s_add_u32 s52, s30, 0x8000
	v_lshl_add_u64 v[174:175], s[30:31], 0, v[134:135]
	s_addc_u32 s53, s31, 0
	s_add_i32 s51, s54, s40
	global_load_lds_dwordx4 v[174:175], off
	ds_read_b128 v[212:215], v144 offset:20480
	ds_read_b128 v[216:219], v144 offset:21504
	ds_read_b128 v[220:223], v144 offset:22528
	v_lshl_add_u64 v[176:177], s[52:53], 0, v[0:1]
	s_mov_b32 m0, s51
	v_lshl_add_u64 v[228:229], s[34:35], 0, v[132:133]
	global_load_lds_dwordx4 v[176:177], off
	ds_read_b128 v[224:227], v144 offset:23552
	v_lshl_add_u64 v[176:177], s[52:53], 0, v[134:135]
	s_add_i32 m0, s51, 0x2000
	s_nop 0
	global_load_lds_dwordx4 v[176:177], off
	v_lshl_add_u64 v[176:177], s[34:35], 0, v[130:131]
	s_mov_b32 m0, s25
	s_nop 0
	global_load_lds_dwordx4 v[176:177], off
	s_mov_b32 m0, s27
	s_nop 0
	global_load_lds_dwordx4 v[228:229], off
	s_waitcnt vmcnt(8)
	s_waitcnt lgkmcnt(0)
	s_barrier
; #define PG8_STAGE(bufoff, gbase, voff) do { _Pragma("unroll") for (int _i = 0; _i < 2; ++_i) \
;         __builtin_amdgcn_global_load_lds((const unsigned*)((const char*)(gbase) + (voff)[_i]), (LAS unsigned*)(lds + (bufoff) + ldsw + _i * 8192), 16, 0, 0); } while (0)
; #define PG8_LDA(dst, b, h) do { _Pragma("unroll") for (int m = 0; m < 4; ++m) _Pragma("unroll") for (int k = 0; k < 2; ++k) dst[m][k] = *(const LAS bf16x8*)(lds + PG8_SA(b, h) + aoff + m * 2048 + k * 1024); } while (0)
; #define PG8_LDB(dst, b, h) do { _Pragma("unroll") for (int n = 0; n < 2; ++n) _Pragma("unroll") for (int k = 0; k < 2; ++k) dst[n][k] = *(const LAS bf16x8*)(lds + PG8_SB(b, h) + boff + n * 2048 + k * 1024); } while (0)
; #define PG8_MMA(ai, bj, At, Bt) do { __builtin_amdgcn_s_setprio(1); _Pragma("unroll") for (int m = 0; m < 4; ++m) _Pragma("unroll") for (int n = 0; n < 2; ++n) _Pragma("unroll") for (int k = 0; k < 2; ++k) \
;         acc[ai][bj][m][n] = __builtin_amdgcn_mfma_f32_16x16x32_bf16(Bt[n][k], At[m][k], acc[ai][bj][m][n], 0, 0, 0); __builtin_amdgcn_s_setprio(0); } while (0)
; #define PG8_WAIT_V(n) asm volatile("s_waitcnt vmcnt(" #n ")" ::: "memory")
; #define PG8_WAIT_L(n) asm volatile("s_waitcnt lgkmcnt(" #n ")" ::: "memory")
; #define PG8_BAR __builtin_amdgcn_s_barrier()
; #define PG8_SCHED __builtin_amdgcn_sched_barrier(0)
; template <class Epi>
; __device__ __forceinline__ void gemm_phase(LAS unsigned char* lds, const Gemm g, const StaticOrder& S, const Epi& E, const int tid) {
;     ...
;             PG8_WAIT_V(8); PG8_WAIT_L(0); PG8_BAR; PG8_MMA(1, 0, At, B0); PG8_MMA(1, 1, At, B1); PG8_BAR; PG8_SCHED;
;             PG8_LDB(B0, 1, 0); PG8_LDB(B1, 1, 1); PG8_SCHED; PG8_LDA(At, 1, 0); PG8_STAGE(PG8_SA(0, 1), a2 + hstep, voffA);
;             PG8_WAIT_V(8); PG8_WAIT_L(0); PG8_BAR; PG8_MMA(0, 0, At, B0); PG8_MMA(0, 1, At, B1); PG8_BAR; PG8_SCHED;
	s_setprio 1
	s_waitcnt lgkmcnt(0)
	v_mfma_f32_16x16x32_bf16 v[62:65], v[146:149], v[186:189], v[62:65]
	v_mfma_f32_16x16x32_bf16 v[58:61], v[154:157], v[186:189], v[58:61]
	v_mfma_f32_16x16x32_bf16 v[54:57], v[146:149], v[194:197], v[54:57]
	v_mfma_f32_16x16x32_bf16 v[46:49], v[154:157], v[194:197], v[46:49]
	v_mfma_f32_16x16x32_bf16 v[38:41], v[146:149], v[212:215], v[38:41]
	v_mfma_f32_16x16x32_bf16 v[30:33], v[154:157], v[212:215], v[30:33]
	v_mfma_f32_16x16x32_bf16 v[22:25], v[146:149], v[220:223], v[22:25]
	v_mfma_f32_16x16x32_bf16 v[14:17], v[154:157], v[220:223], v[14:17]
	v_mfma_f32_16x16x32_bf16 v[62:65], v[150:153], v[190:193], v[62:65]
	v_mfma_f32_16x16x32_bf16 v[58:61], v[158:161], v[190:193], v[58:61]
	v_mfma_f32_16x16x32_bf16 v[54:57], v[150:153], v[198:201], v[54:57]
	v_mfma_f32_16x16x32_bf16 v[46:49], v[158:161], v[198:201], v[46:49]
	v_mfma_f32_16x16x32_bf16 v[38:41], v[150:153], v[216:219], v[38:41]
	v_mfma_f32_16x16x32_bf16 v[30:33], v[158:161], v[216:219], v[30:33]
	v_mfma_f32_16x16x32_bf16 v[22:25], v[150:153], v[224:227], v[22:25]
	v_mfma_f32_16x16x32_bf16 v[14:17], v[158:161], v[224:227], v[14:17]
	s_setprio 0
	s_setprio 1
	v_mfma_f32_16x16x32_bf16 v[50:53], v[162:165], v[186:189], v[50:53]
	v_mfma_f32_16x16x32_bf16 v[42:45], v[178:181], v[186:189], v[42:45]
	v_mfma_f32_16x16x32_bf16 v[34:37], v[162:165], v[194:197], v[34:37]
	v_mfma_f32_16x16x32_bf16 v[26:29], v[178:181], v[194:197], v[26:29]
	v_mfma_f32_16x16x32_bf16 v[18:21], v[162:165], v[212:215], v[18:21]
	v_mfma_f32_16x16x32_bf16 v[10:13], v[178:181], v[212:215], v[10:13]
	v_mfma_f32_16x16x32_bf16 v[6:9], v[162:165], v[220:223], v[6:9]
	v_mfma_f32_16x16x32_bf16 v[2:5], v[178:181], v[220:223], v[2:5]
	v_mfma_f32_16x16x32_bf16 v[50:53], v[166:169], v[190:193], v[50:53]
	v_mfma_f32_16x16x32_bf16 v[42:45], v[182:185], v[190:193], v[42:45]
	v_mfma_f32_16x16x32_bf16 v[34:37], v[166:169], v[198:201], v[34:37]
	v_mfma_f32_16x16x32_bf16 v[26:29], v[182:185], v[198:201], v[26:29]
	v_mfma_f32_16x16x32_bf16 v[18:21], v[166:169], v[216:219], v[18:21]
	v_mfma_f32_16x16x32_bf16 v[10:13], v[182:185], v[216:219], v[10:13]
	v_mfma_f32_16x16x32_bf16 v[6:9], v[166:169], v[224:227], v[6:9]
	v_mfma_f32_16x16x32_bf16 v[2:5], v[182:185], v[224:227], v[2:5]
	s_setprio 0
	s_barrier
	s_add_i32 s51, 0, 0x18000
	v_add_u32_e32 v145, s51, v142
	s_add_i32 s52, 0, 0x1c000
	ds_read_b128 v[146:149], v145
	ds_read_b128 v[150:153], v145 offset:1024
	ds_read_b128 v[154:157], v145 offset:2048
	ds_read_b128 v[158:161], v145 offset:3072
	v_add_u32_e32 v145, s52, v142
	ds_read_b128 v[162:165], v145
	ds_read_b128 v[166:169], v145 offset:1024
	ds_read_b128 v[178:181], v145 offset:2048
	ds_read_b128 v[182:185], v145 offset:3072
	s_add_u32 s34, s34, 0x80000
	s_addc_u32 s35, s35, 0
	s_mov_b32 m0, s41
	v_lshl_add_u64 v[230:231], s[34:35], 0, v[130:131]
	ds_read_b128 v[186:189], v144 offset:32768
	global_load_lds_dwordx4 v[230:231], off
	ds_read_b128 v[190:193], v144 offset:33792
	ds_read_b128 v[194:197], v144 offset:34816
	ds_read_b128 v[198:201], v144 offset:35840
	v_lshl_add_u64 v[230:231], s[34:35], 0, v[132:133]
	s_mov_b32 m0, s42
	s_nop 0
	global_load_lds_dwordx4 v[230:231], off
	ds_read_b128 v[212:215], v144 offset:36864
	ds_read_b128 v[216:219], v144 offset:37888
	ds_read_b128 v[220:223], v144 offset:38912
	ds_read_b128 v[224:227], v144 offset:39936
	s_waitcnt vmcnt(8)
	s_waitcnt lgkmcnt(0)
	s_barrier
	s_setprio 1
	s_waitcnt lgkmcnt(0)
	v_mfma_f32_16x16x32_bf16 v[126:129], v[146:149], v[186:189], v[126:129]
	v_mfma_f32_16x16x32_bf16 v[122:125], v[154:157], v[186:189], v[122:125]
	v_mfma_f32_16x16x32_bf16 v[118:121], v[146:149], v[194:197], v[118:121]
	v_mfma_f32_16x16x32_bf16 v[110:113], v[154:157], v[194:197], v[110:113]
	v_mfma_f32_16x16x32_bf16 v[102:105], v[146:149], v[212:215], v[102:105]
	v_mfma_f32_16x16x32_bf16 v[94:97], v[154:157], v[212:215], v[94:97]
	v_mfma_f32_16x16x32_bf16 v[86:89], v[146:149], v[220:223], v[86:89]
	v_mfma_f32_16x16x32_bf16 v[78:81], v[154:157], v[220:223], v[78:81]
	v_mfma_f32_16x16x32_bf16 v[126:129], v[150:153], v[190:193], v[126:129]
	v_mfma_f32_16x16x32_bf16 v[122:125], v[158:161], v[190:193], v[122:125]
	v_mfma_f32_16x16x32_bf16 v[118:121], v[150:153], v[198:201], v[118:121]
	v_mfma_f32_16x16x32_bf16 v[110:113], v[158:161], v[198:201], v[110:113]
	v_mfma_f32_16x16x32_bf16 v[102:105], v[150:153], v[216:219], v[102:105]
	v_mfma_f32_16x16x32_bf16 v[94:97], v[158:161], v[216:219], v[94:97]
	v_mfma_f32_16x16x32_bf16 v[86:89], v[150:153], v[224:227], v[86:89]
	v_mfma_f32_16x16x32_bf16 v[78:81], v[158:161], v[224:227], v[78:81]
	s_setprio 0
	s_setprio 1
	v_mfma_f32_16x16x32_bf16 v[114:117], v[162:165], v[186:189], v[114:117]
	v_mfma_f32_16x16x32_bf16 v[106:109], v[178:181], v[186:189], v[106:109]
	v_mfma_f32_16x16x32_bf16 v[98:101], v[162:165], v[194:197], v[98:101]
	v_mfma_f32_16x16x32_bf16 v[90:93], v[178:181], v[194:197], v[90:93]
	v_mfma_f32_16x16x32_bf16 v[82:85], v[162:165], v[212:215], v[82:85]
	v_mfma_f32_16x16x32_bf16 v[74:77], v[178:181], v[212:215], v[74:77]
	v_mfma_f32_16x16x32_bf16 v[70:73], v[162:165], v[220:223], v[70:73]
	v_mfma_f32_16x16x32_bf16 v[66:69], v[178:181], v[220:223], v[66:69]
	v_mfma_f32_16x16x32_bf16 v[114:117], v[166:169], v[190:193], v[114:117]
	v_mfma_f32_16x16x32_bf16 v[106:109], v[182:185], v[190:193], v[106:109]
	v_mfma_f32_16x16x32_bf16 v[98:101], v[166:169], v[198:201], v[98:101]
	v_mfma_f32_16x16x32_bf16 v[90:93], v[182:185], v[198:201], v[90:93]
	v_mfma_f32_16x16x32_bf16 v[82:85], v[166:169], v[216:219], v[82:85]
	v_mfma_f32_16x16x32_bf16 v[74:77], v[182:185], v[216:219], v[74:77]
	v_mfma_f32_16x16x32_bf16 v[70:73], v[166:169], v[224:227], v[70:73]
	v_mfma_f32_16x16x32_bf16 v[66:69], v[182:185], v[224:227], v[66:69]
	s_setprio 0
	s_barrier
; #define PG8_STAGE(bufoff, gbase, voff) do { _Pragma("unroll") for (int _i = 0; _i < 2; ++_i) \
;         __builtin_amdgcn_global_load_lds((const unsigned*)((const char*)(gbase) + (voff)[_i]), (LAS unsigned*)(lds + (bufoff) + ldsw + _i * 8192), 16, 0, 0); } while (0)
; #define PG8_LDA(dst, b, h) do { _Pragma("unroll") for (int m = 0; m < 4; ++m) _Pragma("unroll") for (int k = 0; k < 2; ++k) dst[m][k] = *(const LAS bf16x8*)(lds + PG8_SA(b, h) + aoff + m * 2048 + k * 1024); } while (0)
; #define PG8_MMA(ai, bj, At, Bt) do { __builtin_amdgcn_s_setprio(1); _Pragma("unroll") for (int m = 0; m < 4; ++m) _Pragma("unroll") for (int n = 0; n < 2; ++n) _Pragma("unroll") for (int k = 0; k < 2; ++k) \
;         acc[ai][bj][m][n] = __builtin_amdgcn_mfma_f32_16x16x32_bf16(Bt[n][k], At[m][k], acc[ai][bj][m][n], 0, 0, 0); __builtin_amdgcn_s_setprio(0); } while (0)
; #define PG8_WAIT_V(n) asm volatile("s_waitcnt vmcnt(" #n ")" ::: "memory")
; #define PG8_WAIT_L(n) asm volatile("s_waitcnt lgkmcnt(" #n ")" ::: "memory")
; #define PG8_BAR __builtin_amdgcn_s_barrier()
; #define PG8_SCHED __builtin_amdgcn_sched_barrier(0)
; template <class Epi>
; __device__ __forceinline__ void gemm_phase(LAS unsigned char* lds, const Gemm g, const StaticOrder& S, const Epi& E, const int tid) {
;     ...
;             PG8_LDA(At, 1, 1); PG8_STAGE(PG8_SB(1, 0), b3, voffB); PG8_STAGE(PG8_SB(1, 1), b3 + bhs, voffB); PG8_STAGE(PG8_SA(1, 0), a3, voffA);
;             PG8_WAIT_V(8); PG8_WAIT_L(0); PG8_BAR; PG8_MMA(1, 0, At, B0); PG8_MMA(1, 1, At, B1); PG8_BAR; PG8_SCHED;
	s_add_i32 s34, s51, s40
	v_lshl_add_u64 v[172:173], v[172:173], 0, s[70:71]
	s_mov_b32 m0, s34
	ds_read_b128 v[186:189], v144 offset:49152
	global_load_lds_dwordx4 v[172:173], off
	ds_read_b128 v[190:193], v144 offset:50176
	ds_read_b128 v[194:197], v144 offset:51200
	ds_read_b128 v[198:201], v144 offset:52224
	s_add_i32 m0, s34, 0x2000
	s_add_u32 s30, s30, 0x8080
	v_lshl_add_u64 v[172:173], v[174:175], 0, s[70:71]
	s_addc_u32 s31, s31, 0
	s_add_i32 s34, s52, s40
	global_load_lds_dwordx4 v[172:173], off
	ds_read_b128 v[212:215], v144 offset:53248
	ds_read_b128 v[216:219], v144 offset:54272
	ds_read_b128 v[220:223], v144 offset:55296
	v_lshl_add_u64 v[172:173], s[30:31], 0, v[0:1]
	s_mov_b32 m0, s34
	s_nop 0
	global_load_lds_dwordx4 v[172:173], off
	ds_read_b128 v[224:227], v144 offset:56320
	v_lshl_add_u64 v[172:173], s[30:31], 0, v[134:135]
	s_add_i32 m0, s34, 0x2000
	s_nop 0
	global_load_lds_dwordx4 v[172:173], off
	v_lshl_add_u64 v[172:173], v[176:177], 0, s[70:71]
	s_mov_b32 m0, s43
	s_nop 0
	global_load_lds_dwordx4 v[172:173], off
	v_lshl_add_u64 v[172:173], v[228:229], 0, s[70:71]
	s_mov_b32 m0, s44
	s_nop 0
	global_load_lds_dwordx4 v[172:173], off
	s_waitcnt vmcnt(8)
	s_waitcnt lgkmcnt(0)
	s_barrier
	s_setprio 1
	s_waitcnt lgkmcnt(0)
	v_mfma_f32_16x16x32_bf16 v[62:65], v[146:149], v[186:189], v[62:65]
	v_mfma_f32_16x16x32_bf16 v[58:61], v[154:157], v[186:189], v[58:61]
	v_mfma_f32_16x16x32_bf16 v[54:57], v[146:149], v[194:197], v[54:57]
	v_mfma_f32_16x16x32_bf16 v[46:49], v[154:157], v[194:197], v[46:49]
	v_mfma_f32_16x16x32_bf16 v[38:41], v[146:149], v[212:215], v[38:41]
	v_mfma_f32_16x16x32_bf16 v[30:33], v[154:157], v[212:215], v[30:33]
	v_mfma_f32_16x16x32_bf16 v[22:25], v[146:149], v[220:223], v[22:25]
	v_mfma_f32_16x16x32_bf16 v[14:17], v[154:157], v[220:223], v[14:17]
	v_mfma_f32_16x16x32_bf16 v[62:65], v[150:153], v[190:193], v[62:65]
	v_mfma_f32_16x16x32_bf16 v[58:61], v[158:161], v[190:193], v[58:61]
	v_mfma_f32_16x16x32_bf16 v[54:57], v[150:153], v[198:201], v[54:57]
	v_mfma_f32_16x16x32_bf16 v[46:49], v[158:161], v[198:201], v[46:49]
	v_mfma_f32_16x16x32_bf16 v[38:41], v[150:153], v[216:219], v[38:41]
	v_mfma_f32_16x16x32_bf16 v[30:33], v[158:161], v[216:219], v[30:33]
	v_mfma_f32_16x16x32_bf16 v[22:25], v[150:153], v[224:227], v[22:25]
	v_mfma_f32_16x16x32_bf16 v[14:17], v[158:161], v[224:227], v[14:17]
	s_setprio 0
	s_setprio 1
	v_mfma_f32_16x16x32_bf16 v[50:53], v[162:165], v[186:189], v[50:53]
	v_mfma_f32_16x16x32_bf16 v[42:45], v[178:181], v[186:189], v[42:45]
	v_mfma_f32_16x16x32_bf16 v[34:37], v[162:165], v[194:197], v[34:37]
	v_mfma_f32_16x16x32_bf16 v[26:29], v[178:181], v[194:197], v[26:29]
	v_mfma_f32_16x16x32_bf16 v[18:21], v[162:165], v[212:215], v[18:21]
	v_mfma_f32_16x16x32_bf16 v[10:13], v[178:181], v[212:215], v[10:13]
	v_mfma_f32_16x16x32_bf16 v[6:9], v[162:165], v[220:223], v[6:9]
	v_mfma_f32_16x16x32_bf16 v[2:5], v[178:181], v[220:223], v[2:5]
	v_mfma_f32_16x16x32_bf16 v[50:53], v[166:169], v[190:193], v[50:53]
	v_mfma_f32_16x16x32_bf16 v[42:45], v[182:185], v[190:193], v[42:45]
	v_mfma_f32_16x16x32_bf16 v[34:37], v[166:169], v[198:201], v[34:37]
	v_mfma_f32_16x16x32_bf16 v[26:29], v[182:185], v[198:201], v[26:29]
	v_mfma_f32_16x16x32_bf16 v[18:21], v[166:169], v[216:219], v[18:21]
	v_mfma_f32_16x16x32_bf16 v[10:13], v[182:185], v[216:219], v[10:13]
	v_mfma_f32_16x16x32_bf16 v[6:9], v[166:169], v[224:227], v[6:9]
	v_mfma_f32_16x16x32_bf16 v[2:5], v[182:185], v[224:227], v[2:5]
	s_setprio 0
	s_barrier
	s_add_i32 s50, s50, 2
	s_add_u32 s48, s48, 0x100
	s_addc_u32 s49, s49, 0
	s_add_u32 s28, s28, 0x100
	s_addc_u32 s29, s29, 0
	s_cmp_gt_u32 s50, 29
	s_cbranch_scc0 .LBB0_861
	s_and_b64 vcc, exec, s[12:13]
	s_cbranch_vccz .LBB0_864
	s_barrier
